# fuse causal conv + silu gate into up-GEMM epilogue (f32 acc, DPP row shifts), boundary pass for block edges, HB relocated
# speedup vs baseline: 1.0723x; 1.0422x over previous
.LBB0_70:
	s_andn2_b64 vcc, exec, s[2:3]
	s_cbranch_vccnz .LBB0_146
	v_ashrrev_i32_e32 v0, 31, v18
	v_lshrrev_b32_e32 v0, 26, v0
	v_add_u32_e32 v0, v18, v0
	v_ashrrev_i32_e32 v14, 6, v0
	v_bfe_i32 v0, v18, 27, 1
	v_lshlrev_b32_e32 v3, 4, v18
	v_lshrrev_b32_e32 v0, 22, v0
	v_add_u32_e32 v0, v3, v0
	v_and_b32_e32 v0, 0xfffffc00, v0
	v_sub_u32_e32 v0, v3, v0
	v_lshrrev_b32_e32 v2, 4, v0
	v_bitop3_b32 v0, v2, v0, 32 bitop3:0x6c
	v_ashrrev_i32_e32 v5, 31, v0
	v_readlane_b32 s3, v253, 41
	v_lshrrev_b32_e32 v5, 26, v5
	s_mul_hi_i32 s2, s3, 0xb00000
	s_mul_i32 s3, s3, 0xb00000
	v_add_u32_e32 v5, v0, v5
	s_add_u32 s3, s82, s3
	v_lshlrev_b32_e32 v2, 3, v14
	v_ashrrev_i32_e32 v15, 6, v5
	v_and_b32_e32 v5, 0xc0, v5
	s_addc_u32 s2, s83, s2
	v_and_b32_e32 v2, -16, v2
	v_sub_u32_e32 v0, v0, v5
	v_mov_b32_e32 v8, 1
	s_add_u32 s33, s3, 0x3200000
	v_add_u32_e32 v2, v15, v2
	v_ashrrev_i16_sdwa v0, v8, sext(v0) dst_sel:DWORD dst_unused:UNUSED_PAD src0_sel:DWORD src1_sel:BYTE_0
	s_addc_u32 s36, s2, 0
	v_lshlrev_b32_e32 v6, 5, v14
	v_bfe_i32 v16, v0, 0, 16
	v_lshlrev_b32_e32 v0, 1, v2
	v_lshrrev_b32_e32 v5, 2, v2
	v_and_b32_e32 v7, 3, v15
	s_mov_b32 s2, 0x1fffe0
	v_and_b32_e32 v6, 32, v6
	v_and_b32_e32 v0, 24, v0
	v_and_b32_e32 v5, 4, v5
	v_and_or_b32 v7, v2, s2, v7
	v_or3_b32 v0, v7, v5, v0
	v_add_lshl_u32 v5, v6, v16, 1
	v_add_u32_e32 v3, 0x2000, v3
	v_and_b32_e32 v22, 15, v2
	v_bfe_u32 v23, v2, 4, 2
	v_lshl_or_b32 v22, v22, 2, v23
	v_and_or_b32 v2, v2, 64, v22
	v_lshl_add_u32 v2, v2, 11, v5
	v_lshl_add_u32 v0, v0, 11, v5
	v_ashrrev_i32_e32 v5, 31, v3
	v_lshrrev_b32_e32 v5, 22, v5
	v_add_u32_e32 v5, v3, v5
	v_ashrrev_i32_e32 v17, 10, v5
	v_mul_i32_i24_e32 v5, 0x400, v17
	v_sub_u32_e32 v3, v3, v5
	v_lshrrev_b32_e32 v5, 4, v3
	v_bitop3_b32 v3, v5, v3, 32 bitop3:0x6c
	v_ashrrev_i32_e32 v6, 31, v3
	v_lshrrev_b32_e32 v6, 26, v6
	v_add_u32_e32 v6, v3, v6
	v_lshlrev_b32_e32 v5, 3, v17
	v_ashrrev_i32_e32 v19, 6, v6
	v_and_b32_e32 v6, 0xc0, v6
	v_and_b32_e32 v5, -16, v5
	v_sub_u32_e32 v3, v3, v6
	v_add_u32_e32 v5, v19, v5
	v_ashrrev_i16_sdwa v3, v8, sext(v3) dst_sel:DWORD dst_unused:UNUSED_PAD src0_sel:DWORD src1_sel:BYTE_0
	v_and_b32_e32 v8, 3, v19
	s_ashr_i32 s18, s16, 6
	s_ashr_i32 s5, s4, 31
	s_ashr_i32 s27, s26, 31
	s_ashr_i32 s17, s16, 8
	v_and_or_b32 v8, v5, s2, v8
	s_lshl_b32 s37, s18, 10
	s_lshl_b64 s[2:3], s[4:5], 19
	s_lshl_b64 s[8:9], s[26:27], 18
	s_add_u32 s30, s33, s8
	v_lshlrev_b32_e32 v7, 5, v17
	v_bfe_i32 v20, v3, 0, 16
	v_lshlrev_b32_e32 v3, 1, v5
	v_lshrrev_b32_e32 v6, 2, v5
	s_addc_u32 s31, s36, s9
	s_add_i32 s38, s37, 0
	v_and_b32_e32 v7, 32, v7
	v_and_b32_e32 v3, 24, v3
	v_and_b32_e32 v6, 4, v6
	s_add_i32 m0, s38, 0x10000
	v_or3_b32 v3, v8, v6, v3
	v_add_lshl_u32 v6, v7, v20, 1
	global_load_lds_dwordx4 v0, s[30:31]
	s_add_i32 m0, s38, 0x12000
	v_lshl_add_u32 v136, v3, 11, v6
	s_add_u32 s8, s30, 0x580000
	global_load_lds_dwordx4 v136, s[30:31]
	s_addc_u32 s9, s31, 0
	s_add_i32 m0, s38, 0x14000
	v_and_b32_e32 v22, 15, v5
	v_bfe_u32 v23, v5, 4, 2
	v_lshl_or_b32 v22, v22, 2, v23
	v_and_or_b32 v5, v5, 64, v22
	v_lshl_add_u32 v134, v5, 11, v6
	global_load_lds_dwordx4 v0, s[8:9]
	s_add_i32 m0, s38, 0x16000
	s_add_u32 s28, s80, s2
	s_addc_u32 s29, s81, s3
	s_add_i32 s39, s38, 0x2000
	global_load_lds_dwordx4 v136, s[8:9]
	s_mov_b32 m0, s38
	s_add_u32 s2, s28, 0x40000
	global_load_lds_dwordx4 v2, s[28:29]
	s_mov_b32 m0, s39
	s_addc_u32 s3, s29, 0
	s_add_i32 s41, s38, 0x4000
	global_load_lds_dwordx4 v134, s[28:29]
	s_mov_b32 m0, s41
	s_add_i32 s42, s38, 0x6000
	global_load_lds_dwordx4 v2, s[2:3]
	s_mov_b32 m0, s42
	v_mov_b32_e32 v137, v1
	global_load_lds_dwordx4 v134, s[2:3]
	s_load_dwordx2 s[2:3], s[54:55], 0xd8
	v_mov_b32_e32 v3, v1
	v_mov_b32_e32 v135, v1
	s_cmp_eq_u32 s17, 1
	v_lshl_add_u64 v[12:13], s[30:31], 0, v[0:1]
	v_lshl_add_u64 v[10:11], s[30:31], 0, v[136:137]
	v_lshl_add_u64 v[6:7], s[28:29], 0, v[2:3]
	s_cselect_b64 s[8:9], -1, 0
	s_cmp_lg_u32 s17, 1
	v_lshl_add_u64 v[8:9], s[28:29], 0, v[134:135]
	s_cbranch_scc1 .LBB0_73
	s_barrier
.LBB0_73:
	s_add_u32 s10, s82, 0xd200000
	v_readlane_b32 s14, v253, 41
	s_addc_u32 s11, s83, 0
	s_mul_i32 s12, s14, 0x16000
	s_mul_hi_i32 s5, s14, 0x16000
	s_waitcnt lgkmcnt(0)
	s_add_u32 s12, s2, s12
	s_addc_u32 s5, s3, s5
	s_add_u32 s12, s12, 0x4500000
	s_addc_u32 s13, s5, 0
	s_mul_hi_i32 s5, s14, 0x580000
	s_mul_i32 s14, s14, 0x580000
	s_add_u32 s2, s2, s14
	v_lshrrev_b32_e32 v21, 1, v18
	s_addc_u32 s3, s3, s5
	v_and_b32_e32 v21, 24, v21
	s_add_u32 s14, s2, 0x8558000
	v_and_b32_e32 v5, 15, v18
	v_lshlrev_b32_e32 v22, 1, v21
	v_lshlrev_b32_e32 v18, 2, v18
	s_addc_u32 s15, s3, 0
	v_lshl_or_b32 v22, v5, 6, v22
	s_lshl_b32 s2, s17, 13
	v_and_b32_e32 v18, 32, v18
	v_bitop3_b32 v23, v22, s2, v18 bitop3:0xde
	s_lshl_b32 s2, s18, 5
	s_and_b32 s5, s2, 0x60
	s_add_i32 m0, s38, 0x18000
	v_lshl_add_u64 v[12:13], v[12:13], 0, s[50:51]
	s_lshl_b32 s43, s17, 6
	s_lshl_b32 s2, s5, 7
	s_waitcnt vmcnt(2)
	s_barrier
	global_load_lds_dwordx4 v[12:13], off
	v_lshl_add_u64 v[10:11], v[10:11], 0, s[50:51]
	s_add_i32 m0, s38, 0x1a000
	s_add_i32 s44, s38, 0x8000
	s_add_i32 s45, s38, 0xa000
	v_bitop3_b32 v148, v22, s2, v18 bitop3:0xde
	global_load_lds_dwordx4 v[10:11], off
	v_lshl_add_u64 v[6:7], v[6:7], 0, s[50:51]
	s_mov_b32 m0, s44
	s_add_u32 s2, s30, 0x580080
	global_load_lds_dwordx4 v[6:7], off
	v_lshl_add_u64 v[6:7], v[8:9], 0, s[50:51]
	s_mov_b32 m0, s45
	s_addc_u32 s3, s31, 0
	global_load_lds_dwordx4 v[6:7], off
	s_add_i32 m0, s38, 0x1c000
	v_lshl_add_u64 v[6:7], s[2:3], 0, v[0:1]
	global_load_lds_dwordx4 v[6:7], off
	v_lshl_add_u64 v[6:7], s[2:3], 0, v[136:137]
	s_add_i32 m0, s38, 0x1e000
	s_cmpk_lt_u32 s16, 0x100
	global_load_lds_dwordx4 v[6:7], off
	v_lshlrev_b32_e32 v6, 14, v14
	v_and_b32_e32 v6, 0xffff8000, v6
	v_lshl_add_u32 v6, v15, 11, v6
	v_and_b32_e32 v7, 1, v14
	v_lshl_or_b32 v6, v7, 6, v6
	v_lshl_add_u32 v138, v16, 1, v6
	v_bfe_u32 v24, v138, 11, 4
	v_bfe_u32 v25, v138, 15, 2
	v_and_b32_e32 v138, 0xfffe07ff, v138
	v_lshl_or_b32 v138, v24, 13, v138
	v_lshl_or_b32 v138, v25, 11, v138
	v_lshlrev_b32_e32 v6, 14, v17
	v_and_b32_e32 v6, 0xffff8000, v6
	s_waitcnt vmcnt(6)
	v_lshl_add_u32 v6, v19, 11, v6
	v_and_b32_e32 v7, 1, v17
	v_lshl_or_b32 v6, v7, 6, v6
	s_cselect_b64 s[16:17], -1, 0
	s_ashr_i32 s48, s40, 31
	s_ashr_i32 s58, s84, 31
	v_or_b32_e32 v149, s5, v21
	v_mov_b32_e32 v139, v1
	v_lshl_add_u32 v140, v20, 1, v6
	v_bfe_u32 v24, v140, 11, 4
	v_bfe_u32 v25, v140, 15, 2
	v_and_b32_e32 v140, 0xfffe07ff, v140
	v_lshl_or_b32 v140, v24, 13, v140
	v_lshl_or_b32 v140, v25, 11, v140
	v_mov_b32_e32 v141, v1
	s_mov_b32 s59, 0
	v_add_u32_e32 v150, 0, v23
	s_barrier
	s_branch .LBB0_76

.LBB0_78:
	s_ashr_i32 s21, s20, 31
	s_lshl_b64 s[22:23], s[20:21], 19
	s_add_u32 s22, s80, s22
	s_addc_u32 s23, s81, s23
	s_and_b64 s[24:25], s[2:3], exec
	s_cselect_b32 s5, s23, s29
	s_cselect_b32 s21, s22, s28
	s_ashr_i32 s19, s18, 31
	s_lshl_b64 s[24:25], s[18:19], 18
	s_add_u32 s24, s33, s24
	s_addc_u32 s25, s36, s25
	s_and_b64 s[34:35], s[2:3], exec
	s_cselect_b32 s19, s25, s31
	s_cselect_b32 s27, s24, s30
	s_add_u32 s28, s28, 0x40080
	s_addc_u32 s29, s29, 0
	s_add_u32 s60, s30, 0x100
	v_mov_b32_e32 v6, 0
	s_addc_u32 s61, s31, 0
	s_mov_b32 s62, -2
	v_mov_b32_e32 v7, v6
	v_mov_b32_e32 v8, v6
	v_mov_b32_e32 v9, v6
	v_mov_b32_e32 v10, v6
	v_mov_b32_e32 v11, v6
	v_mov_b32_e32 v12, v6
	v_mov_b32_e32 v13, v6
	v_mov_b32_e32 v22, v6
	v_mov_b32_e32 v23, v6
	v_mov_b32_e32 v24, v6
	v_mov_b32_e32 v25, v6
	v_mov_b32_e32 v26, v6
	v_mov_b32_e32 v27, v6
	v_mov_b32_e32 v28, v6
	v_mov_b32_e32 v29, v6
	v_mov_b32_e32 v38, v6
	v_mov_b32_e32 v39, v6
	v_mov_b32_e32 v40, v6
	v_mov_b32_e32 v41, v6
	v_mov_b32_e32 v42, v6
	v_mov_b32_e32 v43, v6
	v_mov_b32_e32 v44, v6
	v_mov_b32_e32 v45, v6
	v_mov_b32_e32 v54, v6
	v_mov_b32_e32 v55, v6
	v_mov_b32_e32 v56, v6
	v_mov_b32_e32 v57, v6
	v_mov_b32_e32 v58, v6
	v_mov_b32_e32 v59, v6
	v_mov_b32_e32 v60, v6
	v_mov_b32_e32 v61, v6
	v_mov_b32_e32 v14, v6
	v_mov_b32_e32 v15, v6
	v_mov_b32_e32 v16, v6
	v_mov_b32_e32 v17, v6
	v_mov_b32_e32 v18, v6
	v_mov_b32_e32 v19, v6
	v_mov_b32_e32 v20, v6
	v_mov_b32_e32 v21, v6
	v_mov_b32_e32 v30, v6
	v_mov_b32_e32 v31, v6
	v_mov_b32_e32 v32, v6
	v_mov_b32_e32 v33, v6
	v_mov_b32_e32 v34, v6
	v_mov_b32_e32 v35, v6
	v_mov_b32_e32 v36, v6
	v_mov_b32_e32 v37, v6
	v_mov_b32_e32 v46, v6
	v_mov_b32_e32 v47, v6
	v_mov_b32_e32 v48, v6
	v_mov_b32_e32 v49, v6
	v_mov_b32_e32 v50, v6
	v_mov_b32_e32 v51, v6
	v_mov_b32_e32 v52, v6
	v_mov_b32_e32 v53, v6
	v_mov_b32_e32 v62, v6
	v_mov_b32_e32 v63, v6
	v_mov_b32_e32 v64, v6
	v_mov_b32_e32 v65, v6
	v_mov_b32_e32 v66, v6
	v_mov_b32_e32 v67, v6
	v_mov_b32_e32 v68, v6
	v_mov_b32_e32 v69, v6
	v_mov_b32_e32 v70, v6
	v_mov_b32_e32 v71, v6
	v_mov_b32_e32 v72, v6
	v_mov_b32_e32 v73, v6
	v_mov_b32_e32 v74, v6
	v_mov_b32_e32 v75, v6
	v_mov_b32_e32 v76, v6
	v_mov_b32_e32 v77, v6
	v_mov_b32_e32 v86, v6
	v_mov_b32_e32 v87, v6
	v_mov_b32_e32 v88, v6
	v_mov_b32_e32 v89, v6
	v_mov_b32_e32 v90, v6
	v_mov_b32_e32 v91, v6
	v_mov_b32_e32 v92, v6
	v_mov_b32_e32 v93, v6
	v_mov_b32_e32 v102, v6
	v_mov_b32_e32 v103, v6
	v_mov_b32_e32 v104, v6
	v_mov_b32_e32 v105, v6
	v_mov_b32_e32 v106, v6
	v_mov_b32_e32 v107, v6
	v_mov_b32_e32 v108, v6
	v_mov_b32_e32 v109, v6
	v_mov_b32_e32 v118, v6
	v_mov_b32_e32 v119, v6
	v_mov_b32_e32 v120, v6
	v_mov_b32_e32 v121, v6
	v_mov_b32_e32 v122, v6
	v_mov_b32_e32 v123, v6
	v_mov_b32_e32 v124, v6
	v_mov_b32_e32 v125, v6
	v_mov_b32_e32 v78, v6
	v_mov_b32_e32 v79, v6
	v_mov_b32_e32 v80, v6
	v_mov_b32_e32 v81, v6
	v_mov_b32_e32 v82, v6
	v_mov_b32_e32 v83, v6
	v_mov_b32_e32 v84, v6
	v_mov_b32_e32 v85, v6
	v_mov_b32_e32 v94, v6
	v_mov_b32_e32 v95, v6
	v_mov_b32_e32 v96, v6
	v_mov_b32_e32 v97, v6
	v_mov_b32_e32 v98, v6
	v_mov_b32_e32 v99, v6
	v_mov_b32_e32 v100, v6
	v_mov_b32_e32 v101, v6
	v_mov_b32_e32 v110, v6
	v_mov_b32_e32 v111, v6
	v_mov_b32_e32 v112, v6
	v_mov_b32_e32 v113, v6
	v_mov_b32_e32 v114, v6
	v_mov_b32_e32 v115, v6
	v_mov_b32_e32 v116, v6
	v_mov_b32_e32 v117, v6
	v_mov_b32_e32 v126, v6
	v_mov_b32_e32 v127, v6
	v_mov_b32_e32 v128, v6
	v_mov_b32_e32 v129, v6
	v_mov_b32_e32 v130, v6
	v_mov_b32_e32 v131, v6
	v_mov_b32_e32 v132, v6
	v_mov_b32_e32 v133, v6
.LBB0_79:
	s_add_u32 s30, s28, 0xfffc0080
	s_addc_u32 s31, s29, -1
	s_add_i32 s63, 0, 0x10000
	s_cmp_eq_u32 s62, 12
	s_cselect_b32 s35, s5, s31
	s_cselect_b32 s34, s21, s30
	v_add_u32_e32 v146, s63, v148
	s_cselect_b32 s31, s19, s61
	s_cselect_b32 s30, s27, s60
	s_add_i32 s66, 0, 0x14000
	ds_read_b128 v[142:145], v146
	ds_read_b128 v[152:155], v146 offset:1024
	ds_read_b128 v[156:159], v146 offset:2048
	ds_read_b128 v[160:163], v146 offset:3072
	v_add_u32_e32 v146, s66, v148
	ds_read_b128 v[164:167], v146
	ds_read_b128 v[168:171], v146 offset:1024
	ds_read_b128 v[172:175], v146 offset:2048
	ds_read_b128 v[176:179], v146 offset:3072
	v_lshl_add_u64 v[146:147], s[28:29], 0, v[138:139]
	s_add_i32 m0, s38, 0xc000
	ds_read_b128 v[180:183], v150
	ds_read_b128 v[184:187], v150 offset:1024
	ds_read_b128 v[188:191], v150 offset:2048
	ds_read_b128 v[192:195], v150 offset:3072
	ds_read_b128 v[196:199], v150 offset:4096
	ds_read_b128 v[200:203], v150 offset:5120
	ds_read_b128 v[204:207], v150 offset:6144
	ds_read_b128 v[208:211], v150 offset:7168
	global_load_lds_dwordx4 v[146:147], off
	v_lshl_add_u64 v[146:147], s[28:29], 0, v[140:141]
	s_add_i32 m0, s38, 0xe000
	s_nop 0
	global_load_lds_dwordx4 v[146:147], off
	s_waitcnt vmcnt(8)
	s_waitcnt lgkmcnt(0)
	s_barrier
	s_setprio 1
	s_waitcnt lgkmcnt(0)
	v_mfma_f32_16x16x32_bf16 v[130:133], v[142:145], v[180:183], v[130:133]
	v_mfma_f32_16x16x32_bf16 v[126:129], v[156:159], v[180:183], v[126:129]
	v_mfma_f32_16x16x32_bf16 v[114:117], v[142:145], v[188:191], v[114:117]
	v_mfma_f32_16x16x32_bf16 v[110:113], v[156:159], v[188:191], v[110:113]
	v_mfma_f32_16x16x32_bf16 v[98:101], v[142:145], v[196:199], v[98:101]
	v_mfma_f32_16x16x32_bf16 v[94:97], v[156:159], v[196:199], v[94:97]
	v_mfma_f32_16x16x32_bf16 v[82:85], v[142:145], v[204:207], v[82:85]
	v_mfma_f32_16x16x32_bf16 v[78:81], v[156:159], v[204:207], v[78:81]
	v_mfma_f32_16x16x32_bf16 v[130:133], v[152:155], v[184:187], v[130:133]
	v_mfma_f32_16x16x32_bf16 v[126:129], v[160:163], v[184:187], v[126:129]
	v_mfma_f32_16x16x32_bf16 v[114:117], v[152:155], v[192:195], v[114:117]
	v_mfma_f32_16x16x32_bf16 v[110:113], v[160:163], v[192:195], v[110:113]
	v_mfma_f32_16x16x32_bf16 v[98:101], v[152:155], v[200:203], v[98:101]
	v_mfma_f32_16x16x32_bf16 v[94:97], v[160:163], v[200:203], v[94:97]
	v_mfma_f32_16x16x32_bf16 v[82:85], v[152:155], v[208:211], v[82:85]
	v_mfma_f32_16x16x32_bf16 v[78:81], v[160:163], v[208:211], v[78:81]
	s_setprio 0
	s_setprio 1
	v_mfma_f32_16x16x32_bf16 v[122:125], v[164:167], v[180:183], v[122:125]
	v_mfma_f32_16x16x32_bf16 v[118:121], v[172:175], v[180:183], v[118:121]
	v_mfma_f32_16x16x32_bf16 v[106:109], v[164:167], v[188:191], v[106:109]
	v_mfma_f32_16x16x32_bf16 v[102:105], v[172:175], v[188:191], v[102:105]
	v_mfma_f32_16x16x32_bf16 v[90:93], v[164:167], v[196:199], v[90:93]
	v_mfma_f32_16x16x32_bf16 v[86:89], v[172:175], v[196:199], v[86:89]
	v_mfma_f32_16x16x32_bf16 v[74:77], v[164:167], v[204:207], v[74:77]
	v_mfma_f32_16x16x32_bf16 v[70:73], v[172:175], v[204:207], v[70:73]
	v_mfma_f32_16x16x32_bf16 v[122:125], v[168:171], v[184:187], v[122:125]
	v_mfma_f32_16x16x32_bf16 v[118:121], v[176:179], v[184:187], v[118:121]
	v_mfma_f32_16x16x32_bf16 v[106:109], v[168:171], v[192:195], v[106:109]
	v_mfma_f32_16x16x32_bf16 v[102:105], v[176:179], v[192:195], v[102:105]
	v_mfma_f32_16x16x32_bf16 v[90:93], v[168:171], v[200:203], v[90:93]
	v_mfma_f32_16x16x32_bf16 v[86:89], v[176:179], v[200:203], v[86:89]
	v_mfma_f32_16x16x32_bf16 v[74:77], v[168:171], v[208:211], v[74:77]
	v_mfma_f32_16x16x32_bf16 v[70:73], v[176:179], v[208:211], v[70:73]
	s_setprio 0
	s_barrier
	s_add_i32 s63, s63, s37
	v_lshl_add_u64 v[146:147], s[30:31], 0, v[0:1]
	s_mov_b32 m0, s63
	ds_read_b128 v[180:183], v150 offset:16384
	ds_read_b128 v[184:187], v150 offset:17408
	ds_read_b128 v[188:191], v150 offset:18432
	ds_read_b128 v[192:195], v150 offset:19456
	ds_read_b128 v[196:199], v150 offset:20480
	ds_read_b128 v[200:203], v150 offset:21504
	ds_read_b128 v[204:207], v150 offset:22528
	ds_read_b128 v[208:211], v150 offset:23552
	global_load_lds_dwordx4 v[146:147], off
	s_add_i32 m0, s63, 0x2000
	s_add_u32 s64, s30, 0x580000
	v_lshl_add_u64 v[212:213], s[30:31], 0, v[136:137]
	s_addc_u32 s65, s31, 0
	s_add_i32 s63, s66, s37
	global_load_lds_dwordx4 v[212:213], off
	v_lshl_add_u64 v[214:215], s[64:65], 0, v[0:1]
	s_mov_b32 m0, s63
	v_lshl_add_u64 v[216:217], s[34:35], 0, v[134:135]
	global_load_lds_dwordx4 v[214:215], off
	v_lshl_add_u64 v[214:215], s[64:65], 0, v[136:137]
	s_add_i32 m0, s63, 0x2000
	s_nop 0
	global_load_lds_dwordx4 v[214:215], off
	v_lshl_add_u64 v[214:215], s[34:35], 0, v[2:3]
	s_mov_b32 m0, s38
	s_nop 0
	global_load_lds_dwordx4 v[214:215], off
	s_mov_b32 m0, s39
	s_nop 0
	global_load_lds_dwordx4 v[216:217], off
	s_waitcnt vmcnt(8)
	s_waitcnt lgkmcnt(0)
	s_barrier
	s_setprio 1
	s_waitcnt lgkmcnt(0)
	v_mfma_f32_16x16x32_bf16 v[66:69], v[142:145], v[180:183], v[66:69]
	v_mfma_f32_16x16x32_bf16 v[62:65], v[156:159], v[180:183], v[62:65]
	v_mfma_f32_16x16x32_bf16 v[50:53], v[142:145], v[188:191], v[50:53]
	v_mfma_f32_16x16x32_bf16 v[46:49], v[156:159], v[188:191], v[46:49]
	v_mfma_f32_16x16x32_bf16 v[34:37], v[142:145], v[196:199], v[34:37]
	v_mfma_f32_16x16x32_bf16 v[30:33], v[156:159], v[196:199], v[30:33]
	v_mfma_f32_16x16x32_bf16 v[18:21], v[142:145], v[204:207], v[18:21]
	v_mfma_f32_16x16x32_bf16 v[14:17], v[156:159], v[204:207], v[14:17]
	v_mfma_f32_16x16x32_bf16 v[66:69], v[152:155], v[184:187], v[66:69]
	v_mfma_f32_16x16x32_bf16 v[62:65], v[160:163], v[184:187], v[62:65]
	v_mfma_f32_16x16x32_bf16 v[50:53], v[152:155], v[192:195], v[50:53]
	v_mfma_f32_16x16x32_bf16 v[46:49], v[160:163], v[192:195], v[46:49]
	v_mfma_f32_16x16x32_bf16 v[34:37], v[152:155], v[200:203], v[34:37]
	v_mfma_f32_16x16x32_bf16 v[30:33], v[160:163], v[200:203], v[30:33]
	v_mfma_f32_16x16x32_bf16 v[18:21], v[152:155], v[208:211], v[18:21]
	v_mfma_f32_16x16x32_bf16 v[14:17], v[160:163], v[208:211], v[14:17]
	s_setprio 0
	s_setprio 1
	v_mfma_f32_16x16x32_bf16 v[58:61], v[164:167], v[180:183], v[58:61]
	v_mfma_f32_16x16x32_bf16 v[54:57], v[172:175], v[180:183], v[54:57]
	v_mfma_f32_16x16x32_bf16 v[42:45], v[164:167], v[188:191], v[42:45]
	v_mfma_f32_16x16x32_bf16 v[38:41], v[172:175], v[188:191], v[38:41]
	v_mfma_f32_16x16x32_bf16 v[26:29], v[164:167], v[196:199], v[26:29]
	v_mfma_f32_16x16x32_bf16 v[22:25], v[172:175], v[196:199], v[22:25]
	v_mfma_f32_16x16x32_bf16 v[10:13], v[164:167], v[204:207], v[10:13]
	v_mfma_f32_16x16x32_bf16 v[6:9], v[172:175], v[204:207], v[6:9]
	v_mfma_f32_16x16x32_bf16 v[58:61], v[168:171], v[184:187], v[58:61]
	v_mfma_f32_16x16x32_bf16 v[54:57], v[176:179], v[184:187], v[54:57]
	v_mfma_f32_16x16x32_bf16 v[42:45], v[168:171], v[192:195], v[42:45]
	v_mfma_f32_16x16x32_bf16 v[38:41], v[176:179], v[192:195], v[38:41]
	v_mfma_f32_16x16x32_bf16 v[26:29], v[168:171], v[200:203], v[26:29]
	v_mfma_f32_16x16x32_bf16 v[22:25], v[176:179], v[200:203], v[22:25]
	v_mfma_f32_16x16x32_bf16 v[10:13], v[168:171], v[208:211], v[10:13]
	v_mfma_f32_16x16x32_bf16 v[6:9], v[176:179], v[208:211], v[6:9]
	s_setprio 0
	s_barrier
	s_add_i32 s63, 0, 0x18000
	v_add_u32_e32 v151, s63, v148
	s_add_i32 s64, 0, 0x1c000
	ds_read_b128 v[142:145], v151
	ds_read_b128 v[152:155], v151 offset:1024
	ds_read_b128 v[156:159], v151 offset:2048
	ds_read_b128 v[160:163], v151 offset:3072
	v_add_u32_e32 v151, s64, v148
	ds_read_b128 v[164:167], v151
	ds_read_b128 v[168:171], v151 offset:1024
	ds_read_b128 v[172:175], v151 offset:2048
	ds_read_b128 v[176:179], v151 offset:3072
	s_add_u32 s34, s34, 0x40000
	s_addc_u32 s35, s35, 0
	s_mov_b32 m0, s41
	v_lshl_add_u64 v[220:221], s[34:35], 0, v[2:3]
	ds_read_b128 v[180:183], v150 offset:32768
	ds_read_b128 v[184:187], v150 offset:33792
	ds_read_b128 v[188:191], v150 offset:34816
	ds_read_b128 v[192:195], v150 offset:35840
	ds_read_b128 v[196:199], v150 offset:36864
	ds_read_b128 v[200:203], v150 offset:37888
	ds_read_b128 v[204:207], v150 offset:38912
	ds_read_b128 v[208:211], v150 offset:39936
	global_load_lds_dwordx4 v[220:221], off
	v_lshl_add_u64 v[220:221], s[34:35], 0, v[134:135]
	s_mov_b32 m0, s42
	s_nop 0
	global_load_lds_dwordx4 v[220:221], off
	s_waitcnt vmcnt(8)
	s_waitcnt lgkmcnt(0)
	s_barrier
	s_setprio 1
	s_waitcnt lgkmcnt(0)
	v_mfma_f32_16x16x32_bf16 v[130:133], v[142:145], v[180:183], v[130:133]
	v_mfma_f32_16x16x32_bf16 v[126:129], v[156:159], v[180:183], v[126:129]
	v_mfma_f32_16x16x32_bf16 v[114:117], v[142:145], v[188:191], v[114:117]
	v_mfma_f32_16x16x32_bf16 v[110:113], v[156:159], v[188:191], v[110:113]
	v_mfma_f32_16x16x32_bf16 v[98:101], v[142:145], v[196:199], v[98:101]
	v_mfma_f32_16x16x32_bf16 v[94:97], v[156:159], v[196:199], v[94:97]
	v_mfma_f32_16x16x32_bf16 v[82:85], v[142:145], v[204:207], v[82:85]
	v_mfma_f32_16x16x32_bf16 v[78:81], v[156:159], v[204:207], v[78:81]
	v_mfma_f32_16x16x32_bf16 v[130:133], v[152:155], v[184:187], v[130:133]
	v_mfma_f32_16x16x32_bf16 v[126:129], v[160:163], v[184:187], v[126:129]
	v_mfma_f32_16x16x32_bf16 v[114:117], v[152:155], v[192:195], v[114:117]
	v_mfma_f32_16x16x32_bf16 v[110:113], v[160:163], v[192:195], v[110:113]
	v_mfma_f32_16x16x32_bf16 v[98:101], v[152:155], v[200:203], v[98:101]
	v_mfma_f32_16x16x32_bf16 v[94:97], v[160:163], v[200:203], v[94:97]
	v_mfma_f32_16x16x32_bf16 v[82:85], v[152:155], v[208:211], v[82:85]
	v_mfma_f32_16x16x32_bf16 v[78:81], v[160:163], v[208:211], v[78:81]
	s_setprio 0
	s_setprio 1
	v_mfma_f32_16x16x32_bf16 v[122:125], v[164:167], v[180:183], v[122:125]
	v_mfma_f32_16x16x32_bf16 v[118:121], v[172:175], v[180:183], v[118:121]
	v_mfma_f32_16x16x32_bf16 v[106:109], v[164:167], v[188:191], v[106:109]
	v_mfma_f32_16x16x32_bf16 v[102:105], v[172:175], v[188:191], v[102:105]
	v_mfma_f32_16x16x32_bf16 v[90:93], v[164:167], v[196:199], v[90:93]
	v_mfma_f32_16x16x32_bf16 v[86:89], v[172:175], v[196:199], v[86:89]
	v_mfma_f32_16x16x32_bf16 v[74:77], v[164:167], v[204:207], v[74:77]
	v_mfma_f32_16x16x32_bf16 v[70:73], v[172:175], v[204:207], v[70:73]
	v_mfma_f32_16x16x32_bf16 v[122:125], v[168:171], v[184:187], v[122:125]
	v_mfma_f32_16x16x32_bf16 v[118:121], v[176:179], v[184:187], v[118:121]
	v_mfma_f32_16x16x32_bf16 v[106:109], v[168:171], v[192:195], v[106:109]
	v_mfma_f32_16x16x32_bf16 v[102:105], v[176:179], v[192:195], v[102:105]
	v_mfma_f32_16x16x32_bf16 v[90:93], v[168:171], v[200:203], v[90:93]
	v_mfma_f32_16x16x32_bf16 v[86:89], v[176:179], v[200:203], v[86:89]
	v_mfma_f32_16x16x32_bf16 v[74:77], v[168:171], v[208:211], v[74:77]
	v_mfma_f32_16x16x32_bf16 v[70:73], v[176:179], v[208:211], v[70:73]
	s_setprio 0
	s_barrier
	s_add_i32 s34, s63, s37
	v_lshl_add_u64 v[146:147], v[146:147], 0, s[50:51]
	s_mov_b32 m0, s34
	ds_read_b128 v[180:183], v150 offset:49152
	ds_read_b128 v[184:187], v150 offset:50176
	ds_read_b128 v[188:191], v150 offset:51200
	ds_read_b128 v[192:195], v150 offset:52224
	ds_read_b128 v[196:199], v150 offset:53248
	ds_read_b128 v[200:203], v150 offset:54272
	ds_read_b128 v[204:207], v150 offset:55296
	ds_read_b128 v[208:211], v150 offset:56320
	global_load_lds_dwordx4 v[146:147], off
	s_add_i32 m0, s34, 0x2000
	s_add_u32 s30, s30, 0x580080
	v_lshl_add_u64 v[146:147], v[212:213], 0, s[50:51]
	s_addc_u32 s31, s31, 0
	s_add_i32 s34, s64, s37
	global_load_lds_dwordx4 v[146:147], off
	v_lshl_add_u64 v[146:147], s[30:31], 0, v[0:1]
	s_mov_b32 m0, s34
	s_nop 0
	global_load_lds_dwordx4 v[146:147], off
	v_lshl_add_u64 v[146:147], s[30:31], 0, v[136:137]
	s_add_i32 m0, s34, 0x2000
	s_nop 0
	global_load_lds_dwordx4 v[146:147], off
	v_lshl_add_u64 v[146:147], v[214:215], 0, s[50:51]
	s_mov_b32 m0, s44
	s_nop 0
	global_load_lds_dwordx4 v[146:147], off
	v_lshl_add_u64 v[146:147], v[216:217], 0, s[50:51]
	s_mov_b32 m0, s45
	s_nop 0
	global_load_lds_dwordx4 v[146:147], off
	s_waitcnt vmcnt(8)
	s_waitcnt lgkmcnt(0)
	s_barrier
	s_setprio 1
	s_waitcnt lgkmcnt(0)
	v_mfma_f32_16x16x32_bf16 v[66:69], v[142:145], v[180:183], v[66:69]
	v_mfma_f32_16x16x32_bf16 v[62:65], v[156:159], v[180:183], v[62:65]
	v_mfma_f32_16x16x32_bf16 v[50:53], v[142:145], v[188:191], v[50:53]
	v_mfma_f32_16x16x32_bf16 v[46:49], v[156:159], v[188:191], v[46:49]
	v_mfma_f32_16x16x32_bf16 v[34:37], v[142:145], v[196:199], v[34:37]
	v_mfma_f32_16x16x32_bf16 v[30:33], v[156:159], v[196:199], v[30:33]
	v_mfma_f32_16x16x32_bf16 v[18:21], v[142:145], v[204:207], v[18:21]
	v_mfma_f32_16x16x32_bf16 v[14:17], v[156:159], v[204:207], v[14:17]
	v_mfma_f32_16x16x32_bf16 v[66:69], v[152:155], v[184:187], v[66:69]
	v_mfma_f32_16x16x32_bf16 v[62:65], v[160:163], v[184:187], v[62:65]
	v_mfma_f32_16x16x32_bf16 v[50:53], v[152:155], v[192:195], v[50:53]
	v_mfma_f32_16x16x32_bf16 v[46:49], v[160:163], v[192:195], v[46:49]
	v_mfma_f32_16x16x32_bf16 v[34:37], v[152:155], v[200:203], v[34:37]
	v_mfma_f32_16x16x32_bf16 v[30:33], v[160:163], v[200:203], v[30:33]
	v_mfma_f32_16x16x32_bf16 v[18:21], v[152:155], v[208:211], v[18:21]
	v_mfma_f32_16x16x32_bf16 v[14:17], v[160:163], v[208:211], v[14:17]
	s_setprio 0
	s_setprio 1
	v_mfma_f32_16x16x32_bf16 v[58:61], v[164:167], v[180:183], v[58:61]
	v_mfma_f32_16x16x32_bf16 v[54:57], v[172:175], v[180:183], v[54:57]
	v_mfma_f32_16x16x32_bf16 v[42:45], v[164:167], v[188:191], v[42:45]
	v_mfma_f32_16x16x32_bf16 v[38:41], v[172:175], v[188:191], v[38:41]
	v_mfma_f32_16x16x32_bf16 v[26:29], v[164:167], v[196:199], v[26:29]
	v_mfma_f32_16x16x32_bf16 v[22:25], v[172:175], v[196:199], v[22:25]
	v_mfma_f32_16x16x32_bf16 v[10:13], v[164:167], v[204:207], v[10:13]
	v_mfma_f32_16x16x32_bf16 v[6:9], v[172:175], v[204:207], v[6:9]
	v_mfma_f32_16x16x32_bf16 v[58:61], v[168:171], v[184:187], v[58:61]
	v_mfma_f32_16x16x32_bf16 v[54:57], v[176:179], v[184:187], v[54:57]
	v_mfma_f32_16x16x32_bf16 v[42:45], v[168:171], v[192:195], v[42:45]
	v_mfma_f32_16x16x32_bf16 v[38:41], v[176:179], v[192:195], v[38:41]
	v_mfma_f32_16x16x32_bf16 v[26:29], v[168:171], v[200:203], v[26:29]
	v_mfma_f32_16x16x32_bf16 v[22:25], v[176:179], v[200:203], v[22:25]
	v_mfma_f32_16x16x32_bf16 v[10:13], v[168:171], v[208:211], v[10:13]
	v_mfma_f32_16x16x32_bf16 v[6:9], v[176:179], v[208:211], v[6:9]
	s_setprio 0
	s_barrier
	s_add_i32 s62, s62, 2
	s_add_u32 s28, s28, 0x100
	s_addc_u32 s29, s29, 0
	s_add_u32 s60, s60, 0x100
	s_addc_u32 s61, s61, 0
	s_cmp_gt_u32 s62, 13
	s_cbranch_scc0 .LBB0_79
	s_and_b64 vcc, exec, s[16:17]
	s_cbranch_vccz .LBB0_82
	s_barrier
.LBB0_82:
	s_cmp_gt_i32 s4, 63
	s_cbranch_scc1 .Lup_raw_epi
	s_load_dwordx4 s[28:31], s[54:55], 0xb8
	v_readlane_b32 s21, v253, 41
	v_mbcnt_lo_u32_b32 v142, -1, 0
	v_mbcnt_hi_u32_b32 v142, -1, v142
	v_and_b32_e32 v143, 3, v142
	v_lshrrev_b32_e32 v144, 2, v142
	v_lshl_or_b32 v145, v143, 4, v144
	v_lshlrev_b32_e32 v145, 2, v145
	s_lshl_b32 s19, s4, 8
	s_add_i32 s19, s19, s43
	s_lshl_b32 s26, s26, 7
	v_add_u32_e32 v224, s26, v149
	v_lshlrev_b32_e32 v226, 2, v224
	v_mov_b32_e32 v227, 0
	s_mul_i32 s27, s21, 0x10800
	s_mul_i32 s21, s21, 0x5800
	s_waitcnt lgkmcnt(0)
	s_add_u32 s28, s28, s27
	s_addc_u32 s29, s29, 0
	s_add_u32 s30, s30, s21
	s_addc_u32 s31, s31, 0
	global_load_dwordx4 v[152:155], v226, s[28:29] offset:0
	global_load_dwordx4 v[156:159], v226, s[28:29] offset:16
	v_add_u32_e32 v225, 0x2c00, v226
	global_load_dwordx4 v[184:187], v225, s[28:29]
	v_add_u32_e32 v225, 0x2c10, v226
	global_load_dwordx4 v[188:191], v225, s[28:29]
	v_add_u32_e32 v225, 0x5800, v226
	global_load_dwordx4 v[160:163], v225, s[28:29]
	v_add_u32_e32 v225, 0x5810, v226
	global_load_dwordx4 v[164:167], v225, s[28:29]
	v_add_u32_e32 v225, 0x8400, v226
	global_load_dwordx4 v[192:195], v225, s[28:29]
	v_add_u32_e32 v225, 0x8410, v226
	global_load_dwordx4 v[196:199], v225, s[28:29]
	v_add_u32_e32 v225, 0xb000, v226
	global_load_dwordx4 v[168:171], v225, s[28:29]
	v_add_u32_e32 v225, 0xb010, v226
	global_load_dwordx4 v[172:175], v225, s[28:29]
	v_add_u32_e32 v225, 0xdc00, v226
	global_load_dwordx4 v[200:203], v225, s[28:29]
	v_add_u32_e32 v225, 0xdc10, v226
	global_load_dwordx4 v[204:207], v225, s[28:29]
	global_load_dwordx4 v[176:179], v226, s[30:31] offset:0
	global_load_dwordx4 v[180:183], v226, s[30:31] offset:16
	v_add_u32_e32 v225, 0x2c00, v226
	global_load_dwordx4 v[208:211], v225, s[30:31]
	v_add_u32_e32 v225, 0x2c10, v226
	global_load_dwordx4 v[212:215], v225, s[30:31]
	v_lshl_add_u32 v228, v144, 2, s19
	v_and_b32_e32 v229, 0x60, v149
	v_lshl_or_b32 v229, v143, 3, v229
	v_add_u32_e32 v229, s26, v229
	v_mov_b64_e32 v[146:147], s[10:11]
	s_movk_i32 s27, 0x1600
	v_mad_u64_u32 v[216:217], s[4:5], v228, s27, v[146:147]
	v_lshlrev_b32_e32 v229, 1, v229
	v_mov_b32_e32 v228, v229
	v_mov_b32_e32 v229, 0
	v_lshl_add_u64 v[216:217], v[216:217], 0, v[228:229]
	s_and_b32 s27, s19, 0x1fc0
	s_cmpk_lg_u32 s27, 0x1f40
	s_cbranch_scc1 .Lup_f_notail
	v_cmp_eq_u32_e32 vcc, 15, v5
	s_and_saveexec_b64 s[4:5], vcc
	v_lshl_add_u32 v228, v5, 2, s19
	v_add_u32_e32 v229, 130, v228
	v_lshrrev_b32_e32 v225, 13, v229
	v_and_b32_e32 v229, 0x1fff, v229
	v_lshl_add_u32 v229, v225, 1, v229
	v_add_u32_e32 v229, 0xffffe002, v229
	v_mov_b64_e32 v[146:147], s[12:13]
	v_mad_u64_u32 v[146:147], s[28:29], v229, s90, v[146:147]
	v_lshl_add_u64 v[146:147], v[146:147], 0, v[226:227]
	global_store_dwordx4 v[146:147], v[34:37], off
	global_store_dwordx4 v[146:147], v[30:33], off offset:16
	v_add_co_u32_e32 v146, vcc, 0x2c00, v146
	v_addc_co_u32_e32 v147, vcc, 0, v147, vcc
	global_store_dwordx4 v[146:147], v[26:29], off
	global_store_dwordx4 v[146:147], v[22:25], off offset:16
	v_add_u32_e32 v229, 131, v228
	v_lshrrev_b32_e32 v225, 13, v229
	v_and_b32_e32 v229, 0x1fff, v229
	v_lshl_add_u32 v229, v225, 1, v229
	v_add_u32_e32 v229, 0xffffe002, v229
	v_mov_b64_e32 v[146:147], s[12:13]
	v_mad_u64_u32 v[146:147], s[28:29], v229, s90, v[146:147]
	v_lshl_add_u64 v[146:147], v[146:147], 0, v[226:227]
	global_store_dwordx4 v[146:147], v[18:21], off
	global_store_dwordx4 v[146:147], v[14:17], off offset:16
	v_add_co_u32_e32 v146, vcc, 0x2c00, v146
	v_addc_co_u32_e32 v147, vcc, 0, v147, vcc
	global_store_dwordx4 v[146:147], v[10:13], off
	global_store_dwordx4 v[146:147], v[6:9], off offset:16
	s_or_b64 exec, exec, s[4:5]
	s_waitcnt vmcnt(0)
.Lup_f_notail:
	s_add_u32 s30, s10, 0x6000000
	s_addc_u32 s31, s11, 0
	v_lshlrev_b32_e32 v228, 1, v224
	v_mov_b32_e32 v229, 0
	v_lshl_add_u64 v[228:229], s[30:31], 0, v[228:229]
	s_lshr_b32 s27, s19, 6
	s_mul_i32 s27, s27, 0xb000
	v_cvt_pk_bf16_f32 v242, v130, v131
	v_cvt_pk_bf16_f32 v243, v132, v133
	v_cvt_pk_bf16_f32 v244, v126, v127
	v_cvt_pk_bf16_f32 v245, v128, v129
	v_cvt_pk_bf16_f32 v246, v122, v123
	v_cvt_pk_bf16_f32 v247, v124, v125
	v_cvt_pk_bf16_f32 v248, v118, v119
	v_cvt_pk_bf16_f32 v249, v120, v121
	s_mov_b32 exec_lo, 0x00010001
	s_mov_b32 exec_hi, 0x00010001
	s_add_u32 s28, s27, 0x0
	s_mov_b32 s29, 0
	v_lshl_add_u64 v[146:147], v[228:229], 0, s[28:29]
	global_store_dwordx4 v[146:147], v[242:245], off
	s_add_u32 s28, s28, 0x1600
	v_lshl_add_u64 v[146:147], v[228:229], 0, s[28:29]
	global_store_dwordx4 v[146:147], v[246:249], off
	v_cvt_pk_bf16_f32 v242, v114, v115
	v_cvt_pk_bf16_f32 v243, v116, v117
	v_cvt_pk_bf16_f32 v244, v110, v111
	v_cvt_pk_bf16_f32 v245, v112, v113
	v_cvt_pk_bf16_f32 v246, v106, v107
	v_cvt_pk_bf16_f32 v247, v108, v109
	v_cvt_pk_bf16_f32 v248, v102, v103
	v_cvt_pk_bf16_f32 v249, v104, v105
	s_add_u32 s28, s27, 0x2c00
	s_mov_b32 s29, 0
	v_lshl_add_u64 v[146:147], v[228:229], 0, s[28:29]
	global_store_dwordx4 v[146:147], v[242:245], off
	s_add_u32 s28, s28, 0x1600
	v_lshl_add_u64 v[146:147], v[228:229], 0, s[28:29]
	global_store_dwordx4 v[146:147], v[246:249], off
	s_mov_b64 exec, -1
	v_cvt_pk_bf16_f32 v242, v98, v99
	v_cvt_pk_bf16_f32 v243, v100, v101
	v_cvt_pk_bf16_f32 v244, v94, v95
	v_cvt_pk_bf16_f32 v245, v96, v97
	v_cvt_pk_bf16_f32 v246, v90, v91
	v_cvt_pk_bf16_f32 v247, v92, v93
	v_cvt_pk_bf16_f32 v248, v86, v87
	v_cvt_pk_bf16_f32 v249, v88, v89
	s_mov_b32 exec_lo, 0x80008000
	s_mov_b32 exec_hi, 0x80008000
	s_add_u32 s28, s27, 0x5800
	s_mov_b32 s29, 0
	v_lshl_add_u64 v[146:147], v[228:229], 0, s[28:29]
	global_store_dwordx4 v[146:147], v[242:245], off
	s_add_u32 s28, s28, 0x1600
	v_lshl_add_u64 v[146:147], v[228:229], 0, s[28:29]
	global_store_dwordx4 v[146:147], v[246:249], off
	v_cvt_pk_bf16_f32 v242, v82, v83
	v_cvt_pk_bf16_f32 v243, v84, v85
	v_cvt_pk_bf16_f32 v244, v78, v79
	v_cvt_pk_bf16_f32 v245, v80, v81
	v_cvt_pk_bf16_f32 v246, v74, v75
	v_cvt_pk_bf16_f32 v247, v76, v77
	v_cvt_pk_bf16_f32 v248, v70, v71
	v_cvt_pk_bf16_f32 v249, v72, v73
	s_add_u32 s28, s27, 0x8400
	s_mov_b32 s29, 0
	v_lshl_add_u64 v[146:147], v[228:229], 0, s[28:29]
	global_store_dwordx4 v[146:147], v[242:245], off
	s_add_u32 s28, s28, 0x1600
	v_lshl_add_u64 v[146:147], v[228:229], 0, s[28:29]
	global_store_dwordx4 v[146:147], v[246:249], off
	s_mov_b64 exec, -1
	v_cvt_pk_bf16_f32 v242, v66, v67
	v_cvt_pk_bf16_f32 v243, v68, v69
	v_cvt_pk_bf16_f32 v244, v62, v63
	v_cvt_pk_bf16_f32 v245, v64, v65
	v_cvt_pk_bf16_f32 v246, v58, v59
	v_cvt_pk_bf16_f32 v247, v60, v61
	v_cvt_pk_bf16_f32 v248, v54, v55
	v_cvt_pk_bf16_f32 v249, v56, v57
	s_mov_b32 exec_lo, 0x00010001
	s_mov_b32 exec_hi, 0x00010001
	s_add_u32 s28, s27, 0x16000
	s_mov_b32 s29, 0
	v_lshl_add_u64 v[146:147], v[228:229], 0, s[28:29]
	global_store_dwordx4 v[146:147], v[242:245], off
	s_add_u32 s28, s28, 0x1600
	v_lshl_add_u64 v[146:147], v[228:229], 0, s[28:29]
	global_store_dwordx4 v[146:147], v[246:249], off
	v_cvt_pk_bf16_f32 v242, v50, v51
	v_cvt_pk_bf16_f32 v243, v52, v53
	v_cvt_pk_bf16_f32 v244, v46, v47
	v_cvt_pk_bf16_f32 v245, v48, v49
	v_cvt_pk_bf16_f32 v246, v42, v43
	v_cvt_pk_bf16_f32 v247, v44, v45
	v_cvt_pk_bf16_f32 v248, v38, v39
	v_cvt_pk_bf16_f32 v249, v40, v41
	s_add_u32 s28, s27, 0x18c00
	s_mov_b32 s29, 0
	v_lshl_add_u64 v[146:147], v[228:229], 0, s[28:29]
	global_store_dwordx4 v[146:147], v[242:245], off
	s_add_u32 s28, s28, 0x1600
	v_lshl_add_u64 v[146:147], v[228:229], 0, s[28:29]
	global_store_dwordx4 v[146:147], v[246:249], off
	s_mov_b64 exec, -1
	v_cvt_pk_bf16_f32 v242, v34, v35
	v_cvt_pk_bf16_f32 v243, v36, v37
	v_cvt_pk_bf16_f32 v244, v30, v31
	v_cvt_pk_bf16_f32 v245, v32, v33
	v_cvt_pk_bf16_f32 v246, v26, v27
	v_cvt_pk_bf16_f32 v247, v28, v29
	v_cvt_pk_bf16_f32 v248, v22, v23
	v_cvt_pk_bf16_f32 v249, v24, v25
	s_mov_b32 exec_lo, 0x80008000
	s_mov_b32 exec_hi, 0x80008000
	s_add_u32 s28, s27, 0x1b800
	s_mov_b32 s29, 0
	v_lshl_add_u64 v[146:147], v[228:229], 0, s[28:29]
	global_store_dwordx4 v[146:147], v[242:245], off
	s_add_u32 s28, s28, 0x1600
	v_lshl_add_u64 v[146:147], v[228:229], 0, s[28:29]
	global_store_dwordx4 v[146:147], v[246:249], off
	v_cvt_pk_bf16_f32 v242, v18, v19
	v_cvt_pk_bf16_f32 v243, v20, v21
	v_cvt_pk_bf16_f32 v244, v14, v15
	v_cvt_pk_bf16_f32 v245, v16, v17
	v_cvt_pk_bf16_f32 v246, v10, v11
	v_cvt_pk_bf16_f32 v247, v12, v13
	v_cvt_pk_bf16_f32 v248, v6, v7
	v_cvt_pk_bf16_f32 v249, v8, v9
	s_add_u32 s28, s27, 0x1e400
	s_mov_b32 s29, 0
	v_lshl_add_u64 v[146:147], v[228:229], 0, s[28:29]
	global_store_dwordx4 v[146:147], v[242:245], off
	s_add_u32 s28, s28, 0x1600
	v_lshl_add_u64 v[146:147], v[228:229], 0, s[28:29]
	global_store_dwordx4 v[146:147], v[246:249], off
	s_mov_b64 exec, -1
	s_mov_b32 s30, 0xbfb8aa3b
	s_mov_b32 s31, 0xbfb8aa3b
	s_waitcnt vmcnt(16)
	v_pk_fma_f32 v[220:221], v[130:131], v[168:169], v[176:177]
	v_pk_fma_f32 v[222:223], v[114:115], v[168:169], v[176:177]
	v_fmac_f32_dpp v220, v82, v160 row_shr:1 row_mask:0xf bank_mask:0xf
	v_fmac_f32_dpp v220, v98, v152 row_shr:1 row_mask:0xf bank_mask:0xf
	v_fmac_f32_dpp v222, v82, v152 row_shr:1 row_mask:0xf bank_mask:0xf
	v_fmac_f32_dpp v221, v83, v161 row_shr:1 row_mask:0xf bank_mask:0xf
	v_fmac_f32_dpp v221, v99, v153 row_shr:1 row_mask:0xf bank_mask:0xf
	v_fmac_f32_dpp v223, v83, v153 row_shr:1 row_mask:0xf bank_mask:0xf
	v_pk_fma_f32 v[222:223], v[130:131], v[160:161], v[222:223]
	v_pk_fma_f32 v[82:83], v[82:83], v[168:169], v[176:177]
	v_pk_fma_f32 v[82:83], v[98:99], v[160:161], v[82:83]
	v_pk_fma_f32 v[82:83], v[114:115], v[152:153], v[82:83]
	v_pk_fma_f32 v[98:99], v[98:99], v[168:169], v[176:177]
	v_pk_fma_f32 v[98:99], v[114:115], v[160:161], v[98:99]
	v_pk_fma_f32 v[98:99], v[130:131], v[152:153], v[98:99]
	v_mov_b32_e32 v130, v220
	v_mov_b32_e32 v131, v221
	v_mov_b32_e32 v114, v222
	v_mov_b32_e32 v115, v223
	v_pk_fma_f32 v[220:221], v[132:133], v[170:171], v[178:179]
	v_pk_fma_f32 v[222:223], v[116:117], v[170:171], v[178:179]
	v_fmac_f32_dpp v220, v84, v162 row_shr:1 row_mask:0xf bank_mask:0xf
	v_fmac_f32_dpp v220, v100, v154 row_shr:1 row_mask:0xf bank_mask:0xf
	v_fmac_f32_dpp v222, v84, v154 row_shr:1 row_mask:0xf bank_mask:0xf
	v_fmac_f32_dpp v221, v85, v163 row_shr:1 row_mask:0xf bank_mask:0xf
	v_fmac_f32_dpp v221, v101, v155 row_shr:1 row_mask:0xf bank_mask:0xf
	v_fmac_f32_dpp v223, v85, v155 row_shr:1 row_mask:0xf bank_mask:0xf
	v_pk_fma_f32 v[222:223], v[132:133], v[162:163], v[222:223]
	v_pk_fma_f32 v[84:85], v[84:85], v[170:171], v[178:179]
	v_pk_fma_f32 v[84:85], v[100:101], v[162:163], v[84:85]
	v_pk_fma_f32 v[84:85], v[116:117], v[154:155], v[84:85]
	v_pk_fma_f32 v[100:101], v[100:101], v[170:171], v[178:179]
	v_pk_fma_f32 v[100:101], v[116:117], v[162:163], v[100:101]
	v_pk_fma_f32 v[100:101], v[132:133], v[154:155], v[100:101]
	v_mov_b32_e32 v132, v220
	v_mov_b32_e32 v133, v221
	v_mov_b32_e32 v116, v222
	v_mov_b32_e32 v117, v223
	v_pk_fma_f32 v[220:221], v[126:127], v[172:173], v[180:181]
	v_pk_fma_f32 v[222:223], v[110:111], v[172:173], v[180:181]
	v_fmac_f32_dpp v220, v78, v164 row_shr:1 row_mask:0xf bank_mask:0xf
	v_fmac_f32_dpp v220, v94, v156 row_shr:1 row_mask:0xf bank_mask:0xf
	v_fmac_f32_dpp v222, v78, v156 row_shr:1 row_mask:0xf bank_mask:0xf
	v_fmac_f32_dpp v221, v79, v165 row_shr:1 row_mask:0xf bank_mask:0xf
	v_fmac_f32_dpp v221, v95, v157 row_shr:1 row_mask:0xf bank_mask:0xf
	v_fmac_f32_dpp v223, v79, v157 row_shr:1 row_mask:0xf bank_mask:0xf
	v_pk_fma_f32 v[222:223], v[126:127], v[164:165], v[222:223]
	v_pk_fma_f32 v[78:79], v[78:79], v[172:173], v[180:181]
	v_pk_fma_f32 v[78:79], v[94:95], v[164:165], v[78:79]
	v_pk_fma_f32 v[78:79], v[110:111], v[156:157], v[78:79]
	v_pk_fma_f32 v[94:95], v[94:95], v[172:173], v[180:181]
	v_pk_fma_f32 v[94:95], v[110:111], v[164:165], v[94:95]
	v_pk_fma_f32 v[94:95], v[126:127], v[156:157], v[94:95]
	v_mov_b32_e32 v126, v220
	v_mov_b32_e32 v127, v221
	v_mov_b32_e32 v110, v222
	v_mov_b32_e32 v111, v223
	v_pk_fma_f32 v[220:221], v[128:129], v[174:175], v[182:183]
	v_pk_fma_f32 v[222:223], v[112:113], v[174:175], v[182:183]
	v_fmac_f32_dpp v220, v80, v166 row_shr:1 row_mask:0xf bank_mask:0xf
	v_fmac_f32_dpp v220, v96, v158 row_shr:1 row_mask:0xf bank_mask:0xf
	v_fmac_f32_dpp v222, v80, v158 row_shr:1 row_mask:0xf bank_mask:0xf
	v_fmac_f32_dpp v221, v81, v167 row_shr:1 row_mask:0xf bank_mask:0xf
	v_fmac_f32_dpp v221, v97, v159 row_shr:1 row_mask:0xf bank_mask:0xf
	v_fmac_f32_dpp v223, v81, v159 row_shr:1 row_mask:0xf bank_mask:0xf
	v_pk_fma_f32 v[222:223], v[128:129], v[166:167], v[222:223]
	v_pk_fma_f32 v[80:81], v[80:81], v[174:175], v[182:183]
	v_pk_fma_f32 v[80:81], v[96:97], v[166:167], v[80:81]
	v_pk_fma_f32 v[80:81], v[112:113], v[158:159], v[80:81]
	v_pk_fma_f32 v[96:97], v[96:97], v[174:175], v[182:183]
	v_pk_fma_f32 v[96:97], v[112:113], v[166:167], v[96:97]
	v_pk_fma_f32 v[96:97], v[128:129], v[158:159], v[96:97]
	v_mov_b32_e32 v128, v220
	v_mov_b32_e32 v129, v221
	v_mov_b32_e32 v112, v222
	v_mov_b32_e32 v113, v223
	v_pk_fma_f32 v[220:221], v[122:123], v[200:201], v[208:209]
	v_pk_fma_f32 v[222:223], v[106:107], v[200:201], v[208:209]
	v_fmac_f32_dpp v220, v74, v192 row_shr:1 row_mask:0xf bank_mask:0xf
	v_fmac_f32_dpp v220, v90, v184 row_shr:1 row_mask:0xf bank_mask:0xf
	v_fmac_f32_dpp v222, v74, v184 row_shr:1 row_mask:0xf bank_mask:0xf
	v_fmac_f32_dpp v221, v75, v193 row_shr:1 row_mask:0xf bank_mask:0xf
	v_fmac_f32_dpp v221, v91, v185 row_shr:1 row_mask:0xf bank_mask:0xf
	v_fmac_f32_dpp v223, v75, v185 row_shr:1 row_mask:0xf bank_mask:0xf
	v_pk_fma_f32 v[222:223], v[122:123], v[192:193], v[222:223]
	v_pk_fma_f32 v[74:75], v[74:75], v[200:201], v[208:209]
	v_pk_fma_f32 v[74:75], v[90:91], v[192:193], v[74:75]
	v_pk_fma_f32 v[74:75], v[106:107], v[184:185], v[74:75]
	v_pk_fma_f32 v[90:91], v[90:91], v[200:201], v[208:209]
	v_pk_fma_f32 v[90:91], v[106:107], v[192:193], v[90:91]
	v_pk_fma_f32 v[90:91], v[122:123], v[184:185], v[90:91]
	v_mov_b32_e32 v122, v220
	v_mov_b32_e32 v123, v221
	v_mov_b32_e32 v106, v222
	v_mov_b32_e32 v107, v223
	v_pk_fma_f32 v[220:221], v[124:125], v[202:203], v[210:211]
	v_pk_fma_f32 v[222:223], v[108:109], v[202:203], v[210:211]
	v_fmac_f32_dpp v220, v76, v194 row_shr:1 row_mask:0xf bank_mask:0xf
	v_fmac_f32_dpp v220, v92, v186 row_shr:1 row_mask:0xf bank_mask:0xf
	v_fmac_f32_dpp v222, v76, v186 row_shr:1 row_mask:0xf bank_mask:0xf
	v_fmac_f32_dpp v221, v77, v195 row_shr:1 row_mask:0xf bank_mask:0xf
	v_fmac_f32_dpp v221, v93, v187 row_shr:1 row_mask:0xf bank_mask:0xf
	v_fmac_f32_dpp v223, v77, v187 row_shr:1 row_mask:0xf bank_mask:0xf
	v_pk_fma_f32 v[222:223], v[124:125], v[194:195], v[222:223]
	v_pk_fma_f32 v[76:77], v[76:77], v[202:203], v[210:211]
	v_pk_fma_f32 v[76:77], v[92:93], v[194:195], v[76:77]
	v_pk_fma_f32 v[76:77], v[108:109], v[186:187], v[76:77]
	v_pk_fma_f32 v[92:93], v[92:93], v[202:203], v[210:211]
	v_pk_fma_f32 v[92:93], v[108:109], v[194:195], v[92:93]
	v_pk_fma_f32 v[92:93], v[124:125], v[186:187], v[92:93]
	v_mov_b32_e32 v124, v220
	v_mov_b32_e32 v125, v221
	v_mov_b32_e32 v108, v222
	v_mov_b32_e32 v109, v223
	v_pk_fma_f32 v[220:221], v[118:119], v[204:205], v[212:213]
	v_pk_fma_f32 v[222:223], v[102:103], v[204:205], v[212:213]
	v_fmac_f32_dpp v220, v70, v196 row_shr:1 row_mask:0xf bank_mask:0xf
	v_fmac_f32_dpp v220, v86, v188 row_shr:1 row_mask:0xf bank_mask:0xf
	v_fmac_f32_dpp v222, v70, v188 row_shr:1 row_mask:0xf bank_mask:0xf
	v_fmac_f32_dpp v221, v71, v197 row_shr:1 row_mask:0xf bank_mask:0xf
	v_fmac_f32_dpp v221, v87, v189 row_shr:1 row_mask:0xf bank_mask:0xf
	v_fmac_f32_dpp v223, v71, v189 row_shr:1 row_mask:0xf bank_mask:0xf
	v_pk_fma_f32 v[222:223], v[118:119], v[196:197], v[222:223]
	v_pk_fma_f32 v[70:71], v[70:71], v[204:205], v[212:213]
	v_pk_fma_f32 v[70:71], v[86:87], v[196:197], v[70:71]
	v_pk_fma_f32 v[70:71], v[102:103], v[188:189], v[70:71]
	v_pk_fma_f32 v[86:87], v[86:87], v[204:205], v[212:213]
	v_pk_fma_f32 v[86:87], v[102:103], v[196:197], v[86:87]
	v_pk_fma_f32 v[86:87], v[118:119], v[188:189], v[86:87]
	v_mov_b32_e32 v118, v220
	v_mov_b32_e32 v119, v221
	v_mov_b32_e32 v102, v222
	v_mov_b32_e32 v103, v223
	v_pk_fma_f32 v[220:221], v[120:121], v[206:207], v[214:215]
	v_pk_fma_f32 v[222:223], v[104:105], v[206:207], v[214:215]
	v_fmac_f32_dpp v220, v72, v198 row_shr:1 row_mask:0xf bank_mask:0xf
	v_fmac_f32_dpp v220, v88, v190 row_shr:1 row_mask:0xf bank_mask:0xf
	v_fmac_f32_dpp v222, v72, v190 row_shr:1 row_mask:0xf bank_mask:0xf
	v_fmac_f32_dpp v221, v73, v199 row_shr:1 row_mask:0xf bank_mask:0xf
	v_fmac_f32_dpp v221, v89, v191 row_shr:1 row_mask:0xf bank_mask:0xf
	v_fmac_f32_dpp v223, v73, v191 row_shr:1 row_mask:0xf bank_mask:0xf
	v_pk_fma_f32 v[222:223], v[120:121], v[198:199], v[222:223]
	v_pk_fma_f32 v[72:73], v[72:73], v[206:207], v[214:215]
	v_pk_fma_f32 v[72:73], v[88:89], v[198:199], v[72:73]
	v_pk_fma_f32 v[72:73], v[104:105], v[190:191], v[72:73]
	v_pk_fma_f32 v[88:89], v[88:89], v[206:207], v[214:215]
	v_pk_fma_f32 v[88:89], v[104:105], v[198:199], v[88:89]
	v_pk_fma_f32 v[88:89], v[120:121], v[190:191], v[88:89]
	v_mov_b32_e32 v120, v220
	v_mov_b32_e32 v121, v221
	v_mov_b32_e32 v104, v222
	v_mov_b32_e32 v105, v223
	v_pk_mul_f32 v[220:221], v[130:131], s[30:31]
	v_exp_f32_e32 v220, v220
	v_exp_f32_e32 v221, v221
	s_nop 0
	v_pk_add_f32 v[220:221], v[220:221], 1.0 op_sel_hi:[1,0]
	v_rcp_f32_e32 v220, v220
	v_rcp_f32_e32 v221, v221
	s_nop 0
	v_pk_mul_f32 v[220:221], v[220:221], v[130:131]
	v_pk_mul_f32 v[220:221], v[220:221], v[122:123]
	v_cvt_pk_bf16_f32 v224, v220, v221
	v_pk_mul_f32 v[220:221], v[132:133], s[30:31]
	v_exp_f32_e32 v220, v220
	v_exp_f32_e32 v221, v221
	s_nop 0
	v_pk_add_f32 v[220:221], v[220:221], 1.0 op_sel_hi:[1,0]
	v_rcp_f32_e32 v220, v220
	v_rcp_f32_e32 v221, v221
	s_nop 0
	v_pk_mul_f32 v[220:221], v[220:221], v[132:133]
	v_pk_mul_f32 v[220:221], v[220:221], v[124:125]
	v_cvt_pk_bf16_f32 v225, v220, v221
	v_pk_mul_f32 v[220:221], v[126:127], s[30:31]
	v_exp_f32_e32 v220, v220
	v_exp_f32_e32 v221, v221
	s_nop 0
	v_pk_add_f32 v[220:221], v[220:221], 1.0 op_sel_hi:[1,0]
	v_rcp_f32_e32 v220, v220
	v_rcp_f32_e32 v221, v221
	s_nop 0
	v_pk_mul_f32 v[220:221], v[220:221], v[126:127]
	v_pk_mul_f32 v[220:221], v[220:221], v[118:119]
	v_cvt_pk_bf16_f32 v226, v220, v221
	v_pk_mul_f32 v[220:221], v[128:129], s[30:31]
	v_exp_f32_e32 v220, v220
	v_exp_f32_e32 v221, v221
	s_nop 0
	v_pk_add_f32 v[220:221], v[220:221], 1.0 op_sel_hi:[1,0]
	v_rcp_f32_e32 v220, v220
	v_rcp_f32_e32 v221, v221
	s_nop 0
	v_pk_mul_f32 v[220:221], v[220:221], v[128:129]
	v_pk_mul_f32 v[220:221], v[220:221], v[120:121]
	v_cvt_pk_bf16_f32 v227, v220, v221
	ds_bpermute_b32 v242, v145, v224
	ds_bpermute_b32 v243, v145, v225
	ds_bpermute_b32 v244, v145, v226
	ds_bpermute_b32 v245, v145, v227
	s_mov_b32 s4, 0x0
	s_mov_b32 s5, 0
	v_lshl_add_u64 v[146:147], v[216:217], 0, s[4:5]
	s_waitcnt lgkmcnt(0)
	global_store_dwordx4 v[146:147], v[242:245], off
	v_pk_mul_f32 v[220:221], v[114:115], s[30:31]
	v_exp_f32_e32 v220, v220
	v_exp_f32_e32 v221, v221
	s_nop 0
	v_pk_add_f32 v[220:221], v[220:221], 1.0 op_sel_hi:[1,0]
	v_rcp_f32_e32 v220, v220
	v_rcp_f32_e32 v221, v221
	s_nop 0
	v_pk_mul_f32 v[220:221], v[220:221], v[114:115]
	v_pk_mul_f32 v[220:221], v[220:221], v[106:107]
	v_cvt_pk_bf16_f32 v224, v220, v221
	v_pk_mul_f32 v[220:221], v[116:117], s[30:31]
	v_exp_f32_e32 v220, v220
	v_exp_f32_e32 v221, v221
	s_nop 0
	v_pk_add_f32 v[220:221], v[220:221], 1.0 op_sel_hi:[1,0]
	v_rcp_f32_e32 v220, v220
	v_rcp_f32_e32 v221, v221
	s_nop 0
	v_pk_mul_f32 v[220:221], v[220:221], v[116:117]
	v_pk_mul_f32 v[220:221], v[220:221], v[108:109]
	v_cvt_pk_bf16_f32 v225, v220, v221
	v_pk_mul_f32 v[220:221], v[110:111], s[30:31]
	v_exp_f32_e32 v220, v220
	v_exp_f32_e32 v221, v221
	s_nop 0
	v_pk_add_f32 v[220:221], v[220:221], 1.0 op_sel_hi:[1,0]
	v_rcp_f32_e32 v220, v220
	v_rcp_f32_e32 v221, v221
	s_nop 0
	v_pk_mul_f32 v[220:221], v[220:221], v[110:111]
	v_pk_mul_f32 v[220:221], v[220:221], v[102:103]
	v_cvt_pk_bf16_f32 v226, v220, v221
	v_pk_mul_f32 v[220:221], v[112:113], s[30:31]
	v_exp_f32_e32 v220, v220
	v_exp_f32_e32 v221, v221
	s_nop 0
	v_pk_add_f32 v[220:221], v[220:221], 1.0 op_sel_hi:[1,0]
	v_rcp_f32_e32 v220, v220
	v_rcp_f32_e32 v221, v221
	s_nop 0
	v_pk_mul_f32 v[220:221], v[220:221], v[112:113]
	v_pk_mul_f32 v[220:221], v[220:221], v[104:105]
	v_cvt_pk_bf16_f32 v227, v220, v221
	ds_bpermute_b32 v246, v145, v224
	ds_bpermute_b32 v247, v145, v225
	ds_bpermute_b32 v248, v145, v226
	ds_bpermute_b32 v249, v145, v227
	s_mov_b32 s4, 0x1600
	s_mov_b32 s5, 0
	v_lshl_add_u64 v[146:147], v[216:217], 0, s[4:5]
	s_waitcnt lgkmcnt(0)
	global_store_dwordx4 v[146:147], v[246:249], off
	v_pk_mul_f32 v[220:221], v[98:99], s[30:31]
	v_exp_f32_e32 v220, v220
	v_exp_f32_e32 v221, v221
	s_nop 0
	v_pk_add_f32 v[220:221], v[220:221], 1.0 op_sel_hi:[1,0]
	v_rcp_f32_e32 v220, v220
	v_rcp_f32_e32 v221, v221
	s_nop 0
	v_pk_mul_f32 v[220:221], v[220:221], v[98:99]
	v_pk_mul_f32 v[220:221], v[220:221], v[90:91]
	v_cvt_pk_bf16_f32 v224, v220, v221
	v_pk_mul_f32 v[220:221], v[100:101], s[30:31]
	v_exp_f32_e32 v220, v220
	v_exp_f32_e32 v221, v221
	s_nop 0
	v_pk_add_f32 v[220:221], v[220:221], 1.0 op_sel_hi:[1,0]
	v_rcp_f32_e32 v220, v220
	v_rcp_f32_e32 v221, v221
	s_nop 0
	v_pk_mul_f32 v[220:221], v[220:221], v[100:101]
	v_pk_mul_f32 v[220:221], v[220:221], v[92:93]
	v_cvt_pk_bf16_f32 v225, v220, v221
	v_pk_mul_f32 v[220:221], v[94:95], s[30:31]
	v_exp_f32_e32 v220, v220
	v_exp_f32_e32 v221, v221
	s_nop 0
	v_pk_add_f32 v[220:221], v[220:221], 1.0 op_sel_hi:[1,0]
	v_rcp_f32_e32 v220, v220
	v_rcp_f32_e32 v221, v221
	s_nop 0
	v_pk_mul_f32 v[220:221], v[220:221], v[94:95]
	v_pk_mul_f32 v[220:221], v[220:221], v[86:87]
	v_cvt_pk_bf16_f32 v226, v220, v221
	v_pk_mul_f32 v[220:221], v[96:97], s[30:31]
	v_exp_f32_e32 v220, v220
	v_exp_f32_e32 v221, v221
	s_nop 0
	v_pk_add_f32 v[220:221], v[220:221], 1.0 op_sel_hi:[1,0]
	v_rcp_f32_e32 v220, v220
	v_rcp_f32_e32 v221, v221
	s_nop 0
	v_pk_mul_f32 v[220:221], v[220:221], v[96:97]
	v_pk_mul_f32 v[220:221], v[220:221], v[88:89]
	v_cvt_pk_bf16_f32 v227, v220, v221
	ds_bpermute_b32 v242, v145, v224
	ds_bpermute_b32 v243, v145, v225
	ds_bpermute_b32 v244, v145, v226
	ds_bpermute_b32 v245, v145, v227
	s_mov_b32 s4, 0x2c00
	s_mov_b32 s5, 0
	v_lshl_add_u64 v[146:147], v[216:217], 0, s[4:5]
	s_waitcnt lgkmcnt(0)
	global_store_dwordx4 v[146:147], v[242:245], off
	v_pk_mul_f32 v[220:221], v[82:83], s[30:31]
	v_exp_f32_e32 v220, v220
	v_exp_f32_e32 v221, v221
	s_nop 0
	v_pk_add_f32 v[220:221], v[220:221], 1.0 op_sel_hi:[1,0]
	v_rcp_f32_e32 v220, v220
	v_rcp_f32_e32 v221, v221
	s_nop 0
	v_pk_mul_f32 v[220:221], v[220:221], v[82:83]
	v_pk_mul_f32 v[220:221], v[220:221], v[74:75]
	v_cvt_pk_bf16_f32 v224, v220, v221
	v_pk_mul_f32 v[220:221], v[84:85], s[30:31]
	v_exp_f32_e32 v220, v220
	v_exp_f32_e32 v221, v221
	s_nop 0
	v_pk_add_f32 v[220:221], v[220:221], 1.0 op_sel_hi:[1,0]
	v_rcp_f32_e32 v220, v220
	v_rcp_f32_e32 v221, v221
	s_nop 0
	v_pk_mul_f32 v[220:221], v[220:221], v[84:85]
	v_pk_mul_f32 v[220:221], v[220:221], v[76:77]
	v_cvt_pk_bf16_f32 v225, v220, v221
	v_pk_mul_f32 v[220:221], v[78:79], s[30:31]
	v_exp_f32_e32 v220, v220
	v_exp_f32_e32 v221, v221
	s_nop 0
	v_pk_add_f32 v[220:221], v[220:221], 1.0 op_sel_hi:[1,0]
	v_rcp_f32_e32 v220, v220
	v_rcp_f32_e32 v221, v221
	s_nop 0
	v_pk_mul_f32 v[220:221], v[220:221], v[78:79]
	v_pk_mul_f32 v[220:221], v[220:221], v[70:71]
	v_cvt_pk_bf16_f32 v226, v220, v221
	v_pk_mul_f32 v[220:221], v[80:81], s[30:31]
	v_exp_f32_e32 v220, v220
	v_exp_f32_e32 v221, v221
	s_nop 0
	v_pk_add_f32 v[220:221], v[220:221], 1.0 op_sel_hi:[1,0]
	v_rcp_f32_e32 v220, v220
	v_rcp_f32_e32 v221, v221
	s_nop 0
	v_pk_mul_f32 v[220:221], v[220:221], v[80:81]
	v_pk_mul_f32 v[220:221], v[220:221], v[72:73]
	v_cvt_pk_bf16_f32 v227, v220, v221
	ds_bpermute_b32 v246, v145, v224
	ds_bpermute_b32 v247, v145, v225
	ds_bpermute_b32 v248, v145, v226
	ds_bpermute_b32 v249, v145, v227
	s_mov_b32 s4, 0x4200
	s_mov_b32 s5, 0
	v_lshl_add_u64 v[146:147], v[216:217], 0, s[4:5]
	s_waitcnt lgkmcnt(0)
	global_store_dwordx4 v[146:147], v[246:249], off
	v_pk_fma_f32 v[220:221], v[66:67], v[168:169], v[176:177]
	v_pk_fma_f32 v[222:223], v[50:51], v[168:169], v[176:177]
	v_fmac_f32_dpp v220, v18, v160 row_shr:1 row_mask:0xf bank_mask:0xf
	v_fmac_f32_dpp v220, v34, v152 row_shr:1 row_mask:0xf bank_mask:0xf
	v_fmac_f32_dpp v222, v18, v152 row_shr:1 row_mask:0xf bank_mask:0xf
	v_fmac_f32_dpp v221, v19, v161 row_shr:1 row_mask:0xf bank_mask:0xf
	v_fmac_f32_dpp v221, v35, v153 row_shr:1 row_mask:0xf bank_mask:0xf
	v_fmac_f32_dpp v223, v19, v153 row_shr:1 row_mask:0xf bank_mask:0xf
	v_pk_fma_f32 v[222:223], v[66:67], v[160:161], v[222:223]
	v_pk_fma_f32 v[18:19], v[18:19], v[168:169], v[176:177]
	v_pk_fma_f32 v[18:19], v[34:35], v[160:161], v[18:19]
	v_pk_fma_f32 v[18:19], v[50:51], v[152:153], v[18:19]
	v_pk_fma_f32 v[34:35], v[34:35], v[168:169], v[176:177]
	v_pk_fma_f32 v[34:35], v[50:51], v[160:161], v[34:35]
	v_pk_fma_f32 v[34:35], v[66:67], v[152:153], v[34:35]
	v_mov_b32_e32 v66, v220
	v_mov_b32_e32 v67, v221
	v_mov_b32_e32 v50, v222
	v_mov_b32_e32 v51, v223
	v_pk_fma_f32 v[220:221], v[68:69], v[170:171], v[178:179]
	v_pk_fma_f32 v[222:223], v[52:53], v[170:171], v[178:179]
	v_fmac_f32_dpp v220, v20, v162 row_shr:1 row_mask:0xf bank_mask:0xf
	v_fmac_f32_dpp v220, v36, v154 row_shr:1 row_mask:0xf bank_mask:0xf
	v_fmac_f32_dpp v222, v20, v154 row_shr:1 row_mask:0xf bank_mask:0xf
	v_fmac_f32_dpp v221, v21, v163 row_shr:1 row_mask:0xf bank_mask:0xf
	v_fmac_f32_dpp v221, v37, v155 row_shr:1 row_mask:0xf bank_mask:0xf
	v_fmac_f32_dpp v223, v21, v155 row_shr:1 row_mask:0xf bank_mask:0xf
	v_pk_fma_f32 v[222:223], v[68:69], v[162:163], v[222:223]
	v_pk_fma_f32 v[20:21], v[20:21], v[170:171], v[178:179]
	v_pk_fma_f32 v[20:21], v[36:37], v[162:163], v[20:21]
	v_pk_fma_f32 v[20:21], v[52:53], v[154:155], v[20:21]
	v_pk_fma_f32 v[36:37], v[36:37], v[170:171], v[178:179]
	v_pk_fma_f32 v[36:37], v[52:53], v[162:163], v[36:37]
	v_pk_fma_f32 v[36:37], v[68:69], v[154:155], v[36:37]
	v_mov_b32_e32 v68, v220
	v_mov_b32_e32 v69, v221
	v_mov_b32_e32 v52, v222
	v_mov_b32_e32 v53, v223
	v_pk_fma_f32 v[220:221], v[62:63], v[172:173], v[180:181]
	v_pk_fma_f32 v[222:223], v[46:47], v[172:173], v[180:181]
	v_fmac_f32_dpp v220, v14, v164 row_shr:1 row_mask:0xf bank_mask:0xf
	v_fmac_f32_dpp v220, v30, v156 row_shr:1 row_mask:0xf bank_mask:0xf
	v_fmac_f32_dpp v222, v14, v156 row_shr:1 row_mask:0xf bank_mask:0xf
	v_fmac_f32_dpp v221, v15, v165 row_shr:1 row_mask:0xf bank_mask:0xf
	v_fmac_f32_dpp v221, v31, v157 row_shr:1 row_mask:0xf bank_mask:0xf
	v_fmac_f32_dpp v223, v15, v157 row_shr:1 row_mask:0xf bank_mask:0xf
	v_pk_fma_f32 v[222:223], v[62:63], v[164:165], v[222:223]
	v_pk_fma_f32 v[14:15], v[14:15], v[172:173], v[180:181]
	v_pk_fma_f32 v[14:15], v[30:31], v[164:165], v[14:15]
	v_pk_fma_f32 v[14:15], v[46:47], v[156:157], v[14:15]
	v_pk_fma_f32 v[30:31], v[30:31], v[172:173], v[180:181]
	v_pk_fma_f32 v[30:31], v[46:47], v[164:165], v[30:31]
	v_pk_fma_f32 v[30:31], v[62:63], v[156:157], v[30:31]
	v_mov_b32_e32 v62, v220
	v_mov_b32_e32 v63, v221
	v_mov_b32_e32 v46, v222
	v_mov_b32_e32 v47, v223
	v_pk_fma_f32 v[220:221], v[64:65], v[174:175], v[182:183]
	v_pk_fma_f32 v[222:223], v[48:49], v[174:175], v[182:183]
	v_fmac_f32_dpp v220, v16, v166 row_shr:1 row_mask:0xf bank_mask:0xf
	v_fmac_f32_dpp v220, v32, v158 row_shr:1 row_mask:0xf bank_mask:0xf
	v_fmac_f32_dpp v222, v16, v158 row_shr:1 row_mask:0xf bank_mask:0xf
	v_fmac_f32_dpp v221, v17, v167 row_shr:1 row_mask:0xf bank_mask:0xf
	v_fmac_f32_dpp v221, v33, v159 row_shr:1 row_mask:0xf bank_mask:0xf
	v_fmac_f32_dpp v223, v17, v159 row_shr:1 row_mask:0xf bank_mask:0xf
	v_pk_fma_f32 v[222:223], v[64:65], v[166:167], v[222:223]
	v_pk_fma_f32 v[16:17], v[16:17], v[174:175], v[182:183]
	v_pk_fma_f32 v[16:17], v[32:33], v[166:167], v[16:17]
	v_pk_fma_f32 v[16:17], v[48:49], v[158:159], v[16:17]
	v_pk_fma_f32 v[32:33], v[32:33], v[174:175], v[182:183]
	v_pk_fma_f32 v[32:33], v[48:49], v[166:167], v[32:33]
	v_pk_fma_f32 v[32:33], v[64:65], v[158:159], v[32:33]
	v_mov_b32_e32 v64, v220
	v_mov_b32_e32 v65, v221
	v_mov_b32_e32 v48, v222
	v_mov_b32_e32 v49, v223
	v_pk_fma_f32 v[220:221], v[58:59], v[200:201], v[208:209]
	v_pk_fma_f32 v[222:223], v[42:43], v[200:201], v[208:209]
	v_fmac_f32_dpp v220, v10, v192 row_shr:1 row_mask:0xf bank_mask:0xf
	v_fmac_f32_dpp v220, v26, v184 row_shr:1 row_mask:0xf bank_mask:0xf
	v_fmac_f32_dpp v222, v10, v184 row_shr:1 row_mask:0xf bank_mask:0xf
	v_fmac_f32_dpp v221, v11, v193 row_shr:1 row_mask:0xf bank_mask:0xf
	v_fmac_f32_dpp v221, v27, v185 row_shr:1 row_mask:0xf bank_mask:0xf
	v_fmac_f32_dpp v223, v11, v185 row_shr:1 row_mask:0xf bank_mask:0xf
	v_pk_fma_f32 v[222:223], v[58:59], v[192:193], v[222:223]
	v_pk_fma_f32 v[10:11], v[10:11], v[200:201], v[208:209]
	v_pk_fma_f32 v[10:11], v[26:27], v[192:193], v[10:11]
	v_pk_fma_f32 v[10:11], v[42:43], v[184:185], v[10:11]
	v_pk_fma_f32 v[26:27], v[26:27], v[200:201], v[208:209]
	v_pk_fma_f32 v[26:27], v[42:43], v[192:193], v[26:27]
	v_pk_fma_f32 v[26:27], v[58:59], v[184:185], v[26:27]
	v_mov_b32_e32 v58, v220
	v_mov_b32_e32 v59, v221
	v_mov_b32_e32 v42, v222
	v_mov_b32_e32 v43, v223
	v_pk_fma_f32 v[220:221], v[60:61], v[202:203], v[210:211]
	v_pk_fma_f32 v[222:223], v[44:45], v[202:203], v[210:211]
	v_fmac_f32_dpp v220, v12, v194 row_shr:1 row_mask:0xf bank_mask:0xf
	v_fmac_f32_dpp v220, v28, v186 row_shr:1 row_mask:0xf bank_mask:0xf
	v_fmac_f32_dpp v222, v12, v186 row_shr:1 row_mask:0xf bank_mask:0xf
	v_fmac_f32_dpp v221, v13, v195 row_shr:1 row_mask:0xf bank_mask:0xf
	v_fmac_f32_dpp v221, v29, v187 row_shr:1 row_mask:0xf bank_mask:0xf
	v_fmac_f32_dpp v223, v13, v187 row_shr:1 row_mask:0xf bank_mask:0xf
	v_pk_fma_f32 v[222:223], v[60:61], v[194:195], v[222:223]
	v_pk_fma_f32 v[12:13], v[12:13], v[202:203], v[210:211]
	v_pk_fma_f32 v[12:13], v[28:29], v[194:195], v[12:13]
	v_pk_fma_f32 v[12:13], v[44:45], v[186:187], v[12:13]
	v_pk_fma_f32 v[28:29], v[28:29], v[202:203], v[210:211]
	v_pk_fma_f32 v[28:29], v[44:45], v[194:195], v[28:29]
	v_pk_fma_f32 v[28:29], v[60:61], v[186:187], v[28:29]
	v_mov_b32_e32 v60, v220
	v_mov_b32_e32 v61, v221
	v_mov_b32_e32 v44, v222
	v_mov_b32_e32 v45, v223
	v_pk_fma_f32 v[220:221], v[54:55], v[204:205], v[212:213]
	v_pk_fma_f32 v[222:223], v[38:39], v[204:205], v[212:213]
	v_fmac_f32_dpp v220, v6, v196 row_shr:1 row_mask:0xf bank_mask:0xf
	v_fmac_f32_dpp v220, v22, v188 row_shr:1 row_mask:0xf bank_mask:0xf
	v_fmac_f32_dpp v222, v6, v188 row_shr:1 row_mask:0xf bank_mask:0xf
	v_fmac_f32_dpp v221, v7, v197 row_shr:1 row_mask:0xf bank_mask:0xf
	v_fmac_f32_dpp v221, v23, v189 row_shr:1 row_mask:0xf bank_mask:0xf
	v_fmac_f32_dpp v223, v7, v189 row_shr:1 row_mask:0xf bank_mask:0xf
	v_pk_fma_f32 v[222:223], v[54:55], v[196:197], v[222:223]
	v_pk_fma_f32 v[6:7], v[6:7], v[204:205], v[212:213]
	v_pk_fma_f32 v[6:7], v[22:23], v[196:197], v[6:7]
	v_pk_fma_f32 v[6:7], v[38:39], v[188:189], v[6:7]
	v_pk_fma_f32 v[22:23], v[22:23], v[204:205], v[212:213]
	v_pk_fma_f32 v[22:23], v[38:39], v[196:197], v[22:23]
	v_pk_fma_f32 v[22:23], v[54:55], v[188:189], v[22:23]
	v_mov_b32_e32 v54, v220
	v_mov_b32_e32 v55, v221
	v_mov_b32_e32 v38, v222
	v_mov_b32_e32 v39, v223
	v_pk_fma_f32 v[220:221], v[56:57], v[206:207], v[214:215]
	v_pk_fma_f32 v[222:223], v[40:41], v[206:207], v[214:215]
	v_fmac_f32_dpp v220, v8, v198 row_shr:1 row_mask:0xf bank_mask:0xf
	v_fmac_f32_dpp v220, v24, v190 row_shr:1 row_mask:0xf bank_mask:0xf
	v_fmac_f32_dpp v222, v8, v190 row_shr:1 row_mask:0xf bank_mask:0xf
	v_fmac_f32_dpp v221, v9, v199 row_shr:1 row_mask:0xf bank_mask:0xf
	v_fmac_f32_dpp v221, v25, v191 row_shr:1 row_mask:0xf bank_mask:0xf
	v_fmac_f32_dpp v223, v9, v191 row_shr:1 row_mask:0xf bank_mask:0xf
	v_pk_fma_f32 v[222:223], v[56:57], v[198:199], v[222:223]
	v_pk_fma_f32 v[8:9], v[8:9], v[206:207], v[214:215]
	v_pk_fma_f32 v[8:9], v[24:25], v[198:199], v[8:9]
	v_pk_fma_f32 v[8:9], v[40:41], v[190:191], v[8:9]
	v_pk_fma_f32 v[24:25], v[24:25], v[206:207], v[214:215]
	v_pk_fma_f32 v[24:25], v[40:41], v[198:199], v[24:25]
	v_pk_fma_f32 v[24:25], v[56:57], v[190:191], v[24:25]
	v_mov_b32_e32 v56, v220
	v_mov_b32_e32 v57, v221
	v_mov_b32_e32 v40, v222
	v_mov_b32_e32 v41, v223
	v_pk_mul_f32 v[220:221], v[66:67], s[30:31]
	v_exp_f32_e32 v220, v220
	v_exp_f32_e32 v221, v221
	s_nop 0
	v_pk_add_f32 v[220:221], v[220:221], 1.0 op_sel_hi:[1,0]
	v_rcp_f32_e32 v220, v220
	v_rcp_f32_e32 v221, v221
	s_nop 0
	v_pk_mul_f32 v[220:221], v[220:221], v[66:67]
	v_pk_mul_f32 v[220:221], v[220:221], v[58:59]
	v_cvt_pk_bf16_f32 v224, v220, v221
	v_pk_mul_f32 v[220:221], v[68:69], s[30:31]
	v_exp_f32_e32 v220, v220
	v_exp_f32_e32 v221, v221
	s_nop 0
	v_pk_add_f32 v[220:221], v[220:221], 1.0 op_sel_hi:[1,0]
	v_rcp_f32_e32 v220, v220
	v_rcp_f32_e32 v221, v221
	s_nop 0
	v_pk_mul_f32 v[220:221], v[220:221], v[68:69]
	v_pk_mul_f32 v[220:221], v[220:221], v[60:61]
	v_cvt_pk_bf16_f32 v225, v220, v221
	v_pk_mul_f32 v[220:221], v[62:63], s[30:31]
	v_exp_f32_e32 v220, v220
	v_exp_f32_e32 v221, v221
	s_nop 0
	v_pk_add_f32 v[220:221], v[220:221], 1.0 op_sel_hi:[1,0]
	v_rcp_f32_e32 v220, v220
	v_rcp_f32_e32 v221, v221
	s_nop 0
	v_pk_mul_f32 v[220:221], v[220:221], v[62:63]
	v_pk_mul_f32 v[220:221], v[220:221], v[54:55]
	v_cvt_pk_bf16_f32 v226, v220, v221
	v_pk_mul_f32 v[220:221], v[64:65], s[30:31]
	v_exp_f32_e32 v220, v220
	v_exp_f32_e32 v221, v221
	s_nop 0
	v_pk_add_f32 v[220:221], v[220:221], 1.0 op_sel_hi:[1,0]
	v_rcp_f32_e32 v220, v220
	v_rcp_f32_e32 v221, v221
	s_nop 0
	v_pk_mul_f32 v[220:221], v[220:221], v[64:65]
	v_pk_mul_f32 v[220:221], v[220:221], v[56:57]
	v_cvt_pk_bf16_f32 v227, v220, v221
	ds_bpermute_b32 v242, v145, v224
	ds_bpermute_b32 v243, v145, v225
	ds_bpermute_b32 v244, v145, v226
	ds_bpermute_b32 v245, v145, v227
	s_mov_b32 s4, 0xb0000
	s_mov_b32 s5, 0
	v_lshl_add_u64 v[146:147], v[216:217], 0, s[4:5]
	s_waitcnt lgkmcnt(0)
	global_store_dwordx4 v[146:147], v[242:245], off
	v_pk_mul_f32 v[220:221], v[50:51], s[30:31]
	v_exp_f32_e32 v220, v220
	v_exp_f32_e32 v221, v221
	s_nop 0
	v_pk_add_f32 v[220:221], v[220:221], 1.0 op_sel_hi:[1,0]
	v_rcp_f32_e32 v220, v220
	v_rcp_f32_e32 v221, v221
	s_nop 0
	v_pk_mul_f32 v[220:221], v[220:221], v[50:51]
	v_pk_mul_f32 v[220:221], v[220:221], v[42:43]
	v_cvt_pk_bf16_f32 v224, v220, v221
	v_pk_mul_f32 v[220:221], v[52:53], s[30:31]
	v_exp_f32_e32 v220, v220
	v_exp_f32_e32 v221, v221
	s_nop 0
	v_pk_add_f32 v[220:221], v[220:221], 1.0 op_sel_hi:[1,0]
	v_rcp_f32_e32 v220, v220
	v_rcp_f32_e32 v221, v221
	s_nop 0
	v_pk_mul_f32 v[220:221], v[220:221], v[52:53]
	v_pk_mul_f32 v[220:221], v[220:221], v[44:45]
	v_cvt_pk_bf16_f32 v225, v220, v221
	v_pk_mul_f32 v[220:221], v[46:47], s[30:31]
	v_exp_f32_e32 v220, v220
	v_exp_f32_e32 v221, v221
	s_nop 0
	v_pk_add_f32 v[220:221], v[220:221], 1.0 op_sel_hi:[1,0]
	v_rcp_f32_e32 v220, v220
	v_rcp_f32_e32 v221, v221
	s_nop 0
	v_pk_mul_f32 v[220:221], v[220:221], v[46:47]
	v_pk_mul_f32 v[220:221], v[220:221], v[38:39]
	v_cvt_pk_bf16_f32 v226, v220, v221
	v_pk_mul_f32 v[220:221], v[48:49], s[30:31]
	v_exp_f32_e32 v220, v220
	v_exp_f32_e32 v221, v221
	s_nop 0
	v_pk_add_f32 v[220:221], v[220:221], 1.0 op_sel_hi:[1,0]
	v_rcp_f32_e32 v220, v220
	v_rcp_f32_e32 v221, v221
	s_nop 0
	v_pk_mul_f32 v[220:221], v[220:221], v[48:49]
	v_pk_mul_f32 v[220:221], v[220:221], v[40:41]
	v_cvt_pk_bf16_f32 v227, v220, v221
	ds_bpermute_b32 v246, v145, v224
	ds_bpermute_b32 v247, v145, v225
	ds_bpermute_b32 v248, v145, v226
	ds_bpermute_b32 v249, v145, v227
	s_mov_b32 s4, 0xb1600
	s_mov_b32 s5, 0
	v_lshl_add_u64 v[146:147], v[216:217], 0, s[4:5]
	s_waitcnt lgkmcnt(0)
	global_store_dwordx4 v[146:147], v[246:249], off
	v_pk_mul_f32 v[220:221], v[34:35], s[30:31]
	v_exp_f32_e32 v220, v220
	v_exp_f32_e32 v221, v221
	s_nop 0
	v_pk_add_f32 v[220:221], v[220:221], 1.0 op_sel_hi:[1,0]
	v_rcp_f32_e32 v220, v220
	v_rcp_f32_e32 v221, v221
	s_nop 0
	v_pk_mul_f32 v[220:221], v[220:221], v[34:35]
	v_pk_mul_f32 v[220:221], v[220:221], v[26:27]
	v_cvt_pk_bf16_f32 v224, v220, v221
	v_pk_mul_f32 v[220:221], v[36:37], s[30:31]
	v_exp_f32_e32 v220, v220
	v_exp_f32_e32 v221, v221
	s_nop 0
	v_pk_add_f32 v[220:221], v[220:221], 1.0 op_sel_hi:[1,0]
	v_rcp_f32_e32 v220, v220
	v_rcp_f32_e32 v221, v221
	s_nop 0
	v_pk_mul_f32 v[220:221], v[220:221], v[36:37]
	v_pk_mul_f32 v[220:221], v[220:221], v[28:29]
	v_cvt_pk_bf16_f32 v225, v220, v221
	v_pk_mul_f32 v[220:221], v[30:31], s[30:31]
	v_exp_f32_e32 v220, v220
	v_exp_f32_e32 v221, v221
	s_nop 0
	v_pk_add_f32 v[220:221], v[220:221], 1.0 op_sel_hi:[1,0]
	v_rcp_f32_e32 v220, v220
	v_rcp_f32_e32 v221, v221
	s_nop 0
	v_pk_mul_f32 v[220:221], v[220:221], v[30:31]
	v_pk_mul_f32 v[220:221], v[220:221], v[22:23]
	v_cvt_pk_bf16_f32 v226, v220, v221
	v_pk_mul_f32 v[220:221], v[32:33], s[30:31]
	v_exp_f32_e32 v220, v220
	v_exp_f32_e32 v221, v221
	s_nop 0
	v_pk_add_f32 v[220:221], v[220:221], 1.0 op_sel_hi:[1,0]
	v_rcp_f32_e32 v220, v220
	v_rcp_f32_e32 v221, v221
	s_nop 0
	v_pk_mul_f32 v[220:221], v[220:221], v[32:33]
	v_pk_mul_f32 v[220:221], v[220:221], v[24:25]
	v_cvt_pk_bf16_f32 v227, v220, v221
	ds_bpermute_b32 v242, v145, v224
	ds_bpermute_b32 v243, v145, v225
	ds_bpermute_b32 v244, v145, v226
	ds_bpermute_b32 v245, v145, v227
	s_mov_b32 s4, 0xb2c00
	s_mov_b32 s5, 0
	v_lshl_add_u64 v[146:147], v[216:217], 0, s[4:5]
	s_waitcnt lgkmcnt(0)
	global_store_dwordx4 v[146:147], v[242:245], off
	v_pk_mul_f32 v[220:221], v[18:19], s[30:31]
	v_exp_f32_e32 v220, v220
	v_exp_f32_e32 v221, v221
	s_nop 0
	v_pk_add_f32 v[220:221], v[220:221], 1.0 op_sel_hi:[1,0]
	v_rcp_f32_e32 v220, v220
	v_rcp_f32_e32 v221, v221
	s_nop 0
	v_pk_mul_f32 v[220:221], v[220:221], v[18:19]
	v_pk_mul_f32 v[220:221], v[220:221], v[10:11]
	v_cvt_pk_bf16_f32 v224, v220, v221
	v_pk_mul_f32 v[220:221], v[20:21], s[30:31]
	v_exp_f32_e32 v220, v220
	v_exp_f32_e32 v221, v221
	s_nop 0
	v_pk_add_f32 v[220:221], v[220:221], 1.0 op_sel_hi:[1,0]
	v_rcp_f32_e32 v220, v220
	v_rcp_f32_e32 v221, v221
	s_nop 0
	v_pk_mul_f32 v[220:221], v[220:221], v[20:21]
	v_pk_mul_f32 v[220:221], v[220:221], v[12:13]
	v_cvt_pk_bf16_f32 v225, v220, v221
	v_pk_mul_f32 v[220:221], v[14:15], s[30:31]
	v_exp_f32_e32 v220, v220
	v_exp_f32_e32 v221, v221
	s_nop 0
	v_pk_add_f32 v[220:221], v[220:221], 1.0 op_sel_hi:[1,0]
	v_rcp_f32_e32 v220, v220
	v_rcp_f32_e32 v221, v221
	s_nop 0
	v_pk_mul_f32 v[220:221], v[220:221], v[14:15]
	v_pk_mul_f32 v[220:221], v[220:221], v[6:7]
	v_cvt_pk_bf16_f32 v226, v220, v221
	v_pk_mul_f32 v[220:221], v[16:17], s[30:31]
	v_exp_f32_e32 v220, v220
	v_exp_f32_e32 v221, v221
	s_nop 0
	v_pk_add_f32 v[220:221], v[220:221], 1.0 op_sel_hi:[1,0]
	v_rcp_f32_e32 v220, v220
	v_rcp_f32_e32 v221, v221
	s_nop 0
	v_pk_mul_f32 v[220:221], v[220:221], v[16:17]
	v_pk_mul_f32 v[220:221], v[220:221], v[8:9]
	v_cvt_pk_bf16_f32 v227, v220, v221
	ds_bpermute_b32 v246, v145, v224
	ds_bpermute_b32 v247, v145, v225
	ds_bpermute_b32 v248, v145, v226
	ds_bpermute_b32 v249, v145, v227
	s_mov_b32 s4, 0xb4200
	s_mov_b32 s5, 0
	v_lshl_add_u64 v[146:147], v[216:217], 0, s[4:5]
	s_waitcnt lgkmcnt(0)
	global_store_dwordx4 v[146:147], v[246:249], off
	s_branch .Lup_epi_done
.Lup_raw_epi:
	v_mbcnt_lo_u32_b32 v142, -1, 0
	v_mbcnt_hi_u32_b32 v142, -1, v142
	v_and_b32_e32 v143, 3, v142
	v_lshrrev_b32_e32 v144, 2, v142
	v_lshl_or_b32 v145, v143, 4, v144
	v_lshlrev_b32_e32 v145, 2, v145
	s_lshl_b32 s19, s4, 8
	s_add_i32 s19, s19, s43
	v_lshl_add_u32 v146, v144, 2, s19
	s_lshl_b32 s21, s26, 7
	v_and_b32_e32 v147, 0x60, v149
	v_lshl_or_b32 v147, v143, 3, v147
	v_add_u32_e32 v147, s21, v147
	v_mov_b64_e32 v[154:155], s[10:11]
	v_mad_u64_u32 v[152:153], s[28:29], v146, s91, v[154:155]
	v_mov_b32_e32 v156, v147
	v_mov_b32_e32 v157, 0
	v_lshl_add_u64 v[152:153], v[156:157], 1, v[152:153]
	v_lshl_add_u32 v200, v5, 2, s19
	v_add_u32_e32 v201, s21, v149
	s_mov_b32 s29, 0
	v_cvt_pk_bf16_f32 v160, v130, v131
	v_cvt_pk_bf16_f32 v161, v132, v133
	v_cvt_pk_bf16_f32 v162, v126, v127
	v_cvt_pk_bf16_f32 v163, v128, v129
	v_cvt_pk_bf16_f32 v164, v122, v123
	v_cvt_pk_bf16_f32 v165, v124, v125
	v_cvt_pk_bf16_f32 v166, v118, v119
	v_cvt_pk_bf16_f32 v167, v120, v121
	ds_bpermute_b32 v176, v145, v160
	ds_bpermute_b32 v177, v145, v161
	ds_bpermute_b32 v178, v145, v162
	ds_bpermute_b32 v179, v145, v163
	ds_bpermute_b32 v180, v145, v164
	ds_bpermute_b32 v181, v145, v165
	ds_bpermute_b32 v182, v145, v166
	ds_bpermute_b32 v183, v145, v167
	s_mov_b32 s28, 0x0
	v_lshl_add_u64 v[192:193], v[152:153], 0, s[28:29]
	s_mov_b32 s28, 0x1600
	v_lshl_add_u64 v[194:195], v[152:153], 0, s[28:29]
	s_waitcnt lgkmcnt(0)
	global_store_dwordx4 v[192:193], v[176:179], off
	global_store_dwordx4 v[194:195], v[180:183], off
	v_cvt_pk_bf16_f32 v168, v114, v115
	v_cvt_pk_bf16_f32 v169, v116, v117
	v_cvt_pk_bf16_f32 v170, v110, v111
	v_cvt_pk_bf16_f32 v171, v112, v113
	v_cvt_pk_bf16_f32 v172, v106, v107
	v_cvt_pk_bf16_f32 v173, v108, v109
	v_cvt_pk_bf16_f32 v174, v102, v103
	v_cvt_pk_bf16_f32 v175, v104, v105
	ds_bpermute_b32 v184, v145, v168
	ds_bpermute_b32 v185, v145, v169
	ds_bpermute_b32 v186, v145, v170
	ds_bpermute_b32 v187, v145, v171
	ds_bpermute_b32 v188, v145, v172
	ds_bpermute_b32 v189, v145, v173
	ds_bpermute_b32 v190, v145, v174
	ds_bpermute_b32 v191, v145, v175
	s_mov_b32 s28, 0x2c00
	v_lshl_add_u64 v[196:197], v[152:153], 0, s[28:29]
	s_mov_b32 s28, 0x4200
	v_lshl_add_u64 v[198:199], v[152:153], 0, s[28:29]
	s_waitcnt lgkmcnt(0)
	global_store_dwordx4 v[196:197], v[184:187], off
	global_store_dwordx4 v[198:199], v[188:191], off
	v_cvt_pk_bf16_f32 v160, v98, v99
	v_cvt_pk_bf16_f32 v161, v100, v101
	v_cvt_pk_bf16_f32 v162, v94, v95
	v_cvt_pk_bf16_f32 v163, v96, v97
	v_cvt_pk_bf16_f32 v164, v90, v91
	v_cvt_pk_bf16_f32 v165, v92, v93
	v_cvt_pk_bf16_f32 v166, v86, v87
	v_cvt_pk_bf16_f32 v167, v88, v89
	ds_bpermute_b32 v176, v145, v160
	ds_bpermute_b32 v177, v145, v161
	ds_bpermute_b32 v178, v145, v162
	ds_bpermute_b32 v179, v145, v163
	ds_bpermute_b32 v180, v145, v164
	ds_bpermute_b32 v181, v145, v165
	ds_bpermute_b32 v182, v145, v166
	ds_bpermute_b32 v183, v145, v167
	s_mov_b32 s28, 0x5800
	v_lshl_add_u64 v[192:193], v[152:153], 0, s[28:29]
	s_mov_b32 s28, 0x6e00
	v_lshl_add_u64 v[194:195], v[152:153], 0, s[28:29]
	s_waitcnt lgkmcnt(0)
	global_store_dwordx4 v[192:193], v[176:179], off
	global_store_dwordx4 v[194:195], v[180:183], off
	v_cvt_pk_bf16_f32 v168, v82, v83
	v_cvt_pk_bf16_f32 v169, v84, v85
	v_cvt_pk_bf16_f32 v170, v78, v79
	v_cvt_pk_bf16_f32 v171, v80, v81
	v_cvt_pk_bf16_f32 v172, v74, v75
	v_cvt_pk_bf16_f32 v173, v76, v77
	v_cvt_pk_bf16_f32 v174, v70, v71
	v_cvt_pk_bf16_f32 v175, v72, v73
	ds_bpermute_b32 v184, v145, v168
	ds_bpermute_b32 v185, v145, v169
	ds_bpermute_b32 v186, v145, v170
	ds_bpermute_b32 v187, v145, v171
	ds_bpermute_b32 v188, v145, v172
	ds_bpermute_b32 v189, v145, v173
	ds_bpermute_b32 v190, v145, v174
	ds_bpermute_b32 v191, v145, v175
	s_mov_b32 s28, 0x8400
	v_lshl_add_u64 v[196:197], v[152:153], 0, s[28:29]
	s_mov_b32 s28, 0x9a00
	v_lshl_add_u64 v[198:199], v[152:153], 0, s[28:29]
	s_waitcnt lgkmcnt(0)
	global_store_dwordx4 v[196:197], v[184:187], off
	global_store_dwordx4 v[198:199], v[188:191], off
	v_cvt_pk_bf16_f32 v160, v66, v67
	v_cvt_pk_bf16_f32 v161, v68, v69
	v_cvt_pk_bf16_f32 v162, v62, v63
	v_cvt_pk_bf16_f32 v163, v64, v65
	v_cvt_pk_bf16_f32 v164, v58, v59
	v_cvt_pk_bf16_f32 v165, v60, v61
	v_cvt_pk_bf16_f32 v166, v54, v55
	v_cvt_pk_bf16_f32 v167, v56, v57
	ds_bpermute_b32 v176, v145, v160
	ds_bpermute_b32 v177, v145, v161
	ds_bpermute_b32 v178, v145, v162
	ds_bpermute_b32 v179, v145, v163
	ds_bpermute_b32 v180, v145, v164
	ds_bpermute_b32 v181, v145, v165
	ds_bpermute_b32 v182, v145, v166
	ds_bpermute_b32 v183, v145, v167
	s_mov_b32 s28, 0x160000
	v_lshl_add_u64 v[192:193], v[152:153], 0, s[28:29]
	s_mov_b32 s28, 0x161600
	v_lshl_add_u64 v[194:195], v[152:153], 0, s[28:29]
	s_waitcnt lgkmcnt(0)
	global_store_dwordx4 v[192:193], v[176:179], off
	global_store_dwordx4 v[194:195], v[180:183], off
	v_cvt_pk_bf16_f32 v168, v50, v51
	v_cvt_pk_bf16_f32 v169, v52, v53
	v_cvt_pk_bf16_f32 v170, v46, v47
	v_cvt_pk_bf16_f32 v171, v48, v49
	v_cvt_pk_bf16_f32 v172, v42, v43
	v_cvt_pk_bf16_f32 v173, v44, v45
	v_cvt_pk_bf16_f32 v174, v38, v39
	v_cvt_pk_bf16_f32 v175, v40, v41
	ds_bpermute_b32 v184, v145, v168
	ds_bpermute_b32 v185, v145, v169
	ds_bpermute_b32 v186, v145, v170
	ds_bpermute_b32 v187, v145, v171
	ds_bpermute_b32 v188, v145, v172
	ds_bpermute_b32 v189, v145, v173
	ds_bpermute_b32 v190, v145, v174
	ds_bpermute_b32 v191, v145, v175
	s_mov_b32 s28, 0x162c00
	v_lshl_add_u64 v[196:197], v[152:153], 0, s[28:29]
	s_mov_b32 s28, 0x164200
	v_lshl_add_u64 v[198:199], v[152:153], 0, s[28:29]
	s_waitcnt lgkmcnt(0)
	global_store_dwordx4 v[196:197], v[184:187], off
	global_store_dwordx4 v[198:199], v[188:191], off
	v_cvt_pk_bf16_f32 v160, v34, v35
	v_cvt_pk_bf16_f32 v161, v36, v37
	v_cvt_pk_bf16_f32 v162, v30, v31
	v_cvt_pk_bf16_f32 v163, v32, v33
	v_cvt_pk_bf16_f32 v164, v26, v27
	v_cvt_pk_bf16_f32 v165, v28, v29
	v_cvt_pk_bf16_f32 v166, v22, v23
	v_cvt_pk_bf16_f32 v167, v24, v25
	ds_bpermute_b32 v176, v145, v160
	ds_bpermute_b32 v177, v145, v161
	ds_bpermute_b32 v178, v145, v162
	ds_bpermute_b32 v179, v145, v163
	ds_bpermute_b32 v180, v145, v164
	ds_bpermute_b32 v181, v145, v165
	ds_bpermute_b32 v182, v145, v166
	ds_bpermute_b32 v183, v145, v167
	s_mov_b32 s28, 0x165800
	v_lshl_add_u64 v[192:193], v[152:153], 0, s[28:29]
	s_mov_b32 s28, 0x166e00
	v_lshl_add_u64 v[194:195], v[152:153], 0, s[28:29]
	s_waitcnt lgkmcnt(0)
	global_store_dwordx4 v[192:193], v[176:179], off
	global_store_dwordx4 v[194:195], v[180:183], off
	v_cvt_pk_bf16_f32 v168, v18, v19
	v_cvt_pk_bf16_f32 v169, v20, v21
	v_cvt_pk_bf16_f32 v170, v14, v15
	v_cvt_pk_bf16_f32 v171, v16, v17
	v_cvt_pk_bf16_f32 v172, v10, v11
	v_cvt_pk_bf16_f32 v173, v12, v13
	v_cvt_pk_bf16_f32 v174, v6, v7
	v_cvt_pk_bf16_f32 v175, v8, v9
	ds_bpermute_b32 v184, v145, v168
	ds_bpermute_b32 v185, v145, v169
	ds_bpermute_b32 v186, v145, v170
	ds_bpermute_b32 v187, v145, v171
	ds_bpermute_b32 v188, v145, v172
	ds_bpermute_b32 v189, v145, v173
	ds_bpermute_b32 v190, v145, v174
	ds_bpermute_b32 v191, v145, v175
	s_mov_b32 s28, 0x168400
	v_lshl_add_u64 v[196:197], v[152:153], 0, s[28:29]
	s_mov_b32 s28, 0x169a00
	v_lshl_add_u64 v[198:199], v[152:153], 0, s[28:29]
	s_waitcnt lgkmcnt(0)
	global_store_dwordx4 v[196:197], v[184:187], off
	global_store_dwordx4 v[198:199], v[188:191], off
	s_cmp_gt_i32 s4, 63
	s_cbranch_scc1 .Lup_tail_sample
	s_and_b32 s28, s4, 31
	s_cmp_lg_u32 s28, 31
	s_cbranch_scc1 .Lup_tail_done
	s_cmp_lg_u32 s43, 64
	s_cbranch_scc1 .Lup_tail_done
	v_cmp_eq_u32_e32 vcc, 15, v5
	s_and_saveexec_b64 s[30:31], vcc
	v_add_u32_e32 v204, 130, v200
	v_lshrrev_b32_e32 v205, 13, v204
	v_and_b32_e32 v204, 0x1fff, v204
	v_lshl_add_u32 v204, v205, 1, v204
	v_add_u32_e32 v204, 0xffffe002, v204
	v_mov_b64_e32 v[154:155], s[12:13]
	v_mad_u64_u32 v[202:203], s[28:29], v204, s90, v[154:155]
	v_mov_b32_e32 v156, v201
	v_mov_b32_e32 v157, 0
	v_lshl_add_u64 v[202:203], v[156:157], 2, v[202:203]
	global_store_dwordx4 v[202:203], v[34:37], off
	global_store_dwordx4 v[202:203], v[30:33], off offset:16
	s_mov_b32 s28, 0x2c00
	s_mov_b32 s29, 0
	v_lshl_add_u64 v[202:203], v[202:203], 0, s[28:29]
	global_store_dwordx4 v[202:203], v[26:29], off
	global_store_dwordx4 v[202:203], v[22:25], off offset:16
	v_add_u32_e32 v204, 131, v200
	v_lshrrev_b32_e32 v205, 13, v204
	v_and_b32_e32 v204, 0x1fff, v204
	v_lshl_add_u32 v204, v205, 1, v204
	v_add_u32_e32 v204, 0xffffe002, v204
	v_mov_b64_e32 v[154:155], s[12:13]
	v_mad_u64_u32 v[202:203], s[28:29], v204, s90, v[154:155]
	v_mov_b32_e32 v156, v201
	v_mov_b32_e32 v157, 0
	v_lshl_add_u64 v[202:203], v[156:157], 2, v[202:203]
	global_store_dwordx4 v[202:203], v[18:21], off
	global_store_dwordx4 v[202:203], v[14:17], off offset:16
	s_mov_b32 s28, 0x2c00
	s_mov_b32 s29, 0
	v_lshl_add_u64 v[202:203], v[202:203], 0, s[28:29]
	global_store_dwordx4 v[202:203], v[10:13], off
	global_store_dwordx4 v[202:203], v[6:9], off offset:16
	s_or_b64 exec, exec, s[30:31]
	s_branch .Lup_tail_done
.Lup_tail_sample:
	v_and_b32_e32 v204, 1, v5
	v_cmp_eq_u32_e32 vcc, 1, v204
	s_and_saveexec_b64 s[30:31], vcc
	v_add_u32_e32 v204, 0xffffc002, v200
	v_lshrrev_b32_e32 v204, 3, v204
	v_lshl_add_u32 v204, v204, 1, 0
	v_mov_b64_e32 v[154:155], s[14:15]
	v_mad_u64_u32 v[202:203], s[28:29], v204, s90, v[154:155]
	v_mov_b32_e32 v156, v201
	v_mov_b32_e32 v157, 0
	v_lshl_add_u64 v[202:203], v[156:157], 2, v[202:203]
	global_store_dwordx4 v[202:203], v[98:101], off
	global_store_dwordx4 v[202:203], v[94:97], off offset:16
	s_mov_b32 s28, 0x2c00
	s_mov_b32 s29, 0
	v_lshl_add_u64 v[202:203], v[202:203], 0, s[28:29]
	global_store_dwordx4 v[202:203], v[90:93], off
	global_store_dwordx4 v[202:203], v[86:89], off offset:16
	v_add_u32_e32 v204, 0xffffc003, v200
	v_lshrrev_b32_e32 v204, 3, v204
	v_lshl_add_u32 v204, v204, 1, 1
	v_mov_b64_e32 v[154:155], s[14:15]
	v_mad_u64_u32 v[202:203], s[28:29], v204, s90, v[154:155]
	v_mov_b32_e32 v156, v201
	v_mov_b32_e32 v157, 0
	v_lshl_add_u64 v[202:203], v[156:157], 2, v[202:203]
	global_store_dwordx4 v[202:203], v[82:85], off
	global_store_dwordx4 v[202:203], v[78:81], off offset:16
	s_mov_b32 s28, 0x2c00
	s_mov_b32 s29, 0
	v_lshl_add_u64 v[202:203], v[202:203], 0, s[28:29]
	global_store_dwordx4 v[202:203], v[74:77], off
	global_store_dwordx4 v[202:203], v[70:73], off offset:16
	v_add_u32_e32 v204, 0xffffc082, v200
	v_lshrrev_b32_e32 v204, 3, v204
	v_lshl_add_u32 v204, v204, 1, 0
	v_mov_b64_e32 v[154:155], s[14:15]
	v_mad_u64_u32 v[202:203], s[28:29], v204, s90, v[154:155]
	v_mov_b32_e32 v156, v201
	v_mov_b32_e32 v157, 0
	v_lshl_add_u64 v[202:203], v[156:157], 2, v[202:203]
	global_store_dwordx4 v[202:203], v[34:37], off
	global_store_dwordx4 v[202:203], v[30:33], off offset:16
	s_mov_b32 s28, 0x2c00
	s_mov_b32 s29, 0
	v_lshl_add_u64 v[202:203], v[202:203], 0, s[28:29]
	global_store_dwordx4 v[202:203], v[26:29], off
	global_store_dwordx4 v[202:203], v[22:25], off offset:16
	v_add_u32_e32 v204, 0xffffc083, v200
	v_lshrrev_b32_e32 v204, 3, v204
	v_lshl_add_u32 v204, v204, 1, 1
	v_mov_b64_e32 v[154:155], s[14:15]
	v_mad_u64_u32 v[202:203], s[28:29], v204, s90, v[154:155]
	v_mov_b32_e32 v156, v201
	v_mov_b32_e32 v157, 0
	v_lshl_add_u64 v[202:203], v[156:157], 2, v[202:203]
	global_store_dwordx4 v[202:203], v[18:21], off
	global_store_dwordx4 v[202:203], v[14:17], off offset:16
	s_mov_b32 s28, 0x2c00
	s_mov_b32 s29, 0
	v_lshl_add_u64 v[202:203], v[202:203], 0, s[28:29]
	global_store_dwordx4 v[202:203], v[10:13], off
	global_store_dwordx4 v[202:203], v[6:9], off offset:16
	s_or_b64 exec, exec, s[30:31]
.Lup_tail_done:
.Lup_epi_done:
	s_andn2_b64 vcc, exec, s[2:3]
	s_mov_b64 s[2:3], -1
	s_cbranch_vccnz .LBB0_75
	s_andn2_b64 vcc, exec, s[8:9]
	s_cbranch_vccnz .LBB0_74
	s_barrier
	s_branch .LBB0_74

.LBB0_182:
	v_lshl_add_u32 v0, s84, 9, v241
	s_mov_b32 s2, 0x16000
	v_cmp_gt_u32_e32 vcc, s2, v0
	s_and_saveexec_b64 s[4:5], vcc
	s_cbranch_execz .Lbnd_done
	s_load_dwordx4 s[8:11], s[54:55], 0xb8
	v_readlane_b32 s14, v253, 41
	s_add_u32 s6, s82, 0xd200000
	s_addc_u32 s7, s83, 0
	s_add_u32 s12, s6, 0x6000000
	s_addc_u32 s13, s7, 0
	v_lshrrev_b32_e32 v2, 5, v0
	s_mov_b32 s2, 0xba2e8ba3
	v_mul_hi_u32 v2, v2, s2
	v_lshrrev_b32_e32 v2, 3, v2
	v_mul_u32_u24_e32 v3, 0x160, v2
	v_sub_u32_e32 v3, v0, v3
	v_lshlrev_b32_e32 v6, 4, v3
	v_lshlrev_b32_e32 v7, 5, v3
	s_mul_i32 s15, s14, 0x10800
	s_mul_i32 s14, s14, 0x5800
	s_waitcnt lgkmcnt(0)
	s_add_u32 s8, s8, s15
	s_addc_u32 s9, s9, 0
	s_add_u32 s10, s10, s14
	s_addc_u32 s11, s11, 0
	global_load_dwordx4 v[16:19], v7, s[8:9] offset:0
	global_load_dwordx4 v[20:23], v7, s[8:9] offset:16
	v_add_u32_e32 v8, 0x2c00, v7
	global_load_dwordx4 v[48:51], v8, s[8:9]
	v_add_u32_e32 v8, 0x2c10, v7
	global_load_dwordx4 v[52:55], v8, s[8:9]
	v_add_u32_e32 v8, 0x5800, v7
	global_load_dwordx4 v[24:27], v8, s[8:9]
	v_add_u32_e32 v8, 0x5810, v7
	global_load_dwordx4 v[28:31], v8, s[8:9]
	v_add_u32_e32 v8, 0x8400, v7
	global_load_dwordx4 v[56:59], v8, s[8:9]
	v_add_u32_e32 v8, 0x8410, v7
	global_load_dwordx4 v[60:63], v8, s[8:9]
	v_add_u32_e32 v8, 0xb000, v7
	global_load_dwordx4 v[32:35], v8, s[8:9]
	v_add_u32_e32 v8, 0xb010, v7
	global_load_dwordx4 v[36:39], v8, s[8:9]
	v_add_u32_e32 v8, 0xdc00, v7
	global_load_dwordx4 v[64:67], v8, s[8:9]
	v_add_u32_e32 v8, 0xdc10, v7
	global_load_dwordx4 v[68:71], v8, s[8:9]
	global_load_dwordx4 v[40:43], v7, s[10:11] offset:0
	global_load_dwordx4 v[44:47], v7, s[10:11] offset:16
	v_add_u32_e32 v8, 0x2c00, v7
	global_load_dwordx4 v[72:75], v8, s[10:11]
	v_add_u32_e32 v8, 0x2c10, v7
	global_load_dwordx4 v[76:79], v8, s[10:11]
	v_lshlrev_b32_e32 v9, 2, v2
	v_mov_b64_e32 v[10:11], s[12:13]
	v_mad_u64_u32 v[10:11], s[2:3], v9, s91, v[10:11]
	v_mov_b32_e32 v12, v6
	v_mov_b32_e32 v13, 0
	v_lshl_add_u64 v[10:11], v[10:11], 0, v[12:13]
	v_mov_b32_e32 v80, 0
	v_mov_b32_e32 v81, 0
	v_mov_b32_e32 v82, 0
	v_mov_b32_e32 v83, 0
	v_mov_b32_e32 v84, 0
	v_mov_b32_e32 v85, 0
	v_mov_b32_e32 v86, 0
	v_mov_b32_e32 v87, 0
	v_mov_b32_e32 v96, 0
	v_mov_b32_e32 v97, 0
	v_mov_b32_e32 v98, 0
	v_mov_b32_e32 v99, 0
	v_mov_b32_e32 v100, 0
	v_mov_b32_e32 v101, 0
	v_mov_b32_e32 v102, 0
	v_mov_b32_e32 v103, 0
	global_load_dwordx4 v[88:91], v[10:11], off
	s_mov_b64 s[2:3], 0x1600
	v_lshl_add_u64 v[12:13], v[10:11], 0, s[2:3]
	global_load_dwordx4 v[104:107], v[12:13], off
	s_mov_b64 s[2:3], 0x2c00
	v_lshl_add_u64 v[14:15], v[10:11], 0, s[2:3]
	global_load_dwordx4 v[92:95], v[14:15], off
	s_mov_b64 s[2:3], 0x4200
	v_lshl_add_u64 v[14:15], v[10:11], 0, s[2:3]
	global_load_dwordx4 v[108:111], v[14:15], off
	v_and_b32_e32 v9, 0x7f, v2
	v_cmp_ne_u32_e32 vcc, 0, v9
	s_and_saveexec_b64 s[16:17], vcc
	s_mov_b64 s[2:3], 0x2c00
	v_mov_b32_e32 v14, v10
	v_mov_b32_e32 v15, v11
	v_subrev_co_u32_e32 v14, vcc, 0x2c00, v10
	v_subbrev_co_u32_e32 v15, vcc, 0, v11, vcc
	global_load_dwordx4 v[84:87], v[14:15], off
	s_mov_b64 s[2:3], 0x1600
	v_lshl_add_u64 v[12:13], v[14:15], 0, s[2:3]
	global_load_dwordx4 v[100:103], v[12:13], off
	v_subrev_co_u32_e32 v14, vcc, 0x5800, v10
	v_subbrev_co_u32_e32 v15, vcc, 0, v11, vcc
	global_load_dwordx4 v[80:83], v[14:15], off
	v_lshl_add_u64 v[12:13], v[14:15], 0, s[2:3]
	global_load_dwordx4 v[96:99], v[12:13], off
	s_or_b64 exec, exec, s[16:17]
	s_waitcnt vmcnt(0)
	v_lshlrev_b32_e32 v112, 16, v80
	v_and_b32_e32 v113, 0xffff0000, v80
	v_lshlrev_b32_e32 v114, 16, v81
	v_and_b32_e32 v115, 0xffff0000, v81
	v_lshlrev_b32_e32 v116, 16, v82
	v_and_b32_e32 v117, 0xffff0000, v82
	v_lshlrev_b32_e32 v118, 16, v83
	v_and_b32_e32 v119, 0xffff0000, v83
	v_lshlrev_b32_e32 v120, 16, v84
	v_and_b32_e32 v121, 0xffff0000, v84
	v_lshlrev_b32_e32 v122, 16, v85
	v_and_b32_e32 v123, 0xffff0000, v85
	v_lshlrev_b32_e32 v124, 16, v86
	v_and_b32_e32 v125, 0xffff0000, v86
	v_lshlrev_b32_e32 v126, 16, v87
	v_and_b32_e32 v127, 0xffff0000, v87
	v_lshlrev_b32_e32 v128, 16, v88
	v_and_b32_e32 v129, 0xffff0000, v88
	v_lshlrev_b32_e32 v130, 16, v89
	v_and_b32_e32 v131, 0xffff0000, v89
	v_lshlrev_b32_e32 v132, 16, v90
	v_and_b32_e32 v133, 0xffff0000, v90
	v_lshlrev_b32_e32 v134, 16, v91
	v_and_b32_e32 v135, 0xffff0000, v91
	v_lshlrev_b32_e32 v136, 16, v92
	v_and_b32_e32 v137, 0xffff0000, v92
	v_lshlrev_b32_e32 v138, 16, v93
	v_and_b32_e32 v139, 0xffff0000, v93
	v_lshlrev_b32_e32 v140, 16, v94
	v_and_b32_e32 v141, 0xffff0000, v94
	v_lshlrev_b32_e32 v142, 16, v95
	v_and_b32_e32 v143, 0xffff0000, v95
	v_lshlrev_b32_e32 v144, 16, v96
	v_and_b32_e32 v145, 0xffff0000, v96
	v_lshlrev_b32_e32 v146, 16, v97
	v_and_b32_e32 v147, 0xffff0000, v97
	v_lshlrev_b32_e32 v148, 16, v98
	v_and_b32_e32 v149, 0xffff0000, v98
	v_lshlrev_b32_e32 v150, 16, v99
	v_and_b32_e32 v151, 0xffff0000, v99
	v_lshlrev_b32_e32 v152, 16, v100
	v_and_b32_e32 v153, 0xffff0000, v100
	v_lshlrev_b32_e32 v154, 16, v101
	v_and_b32_e32 v155, 0xffff0000, v101
	v_lshlrev_b32_e32 v156, 16, v102
	v_and_b32_e32 v157, 0xffff0000, v102
	v_lshlrev_b32_e32 v158, 16, v103
	v_and_b32_e32 v159, 0xffff0000, v103
	v_lshlrev_b32_e32 v160, 16, v104
	v_and_b32_e32 v161, 0xffff0000, v104
	v_lshlrev_b32_e32 v162, 16, v105
	v_and_b32_e32 v163, 0xffff0000, v105
	v_lshlrev_b32_e32 v164, 16, v106
	v_and_b32_e32 v165, 0xffff0000, v106
	v_lshlrev_b32_e32 v166, 16, v107
	v_and_b32_e32 v167, 0xffff0000, v107
	v_lshlrev_b32_e32 v168, 16, v108
	v_and_b32_e32 v169, 0xffff0000, v108
	v_lshlrev_b32_e32 v170, 16, v109
	v_and_b32_e32 v171, 0xffff0000, v109
	v_lshlrev_b32_e32 v172, 16, v110
	v_and_b32_e32 v173, 0xffff0000, v110
	v_lshlrev_b32_e32 v174, 16, v111
	v_and_b32_e32 v175, 0xffff0000, v111
	v_pk_fma_f32 v[176:177], v[112:113], v[16:17], v[40:41]
	v_pk_fma_f32 v[176:177], v[120:121], v[24:25], v[176:177]
	v_pk_fma_f32 v[176:177], v[128:129], v[32:33], v[176:177]
	v_pk_fma_f32 v[184:185], v[120:121], v[16:17], v[40:41]
	v_pk_fma_f32 v[184:185], v[128:129], v[24:25], v[184:185]
	v_pk_fma_f32 v[184:185], v[136:137], v[32:33], v[184:185]
	v_pk_fma_f32 v[178:179], v[114:115], v[18:19], v[42:43]
	v_pk_fma_f32 v[178:179], v[122:123], v[26:27], v[178:179]
	v_pk_fma_f32 v[178:179], v[130:131], v[34:35], v[178:179]
	v_pk_fma_f32 v[186:187], v[122:123], v[18:19], v[42:43]
	v_pk_fma_f32 v[186:187], v[130:131], v[26:27], v[186:187]
	v_pk_fma_f32 v[186:187], v[138:139], v[34:35], v[186:187]
	v_pk_fma_f32 v[180:181], v[116:117], v[20:21], v[44:45]
	v_pk_fma_f32 v[180:181], v[124:125], v[28:29], v[180:181]
	v_pk_fma_f32 v[180:181], v[132:133], v[36:37], v[180:181]
	v_pk_fma_f32 v[188:189], v[124:125], v[20:21], v[44:45]
	v_pk_fma_f32 v[188:189], v[132:133], v[28:29], v[188:189]
	v_pk_fma_f32 v[188:189], v[140:141], v[36:37], v[188:189]
	v_pk_fma_f32 v[182:183], v[118:119], v[22:23], v[46:47]
	v_pk_fma_f32 v[182:183], v[126:127], v[30:31], v[182:183]
	v_pk_fma_f32 v[182:183], v[134:135], v[38:39], v[182:183]
	v_pk_fma_f32 v[190:191], v[126:127], v[22:23], v[46:47]
	v_pk_fma_f32 v[190:191], v[134:135], v[30:31], v[190:191]
	v_pk_fma_f32 v[190:191], v[142:143], v[38:39], v[190:191]
	v_pk_fma_f32 v[192:193], v[144:145], v[48:49], v[72:73]
	v_pk_fma_f32 v[192:193], v[152:153], v[56:57], v[192:193]
	v_pk_fma_f32 v[192:193], v[160:161], v[64:65], v[192:193]
	v_pk_fma_f32 v[200:201], v[152:153], v[48:49], v[72:73]
	v_pk_fma_f32 v[200:201], v[160:161], v[56:57], v[200:201]
	v_pk_fma_f32 v[200:201], v[168:169], v[64:65], v[200:201]
	v_pk_fma_f32 v[194:195], v[146:147], v[50:51], v[74:75]
	v_pk_fma_f32 v[194:195], v[154:155], v[58:59], v[194:195]
	v_pk_fma_f32 v[194:195], v[162:163], v[66:67], v[194:195]
	v_pk_fma_f32 v[202:203], v[154:155], v[50:51], v[74:75]
	v_pk_fma_f32 v[202:203], v[162:163], v[58:59], v[202:203]
	v_pk_fma_f32 v[202:203], v[170:171], v[66:67], v[202:203]
	v_pk_fma_f32 v[196:197], v[148:149], v[52:53], v[76:77]
	v_pk_fma_f32 v[196:197], v[156:157], v[60:61], v[196:197]
	v_pk_fma_f32 v[196:197], v[164:165], v[68:69], v[196:197]
	v_pk_fma_f32 v[204:205], v[156:157], v[52:53], v[76:77]
	v_pk_fma_f32 v[204:205], v[164:165], v[60:61], v[204:205]
	v_pk_fma_f32 v[204:205], v[172:173], v[68:69], v[204:205]
	v_pk_fma_f32 v[198:199], v[150:151], v[54:55], v[78:79]
	v_pk_fma_f32 v[198:199], v[158:159], v[62:63], v[198:199]
	v_pk_fma_f32 v[198:199], v[166:167], v[70:71], v[198:199]
	v_pk_fma_f32 v[206:207], v[158:159], v[54:55], v[78:79]
	v_pk_fma_f32 v[206:207], v[166:167], v[62:63], v[206:207]
	v_pk_fma_f32 v[206:207], v[174:175], v[70:71], v[206:207]
	s_mov_b32 s2, 0xbfb8aa3b
	s_mov_b32 s3, 0xbfb8aa3b
	v_pk_mul_f32 v[216:217], v[176:177], s[2:3]
	v_exp_f32_e32 v216, v216
	v_exp_f32_e32 v217, v217
	s_nop 0
	v_pk_add_f32 v[216:217], v[216:217], 1.0 op_sel_hi:[1,0]
	v_rcp_f32_e32 v216, v216
	v_rcp_f32_e32 v217, v217
	s_nop 0
	v_pk_mul_f32 v[216:217], v[216:217], v[176:177]
	v_pk_mul_f32 v[216:217], v[216:217], v[192:193]
	v_cvt_pk_bf16_f32 v208, v216, v217
	v_pk_mul_f32 v[216:217], v[178:179], s[2:3]
	v_exp_f32_e32 v216, v216
	v_exp_f32_e32 v217, v217
	s_nop 0
	v_pk_add_f32 v[216:217], v[216:217], 1.0 op_sel_hi:[1,0]
	v_rcp_f32_e32 v216, v216
	v_rcp_f32_e32 v217, v217
	s_nop 0
	v_pk_mul_f32 v[216:217], v[216:217], v[178:179]
	v_pk_mul_f32 v[216:217], v[216:217], v[194:195]
	v_cvt_pk_bf16_f32 v209, v216, v217
	v_pk_mul_f32 v[216:217], v[180:181], s[2:3]
	v_exp_f32_e32 v216, v216
	v_exp_f32_e32 v217, v217
	s_nop 0
	v_pk_add_f32 v[216:217], v[216:217], 1.0 op_sel_hi:[1,0]
	v_rcp_f32_e32 v216, v216
	v_rcp_f32_e32 v217, v217
	s_nop 0
	v_pk_mul_f32 v[216:217], v[216:217], v[180:181]
	v_pk_mul_f32 v[216:217], v[216:217], v[196:197]
	v_cvt_pk_bf16_f32 v210, v216, v217
	v_pk_mul_f32 v[216:217], v[182:183], s[2:3]
	v_exp_f32_e32 v216, v216
	v_exp_f32_e32 v217, v217
	s_nop 0
	v_pk_add_f32 v[216:217], v[216:217], 1.0 op_sel_hi:[1,0]
	v_rcp_f32_e32 v216, v216
	v_rcp_f32_e32 v217, v217
	s_nop 0
	v_pk_mul_f32 v[216:217], v[216:217], v[182:183]
	v_pk_mul_f32 v[216:217], v[216:217], v[198:199]
	v_cvt_pk_bf16_f32 v211, v216, v217
	v_pk_mul_f32 v[216:217], v[184:185], s[2:3]
	v_exp_f32_e32 v216, v216
	v_exp_f32_e32 v217, v217
	s_nop 0
	v_pk_add_f32 v[216:217], v[216:217], 1.0 op_sel_hi:[1,0]
	v_rcp_f32_e32 v216, v216
	v_rcp_f32_e32 v217, v217
	s_nop 0
	v_pk_mul_f32 v[216:217], v[216:217], v[184:185]
	v_pk_mul_f32 v[216:217], v[216:217], v[200:201]
	v_cvt_pk_bf16_f32 v212, v216, v217
	v_pk_mul_f32 v[216:217], v[186:187], s[2:3]
	v_exp_f32_e32 v216, v216
	v_exp_f32_e32 v217, v217
	s_nop 0
	v_pk_add_f32 v[216:217], v[216:217], 1.0 op_sel_hi:[1,0]
	v_rcp_f32_e32 v216, v216
	v_rcp_f32_e32 v217, v217
	s_nop 0
	v_pk_mul_f32 v[216:217], v[216:217], v[186:187]
	v_pk_mul_f32 v[216:217], v[216:217], v[202:203]
	v_cvt_pk_bf16_f32 v213, v216, v217
	v_pk_mul_f32 v[216:217], v[188:189], s[2:3]
	v_exp_f32_e32 v216, v216
	v_exp_f32_e32 v217, v217
	s_nop 0
	v_pk_add_f32 v[216:217], v[216:217], 1.0 op_sel_hi:[1,0]
	v_rcp_f32_e32 v216, v216
	v_rcp_f32_e32 v217, v217
	s_nop 0
	v_pk_mul_f32 v[216:217], v[216:217], v[188:189]
	v_pk_mul_f32 v[216:217], v[216:217], v[204:205]
	v_cvt_pk_bf16_f32 v214, v216, v217
	v_pk_mul_f32 v[216:217], v[190:191], s[2:3]
	v_exp_f32_e32 v216, v216
	v_exp_f32_e32 v217, v217
	s_nop 0
	v_pk_add_f32 v[216:217], v[216:217], 1.0 op_sel_hi:[1,0]
	v_rcp_f32_e32 v216, v216
	v_rcp_f32_e32 v217, v217
	s_nop 0
	v_pk_mul_f32 v[216:217], v[216:217], v[190:191]
	v_pk_mul_f32 v[216:217], v[216:217], v[206:207]
	v_cvt_pk_bf16_f32 v215, v216, v217
	v_lshlrev_b32_e32 v9, 6, v2
	v_mov_b64_e32 v[10:11], s[6:7]
	s_movk_i32 s2, 0x1600
	v_mad_u64_u32 v[10:11], s[16:17], v9, s2, v[10:11]
	v_mov_b32_e32 v12, v6
	v_mov_b32_e32 v13, 0
	v_lshl_add_u64 v[10:11], v[10:11], 0, v[12:13]
	global_store_dwordx4 v[10:11], v[208:211], off
	s_mov_b64 s[2:3], 0x1600
	v_lshl_add_u64 v[10:11], v[10:11], 0, s[2:3]
	global_store_dwordx4 v[10:11], v[212:215], off
.Lbnd_done:
	s_or_b64 exec, exec, s[4:5]
	v_lshl_add_u32 v0, s84, 9, v241
	v_add_u32_e32 v0, 0x58000, v0
	s_mov_b32 s2, 0x5d800
	v_cmp_gt_i32_e32 vcc, s2, v0
	s_and_saveexec_b64 s[4:5], vcc
	s_cbranch_execz .LBB0_193
	s_load_dwordx4 s[8:11], s[54:55], 0xb8
	s_load_dwordx2 s[2:3], s[54:55], 0x30
	s_lshl_b32 s34, s40, 9
	s_add_u32 s6, s82, 0xd200000
	v_readlane_b32 s14, v253, 41
	s_addc_u32 s7, s83, 0
	s_mul_i32 s13, s14, 0x10800
	s_mul_hi_i32 s12, s14, 0x10800
	s_waitcnt lgkmcnt(0)
	s_add_u32 s8, s8, s13
	s_addc_u32 s9, s9, s12
	s_mul_i32 s13, s14, 0x5800
	s_mul_hi_i32 s12, s14, 0x5800
	s_add_u32 s10, s10, s13
	s_addc_u32 s11, s11, s12
	s_mul_i32 s12, s14, 0x580000
	s_mul_hi_i32 s13, s14, 0x580000
	s_add_u32 s12, s2, s12
	s_addc_u32 s13, s3, s13
	s_add_u32 s14, s10, 0x2c00
	s_addc_u32 s15, s11, 0
	s_add_u32 s16, s8, 0x2c00
	s_addc_u32 s17, s9, 0
	s_add_u32 s18, s8, 0x5800
	s_addc_u32 s19, s9, 0
	s_add_u32 s20, s8, 0x8400
	s_addc_u32 s21, s9, 0
	s_add_u32 s22, s8, 0xb000
	s_addc_u32 s23, s9, 0
	s_add_u32 s24, s8, 0xdc00
	v_mov_b32_e32 v98, 0
	s_addc_u32 s25, s9, 0
	v_lshlrev_b32_e32 v5, 3, v0
	s_lshl_b32 s35, s40, 12
	s_mov_b64 s[26:27], 0
	v_mov_b32_e32 v99, v98
	v_mov_b32_e32 v100, v98
	v_mov_b32_e32 v101, v98
	s_waitcnt vmcnt(0)
	v_mov_b32_e32 v86, v98
	v_mov_b32_e32 v87, v98
	v_mov_b32_e32 v88, v98
	v_mov_b32_e32 v89, v98
	v_mov_b32_e32 v106, v98
	v_mov_b32_e32 v107, v98
	v_mov_b32_e32 v108, v98
	v_mov_b32_e32 v109, v98
	v_mov_b32_e32 v102, v98
	v_mov_b32_e32 v103, v98
	v_mov_b32_e32 v104, v98
	v_mov_b32_e32 v105, v98
	s_branch .LBB0_185

.LBB0_191:
	s_or_b64 exec, exec, s[28:29]
	s_waitcnt vmcnt(24)
	v_mov_b32_e32 v168, v154
	v_mov_b32_e32 v169, v26
	s_waitcnt vmcnt(2)
	v_mov_b32_e32 v182, v106
	v_mov_b32_e32 v183, v98
	v_mov_b32_e32 v166, v150
	v_mov_b32_e32 v167, v22
	s_waitcnt vmcnt(1)
	v_mov_b32_e32 v170, v82
	v_mov_b32_e32 v171, v138
	v_pk_mul_f32 v[172:173], v[168:169], v[182:183]
	v_lshlrev_b32_e32 v179, 16, v158
	v_lshlrev_b32_e32 v178, 16, v162
	v_pk_fma_f32 v[172:173], v[166:167], v[170:171], v[172:173]
	v_mov_b32_e32 v170, v142
	v_mov_b32_e32 v171, v30
	v_pk_fma_f32 v[180:181], v[170:171], v[178:179], v[172:173]
	v_mov_b32_e32 v172, v146
	v_mov_b32_e32 v173, v34
	v_pk_add_f32 v[180:181], v[172:173], v[180:181]
	v_mov_b32_e32 v26, v155
	v_mul_f32_e32 v22, 0xbfb8aa3b, v181
	v_exp_f32_e32 v22, v22
	v_mov_b32_e32 v98, v107
	v_mov_b32_e32 v138, v83
	v_pk_mul_f32 v[82:83], v[26:27], v[98:99]
	v_add_f32_e32 v22, 1.0, v22
	v_rcp_f32_e32 v22, v22
	v_mov_b32_e32 v30, v143
	v_mov_b32_e32 v34, v147
	v_mov_b32_e32 v142, v156
	v_mul_f32_e32 v22, v181, v22
	v_mul_f32_e32 v195, v180, v22
	v_mov_b32_e32 v22, v151
	v_and_b32_e32 v181, 0xffff0000, v158
	v_and_b32_e32 v180, 0xffff0000, v162
	v_pk_fma_f32 v[82:83], v[22:23], v[138:139], v[82:83]
	v_mov_b32_e32 v143, v28
	v_pk_fma_f32 v[82:83], v[30:31], v[180:181], v[82:83]
	v_mov_b32_e32 v184, v108
	v_pk_add_f32 v[82:83], v[34:35], v[82:83]
	v_mov_b32_e32 v185, v100
	v_mul_f32_e32 v106, 0xbfb8aa3b, v83
	v_exp_f32_e32 v106, v106
	v_mov_b32_e32 v138, v152
	v_mov_b32_e32 v139, v24
	v_mov_b32_e32 v107, v140
	v_add_f32_e32 v106, 1.0, v106
	v_rcp_f32_e32 v106, v106
	v_pk_mul_f32 v[146:147], v[142:143], v[184:185]
	v_mov_b32_e32 v150, v148
	v_mov_b32_e32 v151, v36
	v_mul_f32_e32 v83, v83, v106
	v_mov_b32_e32 v106, v84
	v_mul_f32_e32 v158, v82, v83
	v_lshlrev_b32_e32 v83, 16, v159
	v_lshlrev_b32_e32 v82, 16, v163
	v_pk_fma_f32 v[106:107], v[138:139], v[106:107], v[146:147]
	v_mov_b32_e32 v146, v144
	v_mov_b32_e32 v147, v32
	v_pk_fma_f32 v[106:107], v[146:147], v[82:83], v[106:107]
	v_mov_b32_e32 v28, v157
	v_pk_add_f32 v[106:107], v[150:151], v[106:107]
	v_mov_b32_e32 v100, v109
	v_mul_f32_e32 v24, 0xbfb8aa3b, v107
	v_exp_f32_e32 v24, v24
	v_mov_b32_e32 v140, v85
	v_pk_mul_f32 v[84:85], v[28:29], v[100:101]
	v_mov_b32_e32 v32, v145
	v_add_f32_e32 v24, 1.0, v24
	v_rcp_f32_e32 v24, v24
	v_mov_b32_e32 v36, v149
	v_mov_b32_e32 v144, v126
	v_mov_b32_e32 v145, v10
	v_mul_f32_e32 v24, v107, v24
	v_mul_f32_e32 v162, v106, v24
	v_mov_b32_e32 v24, v153
	v_and_b32_e32 v107, 0xffff0000, v159
	v_and_b32_e32 v106, 0xffff0000, v163
	v_pk_fma_f32 v[84:85], v[24:25], v[140:141], v[84:85]
	s_waitcnt vmcnt(0)
	v_mov_b32_e32 v156, v102
	v_pk_fma_f32 v[84:85], v[32:33], v[106:107], v[84:85]
	v_mov_b32_e32 v157, v86
	v_pk_add_f32 v[84:85], v[36:37], v[84:85]
	v_mov_b32_e32 v140, v122
	v_mul_f32_e32 v108, 0xbfb8aa3b, v85
	v_exp_f32_e32 v108, v108
	v_mov_b32_e32 v141, v6
	v_mov_b32_e32 v109, v110
	v_pk_mul_f32 v[148:149], v[144:145], v[156:157]
	v_add_f32_e32 v108, 1.0, v108
	v_rcp_f32_e32 v108, v108
	v_mov_b32_e32 v152, v118
	v_mov_b32_e32 v153, v18
	v_mov_b32_e32 v10, v127
	v_mul_f32_e32 v85, v85, v108
	v_mov_b32_e32 v108, v78
	v_mul_f32_e32 v159, v84, v85
	v_lshlrev_b32_e32 v85, 16, v160
	v_lshlrev_b32_e32 v84, 16, v164
	v_pk_fma_f32 v[108:109], v[140:141], v[108:109], v[148:149]
	v_mov_b32_e32 v148, v114
	v_mov_b32_e32 v149, v14
	v_pk_fma_f32 v[108:109], v[148:149], v[84:85], v[108:109]
	v_mov_b32_e32 v86, v103
	v_pk_add_f32 v[108:109], v[152:153], v[108:109]
	v_mov_b32_e32 v110, v79
	v_mul_f32_e32 v6, 0xbfb8aa3b, v109
	v_exp_f32_e32 v6, v6
	v_pk_mul_f32 v[78:79], v[10:11], v[86:87]
	v_mov_b32_e32 v14, v115
	v_mov_b32_e32 v18, v119
	v_add_f32_e32 v6, 1.0, v6
	v_rcp_f32_e32 v6, v6
	v_mov_b32_e32 v122, v128
	v_mov_b32_e32 v118, v124
	v_mov_b32_e32 v119, v8
	v_mul_f32_e32 v6, v109, v6
	v_mul_f32_e32 v163, v108, v6
	v_mov_b32_e32 v6, v123
	v_and_b32_e32 v109, 0xffff0000, v160
	v_and_b32_e32 v108, 0xffff0000, v164
	v_pk_fma_f32 v[78:79], v[6:7], v[110:111], v[78:79]
	v_mov_b32_e32 v123, v12
	v_pk_fma_f32 v[78:79], v[14:15], v[108:109], v[78:79]
	v_mov_b32_e32 v110, v104
	v_pk_add_f32 v[78:79], v[18:19], v[78:79]
	v_mov_b32_e32 v111, v88
	v_mul_f32_e32 v102, 0xbfb8aa3b, v79
	v_exp_f32_e32 v102, v102
	v_mov_b32_e32 v103, v112
	v_pk_mul_f32 v[114:115], v[122:123], v[110:111]
	v_mov_b32_e32 v126, v116
	v_add_f32_e32 v102, 1.0, v102
	v_rcp_f32_e32 v102, v102
	v_mov_b32_e32 v127, v16
	v_mov_b32_e32 v154, v120
	v_mov_b32_e32 v155, v20
	v_mul_f32_e32 v79, v79, v102
	v_mov_b32_e32 v102, v80
	v_mul_f32_e32 v160, v78, v79
	v_lshlrev_b32_e32 v79, 16, v161
	v_lshlrev_b32_e32 v78, 16, v165
	v_pk_fma_f32 v[102:103], v[118:119], v[102:103], v[114:115]
	v_mov_b32_e32 v12, v129
	v_pk_fma_f32 v[102:103], v[126:127], v[78:79], v[102:103]
	v_mov_b32_e32 v88, v105
	v_pk_add_f32 v[102:103], v[154:155], v[102:103]
	v_mov_b32_e32 v112, v81
	v_mul_f32_e32 v8, 0xbfb8aa3b, v103
	v_exp_f32_e32 v8, v8
	v_pk_mul_f32 v[80:81], v[12:13], v[88:89]
	v_mov_b32_e32 v16, v117
	v_mov_b32_e32 v20, v121
	v_add_f32_e32 v8, 1.0, v8
	v_rcp_f32_e32 v8, v8
	v_lshl_add_u64 v[2:3], s[6:7], 0, v[174:175]
	v_lshlrev_b32_e32 v129, 16, v130
	v_lshlrev_b32_e32 v128, 16, v134
	v_mul_f32_e32 v8, v103, v8
	v_mul_f32_e32 v104, v102, v8
	v_mov_b32_e32 v8, v125
	v_and_b32_e32 v103, 0xffff0000, v161
	v_and_b32_e32 v102, 0xffff0000, v165
	v_pk_fma_f32 v[80:81], v[8:9], v[112:113], v[80:81]
	v_cvt_pk_bf16_f32 v112, v195, v158
	v_cvt_pk_bf16_f32 v113, v162, v159
	v_cvt_pk_bf16_f32 v114, v163, v160
	v_pk_mul_f32 v[98:99], v[22:23], v[98:99]
	v_pk_fma_f32 v[80:81], v[16:17], v[102:103], v[80:81]
	v_pk_fma_f32 v[98:99], v[26:27], v[180:181], v[98:99]
	v_pk_add_f32 v[80:81], v[20:21], v[80:81]
	v_lshlrev_b32_e32 v125, 16, v131
	v_mul_f32_e32 v105, 0xbfb8aa3b, v81
	v_exp_f32_e32 v105, v105
	v_lshlrev_b32_e32 v124, 16, v135
	v_pk_mul_f32 v[100:101], v[24:25], v[100:101]
	v_lshlrev_b32_e32 v121, 16, v132
	v_add_f32_e32 v105, 1.0, v105
	v_rcp_f32_e32 v105, v105
	v_pk_fma_f32 v[100:101], v[28:29], v[106:107], v[100:101]
	v_lshlrev_b32_e32 v120, 16, v136
	v_pk_mul_f32 v[86:87], v[6:7], v[86:87]
	v_mul_f32_e32 v81, v81, v105
	v_mul_f32_e32 v105, v80, v81
	v_mad_i64_i32 v[80:81], s[28:29], v186, s97, v[2:3]
	v_cvt_pk_bf16_f32 v115, v104, v105
	global_store_dwordx4 v[80:81], v[112:115], off
	v_pk_mul_f32 v[80:81], v[166:167], v[182:183]
	v_pk_fma_f32 v[86:87], v[10:11], v[108:109], v[86:87]
	v_pk_fma_f32 v[80:81], v[168:169], v[178:179], v[80:81]
	v_lshlrev_b32_e32 v117, 16, v133
	v_pk_fma_f32 v[80:81], v[170:171], v[128:129], v[80:81]
	v_lshlrev_b32_e32 v116, 16, v137
	v_pk_add_f32 v[80:81], v[172:173], v[80:81]
	v_pk_mul_f32 v[88:89], v[8:9], v[88:89]
	v_mul_f32_e32 v104, 0xbfb8aa3b, v81
	v_exp_f32_e32 v104, v104
	v_pk_fma_f32 v[88:89], v[12:13], v[102:103], v[88:89]
	v_or_b32_e32 v160, 8, v186
	v_or_b32_e32 v165, 12, v186
	v_add_f32_e32 v104, 1.0, v104
	v_rcp_f32_e32 v104, v104
	v_or_b32_e32 v164, 13, v186
	v_or_b32_e32 v163, 14, v186
	v_or_b32_e32 v162, 15, v186
	v_mul_f32_e32 v81, v81, v104
	v_mul_f32_e32 v104, v80, v81
	v_and_b32_e32 v81, 0xffff0000, v130
	v_and_b32_e32 v80, 0xffff0000, v134
	v_pk_fma_f32 v[98:99], v[30:31], v[80:81], v[98:99]
	v_and_b32_e32 v134, 0xffff0000, v45
	v_pk_add_f32 v[98:99], v[34:35], v[98:99]
	s_nop 0
	v_mul_f32_e32 v105, 0xbfb8aa3b, v99
	v_exp_f32_e32 v105, v105
	s_nop 0
	v_add_f32_e32 v105, 1.0, v105
	v_rcp_f32_e32 v105, v105
	s_nop 0
	v_mul_f32_e32 v99, v99, v105
	v_mul_f32_e32 v105, v98, v99
	v_pk_mul_f32 v[98:99], v[138:139], v[184:185]
	s_nop 0
	v_pk_fma_f32 v[98:99], v[142:143], v[82:83], v[98:99]
	s_nop 0
	v_pk_fma_f32 v[98:99], v[146:147], v[124:125], v[98:99]
	s_nop 0
	v_pk_add_f32 v[98:99], v[150:151], v[98:99]
	s_nop 0
	v_mul_f32_e32 v112, 0xbfb8aa3b, v99
	v_exp_f32_e32 v112, v112
	s_nop 0
	v_add_f32_e32 v112, 1.0, v112
	v_rcp_f32_e32 v112, v112
	s_nop 0
	v_mul_f32_e32 v99, v99, v112
	v_mul_f32_e32 v112, v98, v99
	v_and_b32_e32 v99, 0xffff0000, v131
	v_and_b32_e32 v98, 0xffff0000, v135
	v_pk_fma_f32 v[100:101], v[32:33], v[98:99], v[100:101]
	v_and_b32_e32 v135, 0xffff0000, v41
	v_pk_add_f32 v[100:101], v[36:37], v[100:101]
	s_nop 0
	v_mul_f32_e32 v113, 0xbfb8aa3b, v101
	v_exp_f32_e32 v113, v113
	s_nop 0
	v_add_f32_e32 v113, 1.0, v113
	v_rcp_f32_e32 v113, v113
	s_nop 0
	v_mul_f32_e32 v101, v101, v113
	v_mul_f32_e32 v113, v100, v101
	v_pk_mul_f32 v[100:101], v[140:141], v[156:157]
	v_and_b32_e32 v157, 0xffff0000, v39
	v_pk_fma_f32 v[100:101], v[144:145], v[84:85], v[100:101]
	v_and_b32_e32 v156, 0xffff0000, v43
	v_pk_fma_f32 v[100:101], v[148:149], v[120:121], v[100:101]
	s_nop 0
	v_pk_add_f32 v[100:101], v[152:153], v[100:101]
	s_nop 0
	v_mul_f32_e32 v114, 0xbfb8aa3b, v101
	v_exp_f32_e32 v114, v114
	s_nop 0
	v_add_f32_e32 v114, 1.0, v114
	v_rcp_f32_e32 v114, v114
	s_nop 0
	v_mul_f32_e32 v101, v101, v114
	v_mul_f32_e32 v114, v100, v101
	v_and_b32_e32 v101, 0xffff0000, v132
	v_and_b32_e32 v100, 0xffff0000, v136
	v_pk_fma_f32 v[86:87], v[14:15], v[100:101], v[86:87]
	v_and_b32_e32 v136, 0xffff0000, v42
	v_pk_add_f32 v[86:87], v[18:19], v[86:87]
	s_nop 0
	v_mul_f32_e32 v115, 0xbfb8aa3b, v87
	v_exp_f32_e32 v115, v115
	s_nop 0
	v_add_f32_e32 v115, 1.0, v115
	v_rcp_f32_e32 v115, v115
	s_nop 0
	v_mul_f32_e32 v87, v87, v115
	v_mul_f32_e32 v115, v86, v87
	v_pk_mul_f32 v[86:87], v[118:119], v[110:111]
	s_nop 0
	v_pk_fma_f32 v[86:87], v[122:123], v[78:79], v[86:87]
	s_nop 0
	v_pk_fma_f32 v[86:87], v[126:127], v[116:117], v[86:87]
	s_nop 0
	v_pk_add_f32 v[86:87], v[154:155], v[86:87]
	s_nop 0
	v_mul_f32_e32 v110, 0xbfb8aa3b, v87
	v_exp_f32_e32 v110, v110
	s_nop 0
	v_add_f32_e32 v110, 1.0, v110
	v_rcp_f32_e32 v110, v110
	s_nop 0
	v_mul_f32_e32 v87, v87, v110
	v_mul_f32_e32 v130, v86, v87
	v_and_b32_e32 v87, 0xffff0000, v133
	v_and_b32_e32 v86, 0xffff0000, v137
	v_pk_fma_f32 v[88:89], v[16:17], v[86:87], v[88:89]
	v_and_b32_e32 v137, 0xffff0000, v38
	v_pk_add_f32 v[88:89], v[20:21], v[88:89]
	v_and_b32_e32 v133, 0xffff0000, v40
	v_mul_f32_e32 v110, 0xbfb8aa3b, v89
	v_exp_f32_e32 v110, v110
	s_nop 0
	v_add_f32_e32 v110, 1.0, v110
	v_rcp_f32_e32 v110, v110
	s_nop 0
	v_mul_f32_e32 v89, v89, v110
	v_mul_f32_e32 v131, v88, v89
	v_mad_i64_i32 v[88:89], s[28:29], v194, s97, v[2:3]
	v_cvt_pk_bf16_f32 v110, v104, v105
	v_cvt_pk_bf16_f32 v111, v112, v113
	v_cvt_pk_bf16_f32 v112, v114, v115
	v_cvt_pk_bf16_f32 v113, v130, v131
	global_store_dwordx4 v[88:89], v[110:113], off
	v_pk_mul_f32 v[88:89], v[168:169], v[128:129]
	v_lshlrev_b32_e32 v115, 16, v90
	v_lshlrev_b32_e32 v114, 16, v94
	v_pk_fma_f32 v[88:89], v[166:167], v[178:179], v[88:89]
	v_lshlrev_b32_e32 v113, 16, v91
	v_pk_fma_f32 v[88:89], v[170:171], v[114:115], v[88:89]
	v_lshlrev_b32_e32 v112, 16, v95
	v_pk_add_f32 v[88:89], v[172:173], v[88:89]
	v_lshlrev_b32_e32 v111, 16, v92
	v_mul_f32_e32 v104, 0xbfb8aa3b, v89
	v_exp_f32_e32 v104, v104
	v_lshlrev_b32_e32 v110, 16, v96
	v_or_b32_e32 v179, 10, v186
	v_or_b32_e32 v178, 11, v186
	v_add_f32_e32 v104, 1.0, v104
	v_rcp_f32_e32 v104, v104
	s_nop 0
	v_mul_f32_e32 v89, v89, v104
	v_pk_mul_f32 v[104:105], v[26:27], v[80:81]
	v_mul_f32_e32 v130, v88, v89
	v_and_b32_e32 v89, 0xffff0000, v90
	v_and_b32_e32 v88, 0xffff0000, v94
	v_pk_fma_f32 v[104:105], v[22:23], v[180:181], v[104:105]
	v_or_b32_e32 v180, 9, v186
	v_pk_fma_f32 v[104:105], v[30:31], v[88:89], v[104:105]
	s_nop 0
	v_pk_add_f32 v[104:105], v[34:35], v[104:105]
	s_nop 0
	v_mul_f32_e32 v90, 0xbfb8aa3b, v105
	v_exp_f32_e32 v90, v90
	s_nop 0
	v_add_f32_e32 v90, 1.0, v90
	v_rcp_f32_e32 v90, v90
	s_nop 0
	v_mul_f32_e32 v90, v105, v90
	v_mul_f32_e32 v131, v104, v90
	v_pk_mul_f32 v[104:105], v[142:143], v[124:125]
	s_nop 0
	v_pk_fma_f32 v[82:83], v[138:139], v[82:83], v[104:105]
	s_nop 0
	v_pk_fma_f32 v[82:83], v[146:147], v[112:113], v[82:83]
	s_nop 0
	v_pk_add_f32 v[82:83], v[150:151], v[82:83]
	s_nop 0
	v_mul_f32_e32 v90, 0xbfb8aa3b, v83
	v_exp_f32_e32 v90, v90
	s_nop 0
	v_add_f32_e32 v90, 1.0, v90
	v_rcp_f32_e32 v90, v90
	s_nop 0
	v_mul_f32_e32 v83, v83, v90
	v_mul_f32_e32 v104, v82, v83
	v_and_b32_e32 v83, 0xffff0000, v91
	v_pk_mul_f32 v[90:91], v[28:29], v[98:99]
	v_and_b32_e32 v82, 0xffff0000, v95
	v_pk_fma_f32 v[90:91], v[24:25], v[106:107], v[90:91]
	v_lshlrev_b32_e32 v107, 16, v93
	v_pk_fma_f32 v[90:91], v[32:33], v[82:83], v[90:91]
	v_lshlrev_b32_e32 v106, 16, v97
	v_pk_add_f32 v[90:91], v[36:37], v[90:91]
	s_nop 0
	v_mul_f32_e32 v94, 0xbfb8aa3b, v91
	v_exp_f32_e32 v94, v94
	s_nop 0
	v_add_f32_e32 v94, 1.0, v94
	v_rcp_f32_e32 v94, v94
	s_nop 0
	v_mul_f32_e32 v91, v91, v94
	v_mul_f32_e32 v105, v90, v91
	v_pk_mul_f32 v[90:91], v[144:145], v[120:121]
	v_mad_i64_i32 v[94:95], s[28:29], v193, s97, v[2:3]
	v_pk_fma_f32 v[84:85], v[140:141], v[84:85], v[90:91]
	s_nop 0
	v_pk_fma_f32 v[84:85], v[148:149], v[110:111], v[84:85]
	s_nop 0
	v_pk_add_f32 v[84:85], v[152:153], v[84:85]
	s_nop 0
	v_mul_f32_e32 v90, 0xbfb8aa3b, v85
	v_exp_f32_e32 v90, v90
	s_nop 0
	v_add_f32_e32 v90, 1.0, v90
	v_rcp_f32_e32 v90, v90
	s_nop 0
	v_mul_f32_e32 v85, v85, v90
	v_pk_mul_f32 v[90:91], v[10:11], v[100:101]
	v_mul_f32_e32 v132, v84, v85
	v_and_b32_e32 v85, 0xffff0000, v92
	v_and_b32_e32 v84, 0xffff0000, v96
	v_pk_fma_f32 v[90:91], v[6:7], v[108:109], v[90:91]
	s_nop 0
	v_pk_fma_f32 v[90:91], v[14:15], v[84:85], v[90:91]
	s_nop 0
	v_pk_add_f32 v[90:91], v[18:19], v[90:91]
	s_nop 0
	v_mul_f32_e32 v92, 0xbfb8aa3b, v91
	v_exp_f32_e32 v92, v92
	s_nop 0
	v_add_f32_e32 v92, 1.0, v92
	v_rcp_f32_e32 v92, v92
	s_nop 0
	v_mul_f32_e32 v91, v91, v92
	v_mul_f32_e32 v92, v90, v91
	v_pk_mul_f32 v[90:91], v[122:123], v[116:117]
	s_nop 0
	v_pk_fma_f32 v[78:79], v[118:119], v[78:79], v[90:91]
	s_nop 0
	v_pk_fma_f32 v[78:79], v[126:127], v[106:107], v[78:79]
	s_nop 0
	v_pk_add_f32 v[78:79], v[154:155], v[78:79]
	s_nop 0
	v_mul_f32_e32 v90, 0xbfb8aa3b, v79
	v_exp_f32_e32 v90, v90
	s_nop 0
	v_add_f32_e32 v90, 1.0, v90
	v_rcp_f32_e32 v90, v90
	s_nop 0
	v_mul_f32_e32 v79, v79, v90
	v_pk_mul_f32 v[90:91], v[12:13], v[86:87]
	v_mul_f32_e32 v96, v78, v79
	v_and_b32_e32 v79, 0xffff0000, v93
	v_and_b32_e32 v78, 0xffff0000, v97
	v_pk_fma_f32 v[90:91], v[8:9], v[102:103], v[90:91]
	v_lshlrev_b32_e32 v103, 16, v71
	v_pk_fma_f32 v[90:91], v[16:17], v[78:79], v[90:91]
	v_lshlrev_b32_e32 v102, 16, v75
	v_pk_add_f32 v[90:91], v[20:21], v[90:91]
	v_and_b32_e32 v71, 0xffff0000, v71
	v_mul_f32_e32 v93, 0xbfb8aa3b, v91
	v_exp_f32_e32 v93, v93
	v_lshlrev_b32_e32 v97, 16, v73
	v_and_b32_e32 v73, 0xffff0000, v73
	v_add_f32_e32 v93, 1.0, v93
	v_rcp_f32_e32 v93, v93
	s_nop 0
	v_mul_f32_e32 v91, v91, v93
	v_mul_f32_e32 v93, v90, v91
	v_cvt_pk_bf16_f32 v90, v130, v131
	v_cvt_pk_bf16_f32 v91, v104, v105
	v_cvt_pk_bf16_f32 v92, v132, v92
	v_cvt_pk_bf16_f32 v93, v96, v93
	global_store_dwordx4 v[94:95], v[90:93], off
	v_lshlrev_b32_e32 v105, 16, v70
	v_lshlrev_b32_e32 v104, 16, v74
	v_pk_mul_f32 v[90:91], v[168:169], v[114:115]
	v_lshlrev_b32_e32 v96, 16, v77
	v_pk_fma_f32 v[90:91], v[166:167], v[128:129], v[90:91]
	v_lshlrev_b32_e32 v129, 16, v46
	v_pk_fma_f32 v[90:91], v[170:171], v[104:105], v[90:91]
	v_lshlrev_b32_e32 v128, 16, v50
	v_pk_add_f32 v[90:91], v[172:173], v[90:91]
	v_lshlrev_b32_e32 v131, 16, v47
	v_mul_f32_e32 v92, 0xbfb8aa3b, v91
	v_exp_f32_e32 v92, v92
	v_lshlrev_b32_e32 v130, 16, v51
	v_and_b32_e32 v132, 0xffff0000, v44
	v_add_f32_e32 v92, 1.0, v92
	v_rcp_f32_e32 v92, v92
	s_nop 0
	v_mul_f32_e32 v91, v91, v92
	v_pk_mul_f32 v[92:93], v[26:27], v[88:89]
	v_mul_f32_e32 v94, v90, v91
	v_and_b32_e32 v91, 0xffff0000, v70
	v_and_b32_e32 v90, 0xffff0000, v74
	v_pk_fma_f32 v[80:81], v[22:23], v[80:81], v[92:93]
	s_nop 0
	v_pk_fma_f32 v[80:81], v[30:31], v[90:91], v[80:81]
	s_nop 0
	v_pk_add_f32 v[80:81], v[34:35], v[80:81]
	s_nop 0
	v_mul_f32_e32 v70, 0xbfb8aa3b, v81
	v_exp_f32_e32 v70, v70
	s_nop 0
	v_add_f32_e32 v70, 1.0, v70
	v_rcp_f32_e32 v70, v70
	s_nop 0
	v_mul_f32_e32 v70, v81, v70
	v_mul_f32_e32 v92, v80, v70
	v_pk_mul_f32 v[80:81], v[142:143], v[112:113]
	v_cvt_pk_bf16_f32 v92, v94, v92
	s_nop 0
	v_pk_fma_f32 v[80:81], v[138:139], v[124:125], v[80:81]
	v_lshlrev_b32_e32 v125, 16, v48
	v_pk_fma_f32 v[80:81], v[146:147], v[102:103], v[80:81]
	v_lshlrev_b32_e32 v124, 16, v52
	v_pk_add_f32 v[80:81], v[150:151], v[80:81]
	s_nop 0
	v_mul_f32_e32 v70, 0xbfb8aa3b, v81
	v_exp_f32_e32 v70, v70
	s_nop 0
	v_add_f32_e32 v70, 1.0, v70
	v_rcp_f32_e32 v70, v70
	s_nop 0
	v_mul_f32_e32 v70, v81, v70
	v_mul_f32_e32 v93, v80, v70
	v_and_b32_e32 v70, 0xffff0000, v75
	v_pk_mul_f32 v[74:75], v[28:29], v[82:83]
	s_nop 0
	v_pk_fma_f32 v[74:75], v[24:25], v[98:99], v[74:75]
	v_lshlrev_b32_e32 v99, 16, v72
	v_pk_fma_f32 v[74:75], v[32:33], v[70:71], v[74:75]
	v_lshlrev_b32_e32 v98, 16, v76
	v_pk_add_f32 v[74:75], v[36:37], v[74:75]
	s_nop 0
	v_mul_f32_e32 v80, 0xbfb8aa3b, v75
	v_exp_f32_e32 v80, v80
	s_nop 0
	v_add_f32_e32 v80, 1.0, v80
	v_rcp_f32_e32 v80, v80
	s_nop 0
	v_mul_f32_e32 v75, v75, v80
	v_mul_f32_e32 v95, v74, v75
	v_pk_mul_f32 v[74:75], v[144:145], v[110:111]
	v_cvt_pk_bf16_f32 v93, v93, v95
	s_nop 0
	v_pk_fma_f32 v[74:75], v[140:141], v[120:121], v[74:75]
	v_lshlrev_b32_e32 v121, 16, v49
	v_pk_fma_f32 v[74:75], v[148:149], v[98:99], v[74:75]
	v_lshlrev_b32_e32 v120, 16, v53
	v_pk_add_f32 v[74:75], v[152:153], v[74:75]
	s_nop 0
	v_mul_f32_e32 v80, 0xbfb8aa3b, v75
	v_exp_f32_e32 v80, v80
	s_nop 0
	v_add_f32_e32 v80, 1.0, v80
	v_rcp_f32_e32 v80, v80
	s_nop 0
	v_mul_f32_e32 v75, v75, v80
	v_pk_mul_f32 v[80:81], v[10:11], v[84:85]
	v_mul_f32_e32 v108, v74, v75
	v_and_b32_e32 v75, 0xffff0000, v72
	v_and_b32_e32 v74, 0xffff0000, v76
	v_pk_fma_f32 v[80:81], v[6:7], v[100:101], v[80:81]
	s_nop 0
	v_pk_fma_f32 v[80:81], v[14:15], v[74:75], v[80:81]
	s_nop 0
	v_pk_add_f32 v[80:81], v[18:19], v[80:81]
	s_nop 0
	v_mul_f32_e32 v72, 0xbfb8aa3b, v81
	v_exp_f32_e32 v72, v72
	s_nop 0
	v_add_f32_e32 v72, 1.0, v72
	v_rcp_f32_e32 v72, v72
	s_nop 0
	v_mul_f32_e32 v72, v81, v72
	v_mul_f32_e32 v100, v80, v72
	v_pk_mul_f32 v[80:81], v[122:123], v[106:107]
	v_cvt_pk_bf16_f32 v94, v108, v100
	s_nop 0
	v_pk_fma_f32 v[80:81], v[118:119], v[116:117], v[80:81]
	s_nop 0
	v_pk_fma_f32 v[80:81], v[126:127], v[96:97], v[80:81]
	s_nop 0
	v_pk_add_f32 v[80:81], v[154:155], v[80:81]
	s_nop 0
	v_mul_f32_e32 v72, 0xbfb8aa3b, v81
	v_exp_f32_e32 v72, v72
	s_nop 0
	v_add_f32_e32 v72, 1.0, v72
	v_rcp_f32_e32 v72, v72
	s_nop 0
	v_mul_f32_e32 v72, v81, v72
	v_mul_f32_e32 v80, v80, v72
	v_and_b32_e32 v72, 0xffff0000, v77
	v_pk_mul_f32 v[76:77], v[12:13], v[78:79]
	s_nop 0
	v_pk_fma_f32 v[76:77], v[8:9], v[86:87], v[76:77]
	v_lshlrev_b32_e32 v87, 16, v64
	v_pk_fma_f32 v[76:77], v[16:17], v[72:73], v[76:77]
	v_lshlrev_b32_e32 v86, 16, v68
	v_pk_add_f32 v[76:77], v[20:21], v[76:77]
	s_nop 0
	v_mul_f32_e32 v81, 0xbfb8aa3b, v77
	v_exp_f32_e32 v81, v81
	s_nop 0
	v_add_f32_e32 v81, 1.0, v81
	v_rcp_f32_e32 v81, v81
	s_nop 0
	v_mul_f32_e32 v77, v77, v81
	v_mul_f32_e32 v81, v76, v77
	v_mad_i64_i32 v[76:77], s[28:29], v192, s97, v[2:3]
	v_cvt_pk_bf16_f32 v95, v80, v81
	global_store_dwordx4 v[76:77], v[92:95], off
	v_pk_mul_f32 v[76:77], v[168:169], v[104:105]
	s_nop 0
	v_lshlrev_b32_e32 v95, 16, v62
	v_lshlrev_b32_e32 v94, 16, v66
	v_pk_fma_f32 v[76:77], v[166:167], v[114:115], v[76:77]
	v_lshlrev_b32_e32 v93, 16, v63
	v_pk_fma_f32 v[76:77], v[170:171], v[94:95], v[76:77]
	v_lshlrev_b32_e32 v92, 16, v67
	v_pk_add_f32 v[76:77], v[172:173], v[76:77]
	s_nop 0
	v_mul_f32_e32 v80, 0xbfb8aa3b, v77
	v_exp_f32_e32 v80, v80
	s_nop 0
	v_add_f32_e32 v80, 1.0, v80
	v_rcp_f32_e32 v80, v80
	s_nop 0
	v_mul_f32_e32 v77, v77, v80
	v_pk_mul_f32 v[80:81], v[26:27], v[90:91]
	v_mul_f32_e32 v100, v76, v77
	v_and_b32_e32 v77, 0xffff0000, v62
	v_and_b32_e32 v76, 0xffff0000, v66
	v_pk_fma_f32 v[80:81], v[22:23], v[88:89], v[80:81]
	v_lshlrev_b32_e32 v89, 16, v65
	v_pk_fma_f32 v[80:81], v[30:31], v[76:77], v[80:81]
	v_lshlrev_b32_e32 v88, 16, v69
	v_pk_add_f32 v[80:81], v[34:35], v[80:81]
	s_nop 0
	v_mul_f32_e32 v62, 0xbfb8aa3b, v81
	v_exp_f32_e32 v62, v62
	s_nop 0
	v_add_f32_e32 v62, 1.0, v62
	v_rcp_f32_e32 v62, v62
	s_nop 0
	v_mul_f32_e32 v62, v81, v62
	v_mul_f32_e32 v101, v80, v62
	v_pk_mul_f32 v[80:81], v[142:143], v[102:103]
	s_nop 0
	v_pk_fma_f32 v[80:81], v[138:139], v[112:113], v[80:81]
	s_nop 0
	v_pk_fma_f32 v[80:81], v[146:147], v[92:93], v[80:81]
	s_nop 0
	v_pk_add_f32 v[80:81], v[150:151], v[80:81]
	s_nop 0
	v_mul_f32_e32 v62, 0xbfb8aa3b, v81
	v_exp_f32_e32 v62, v62
	s_nop 0
	v_add_f32_e32 v62, 1.0, v62
	v_rcp_f32_e32 v62, v62
	s_nop 0
	v_mul_f32_e32 v62, v81, v62
	v_mul_f32_e32 v108, v80, v62
	v_and_b32_e32 v81, 0xffff0000, v63
	v_pk_mul_f32 v[62:63], v[28:29], v[70:71]
	v_and_b32_e32 v80, 0xffff0000, v67
	v_pk_fma_f32 v[62:63], v[24:25], v[82:83], v[62:63]
	v_and_b32_e32 v83, 0xffff0000, v64
	v_pk_fma_f32 v[62:63], v[32:33], v[80:81], v[62:63]
	v_and_b32_e32 v82, 0xffff0000, v68
	v_pk_add_f32 v[62:63], v[36:37], v[62:63]
	s_nop 0
	v_mul_f32_e32 v66, 0xbfb8aa3b, v63
	v_exp_f32_e32 v66, v66
	s_nop 0
	v_add_f32_e32 v66, 1.0, v66
	v_rcp_f32_e32 v66, v66
	s_nop 0
	v_mul_f32_e32 v63, v63, v66
	v_mul_f32_e32 v109, v62, v63
	v_pk_mul_f32 v[62:63], v[144:145], v[98:99]
	s_nop 0
	v_pk_fma_f32 v[62:63], v[140:141], v[110:111], v[62:63]
	s_nop 0
	v_pk_fma_f32 v[62:63], v[148:149], v[86:87], v[62:63]
	s_nop 0
	v_pk_add_f32 v[62:63], v[152:153], v[62:63]
	s_nop 0
	v_mul_f32_e32 v66, 0xbfb8aa3b, v63
	v_exp_f32_e32 v66, v66
	s_nop 0
	v_add_f32_e32 v66, 1.0, v66
	v_rcp_f32_e32 v66, v66
	s_nop 0
	v_mul_f32_e32 v63, v63, v66
	v_mul_f32_e32 v110, v62, v63
	v_pk_mul_f32 v[62:63], v[10:11], v[74:75]
	s_nop 0
	v_pk_fma_f32 v[62:63], v[6:7], v[84:85], v[62:63]
	v_and_b32_e32 v85, 0xffff0000, v65
	v_pk_fma_f32 v[62:63], v[14:15], v[82:83], v[62:63]
	v_and_b32_e32 v84, 0xffff0000, v69
	v_pk_add_f32 v[62:63], v[18:19], v[62:63]
	v_lshlrev_b32_e32 v69, 16, v55
	v_mul_f32_e32 v64, 0xbfb8aa3b, v63
	v_exp_f32_e32 v64, v64
	s_nop 0
	v_add_f32_e32 v64, 1.0, v64
	v_rcp_f32_e32 v64, v64
	s_nop 0
	v_mul_f32_e32 v63, v63, v64
	v_mul_f32_e32 v64, v62, v63
	v_pk_mul_f32 v[62:63], v[122:123], v[96:97]
	s_nop 0
	v_pk_fma_f32 v[62:63], v[118:119], v[106:107], v[62:63]
	s_nop 0
	v_pk_fma_f32 v[62:63], v[126:127], v[88:89], v[62:63]
	s_nop 0
	v_pk_add_f32 v[62:63], v[154:155], v[62:63]
	s_nop 0
	v_mul_f32_e32 v66, 0xbfb8aa3b, v63
	v_exp_f32_e32 v66, v66
	s_nop 0
	v_add_f32_e32 v66, 1.0, v66
	v_rcp_f32_e32 v66, v66
	s_nop 0
	v_mul_f32_e32 v63, v63, v66
	v_mul_f32_e32 v68, v62, v63
	v_pk_mul_f32 v[62:63], v[12:13], v[72:73]
	v_mad_i64_i32 v[66:67], s[28:29], v191, s97, v[2:3]
	v_pk_fma_f32 v[62:63], v[8:9], v[78:79], v[62:63]
	v_lshlrev_b32_e32 v79, 16, v54
	v_pk_fma_f32 v[62:63], v[16:17], v[84:85], v[62:63]
	v_lshlrev_b32_e32 v78, 16, v58
	v_pk_add_f32 v[62:63], v[20:21], v[62:63]
	s_nop 0
	v_mul_f32_e32 v65, 0xbfb8aa3b, v63
	v_exp_f32_e32 v65, v65
	s_nop 0
	v_add_f32_e32 v65, 1.0, v65
	v_rcp_f32_e32 v65, v65
	s_nop 0
	v_mul_f32_e32 v63, v63, v65
	v_mul_f32_e32 v65, v62, v63
	v_cvt_pk_bf16_f32 v62, v100, v101
	v_cvt_pk_bf16_f32 v63, v108, v109
	v_cvt_pk_bf16_f32 v64, v110, v64
	v_cvt_pk_bf16_f32 v65, v68, v65
	global_store_dwordx4 v[66:67], v[62:65], off
	v_lshlrev_b32_e32 v68, 16, v59
	v_and_b32_e32 v67, 0xffff0000, v55
	v_pk_mul_f32 v[62:63], v[168:169], v[94:95]
	v_and_b32_e32 v65, 0xffff0000, v54
	v_pk_fma_f32 v[62:63], v[166:167], v[104:105], v[62:63]
	v_and_b32_e32 v66, 0xffff0000, v59
	v_pk_fma_f32 v[62:63], v[170:171], v[78:79], v[62:63]
	s_nop 0
	v_pk_add_f32 v[62:63], v[172:173], v[62:63]
	s_nop 0
	v_mul_f32_e32 v64, 0xbfb8aa3b, v63
	v_exp_f32_e32 v64, v64
	s_nop 0
	v_add_f32_e32 v64, 1.0, v64
	v_rcp_f32_e32 v64, v64
	s_nop 0
	v_mul_f32_e32 v63, v63, v64
	v_mul_f32_e32 v100, v62, v63
	v_pk_mul_f32 v[62:63], v[26:27], v[76:77]
	v_and_b32_e32 v64, 0xffff0000, v58
	v_pk_fma_f32 v[62:63], v[22:23], v[90:91], v[62:63]
	s_nop 0
	v_pk_fma_f32 v[62:63], v[30:31], v[64:65], v[62:63]
	s_nop 0
	v_pk_add_f32 v[62:63], v[34:35], v[62:63]
	s_nop 0
	v_mul_f32_e32 v54, 0xbfb8aa3b, v63
	v_exp_f32_e32 v54, v54
	s_nop 0
	v_add_f32_e32 v54, 1.0, v54
	v_rcp_f32_e32 v54, v54
	s_nop 0
	v_mul_f32_e32 v54, v63, v54
	v_mul_f32_e32 v90, v62, v54
	v_pk_mul_f32 v[62:63], v[142:143], v[92:93]
	s_nop 0
	v_pk_fma_f32 v[62:63], v[138:139], v[102:103], v[62:63]
	s_nop 0
	v_pk_fma_f32 v[62:63], v[146:147], v[68:69], v[62:63]
	s_nop 0
	v_pk_add_f32 v[62:63], v[150:151], v[62:63]
	s_nop 0
	v_mul_f32_e32 v54, 0xbfb8aa3b, v63
	v_exp_f32_e32 v54, v54
	s_nop 0
	v_add_f32_e32 v54, 1.0, v54
	v_rcp_f32_e32 v54, v54
	s_nop 0
	v_mul_f32_e32 v54, v63, v54
	v_mul_f32_e32 v91, v62, v54
	v_pk_mul_f32 v[54:55], v[28:29], v[80:81]
	v_lshlrev_b32_e32 v63, 16, v56
	v_pk_fma_f32 v[54:55], v[24:25], v[70:71], v[54:55]
	v_lshlrev_b32_e32 v62, 16, v60
	v_pk_fma_f32 v[54:55], v[32:33], v[66:67], v[54:55]
	v_pk_mul_f32 v[70:71], v[122:123], v[88:89]
	v_pk_add_f32 v[54:55], v[36:37], v[54:55]
	v_pk_fma_f32 v[70:71], v[118:119], v[96:97], v[70:71]
	v_mul_f32_e32 v58, 0xbfb8aa3b, v55
	v_exp_f32_e32 v58, v58
	v_lshlrev_b32_e32 v97, 16, v39
	v_lshlrev_b32_e32 v96, 16, v43
	v_add_f32_e32 v58, 1.0, v58
	v_rcp_f32_e32 v58, v58
	s_nop 0
	v_mul_f32_e32 v55, v55, v58
	v_mul_f32_e32 v101, v54, v55
	v_pk_mul_f32 v[54:55], v[144:145], v[86:87]
	s_nop 0
	v_pk_fma_f32 v[54:55], v[140:141], v[98:99], v[54:55]
	v_lshlrev_b32_e32 v99, 16, v40
	v_pk_fma_f32 v[54:55], v[148:149], v[62:63], v[54:55]
	s_nop 0
	v_pk_add_f32 v[54:55], v[152:153], v[54:55]
	s_nop 0
	v_mul_f32_e32 v58, 0xbfb8aa3b, v55
	v_exp_f32_e32 v58, v58
	s_nop 0
	v_add_f32_e32 v58, 1.0, v58
	v_rcp_f32_e32 v58, v58
	s_nop 0
	v_mul_f32_e32 v55, v55, v58
	v_pk_mul_f32 v[58:59], v[10:11], v[82:83]
	v_mul_f32_e32 v98, v54, v55
	v_and_b32_e32 v55, 0xffff0000, v56
	v_and_b32_e32 v54, 0xffff0000, v60
	v_pk_fma_f32 v[58:59], v[6:7], v[74:75], v[58:59]
	s_nop 0
	v_pk_fma_f32 v[58:59], v[14:15], v[54:55], v[58:59]
	s_nop 0
	v_pk_add_f32 v[58:59], v[18:19], v[58:59]
	s_nop 0
	v_mul_f32_e32 v56, 0xbfb8aa3b, v59
	v_exp_f32_e32 v56, v56
	s_nop 0
	v_add_f32_e32 v56, 1.0, v56
	v_rcp_f32_e32 v56, v56
	s_nop 0
	v_mul_f32_e32 v56, v59, v56
	v_mul_f32_e32 v74, v58, v56
	v_lshlrev_b32_e32 v59, 16, v57
	v_lshlrev_b32_e32 v58, 16, v61
	v_pk_fma_f32 v[70:71], v[126:127], v[58:59], v[70:71]
	v_and_b32_e32 v57, 0xffff0000, v57
	v_pk_add_f32 v[70:71], v[154:155], v[70:71]
	s_nop 0
	v_mul_f32_e32 v56, 0xbfb8aa3b, v71
	v_exp_f32_e32 v56, v56
	s_nop 0
	v_add_f32_e32 v56, 1.0, v56
	v_rcp_f32_e32 v56, v56
	s_nop 0
	v_mul_f32_e32 v56, v71, v56
	v_mul_f32_e32 v75, v70, v56
	v_and_b32_e32 v56, 0xffff0000, v61
	v_pk_mul_f32 v[60:61], v[12:13], v[84:85]
	s_nop 0
	v_pk_fma_f32 v[60:61], v[8:9], v[72:73], v[60:61]
	s_nop 0
	v_pk_fma_f32 v[60:61], v[16:17], v[56:57], v[60:61]
	s_nop 0
	v_pk_add_f32 v[60:61], v[20:21], v[60:61]
	s_nop 0
	v_mul_f32_e32 v70, 0xbfb8aa3b, v61
	v_exp_f32_e32 v70, v70
	s_nop 0
	v_add_f32_e32 v70, 1.0, v70
	v_rcp_f32_e32 v70, v70
	s_nop 0
	v_mul_f32_e32 v61, v61, v70
	v_mul_f32_e32 v73, v60, v61
	v_mad_i64_i32 v[60:61], s[28:29], v190, s97, v[2:3]
	v_cvt_pk_bf16_f32 v70, v100, v90
	v_cvt_pk_bf16_f32 v71, v91, v101
	v_cvt_pk_bf16_f32 v72, v98, v74
	v_cvt_pk_bf16_f32 v73, v75, v73
	global_store_dwordx4 v[60:61], v[70:73], off
	v_pk_mul_f32 v[60:61], v[168:169], v[78:79]
	v_and_b32_e32 v91, 0xffff0000, v46
	v_pk_fma_f32 v[60:61], v[166:167], v[94:95], v[60:61]
	v_and_b32_e32 v90, 0xffff0000, v50
	v_pk_fma_f32 v[60:61], v[170:171], v[128:129], v[60:61]
	v_lshlrev_b32_e32 v95, 16, v38
	v_pk_add_f32 v[60:61], v[172:173], v[60:61]
	v_lshlrev_b32_e32 v94, 16, v42
	v_mul_f32_e32 v70, 0xbfb8aa3b, v61
	v_exp_f32_e32 v70, v70
	v_lshlrev_b32_e32 v98, 16, v44
	v_lshlrev_b32_e32 v101, 16, v41
	v_lshlrev_b32_e32 v100, 16, v45
	v_add_f32_e32 v70, 1.0, v70
	v_rcp_f32_e32 v70, v70
	s_nop 0
	v_mul_f32_e32 v61, v61, v70
	v_mul_f32_e32 v70, v60, v61
	v_pk_mul_f32 v[60:61], v[26:27], v[64:65]
	s_nop 0
	v_pk_fma_f32 v[60:61], v[22:23], v[76:77], v[60:61]
	s_nop 0
	v_pk_fma_f32 v[60:61], v[30:31], v[90:91], v[60:61]
	s_nop 0
	v_pk_add_f32 v[60:61], v[34:35], v[60:61]
	s_nop 0
	v_mul_f32_e32 v46, 0xbfb8aa3b, v61
	v_exp_f32_e32 v46, v46
	s_nop 0
	v_add_f32_e32 v46, 1.0, v46
	v_rcp_f32_e32 v46, v46
	s_nop 0
	v_mul_f32_e32 v46, v61, v46
	v_mul_f32_e32 v71, v60, v46
	v_pk_mul_f32 v[60:61], v[142:143], v[68:69]
	s_nop 0
	v_pk_fma_f32 v[60:61], v[138:139], v[92:93], v[60:61]
	v_and_b32_e32 v93, 0xffff0000, v47
	v_pk_fma_f32 v[60:61], v[146:147], v[130:131], v[60:61]
	v_and_b32_e32 v92, 0xffff0000, v51
	v_pk_add_f32 v[60:61], v[150:151], v[60:61]
	s_nop 0
	v_mul_f32_e32 v46, 0xbfb8aa3b, v61
	v_exp_f32_e32 v46, v46
	s_nop 0
	v_add_f32_e32 v46, 1.0, v46
	v_rcp_f32_e32 v46, v46
	s_nop 0
	v_mul_f32_e32 v46, v61, v46
	v_mul_f32_e32 v60, v60, v46
	v_pk_mul_f32 v[46:47], v[28:29], v[66:67]
	s_nop 0
	v_pk_fma_f32 v[46:47], v[24:25], v[80:81], v[46:47]
	s_nop 0
	v_pk_fma_f32 v[46:47], v[32:33], v[92:93], v[46:47]
	s_nop 0
	v_pk_add_f32 v[46:47], v[36:37], v[46:47]
	s_nop 0
	v_mul_f32_e32 v50, 0xbfb8aa3b, v47
	v_exp_f32_e32 v50, v50
	s_nop 0
	v_add_f32_e32 v50, 1.0, v50
	v_rcp_f32_e32 v50, v50
	s_nop 0
	v_mul_f32_e32 v47, v47, v50
	v_mul_f32_e32 v61, v46, v47
	v_pk_mul_f32 v[46:47], v[144:145], v[62:63]
	s_nop 0
	v_pk_fma_f32 v[46:47], v[140:141], v[86:87], v[46:47]
	v_and_b32_e32 v87, 0xffff0000, v48
	v_pk_fma_f32 v[46:47], v[148:149], v[124:125], v[46:47]
	v_and_b32_e32 v86, 0xffff0000, v52
	v_pk_add_f32 v[46:47], v[152:153], v[46:47]
	s_nop 0
	v_mul_f32_e32 v50, 0xbfb8aa3b, v47
	v_exp_f32_e32 v50, v50
	s_nop 0
	v_add_f32_e32 v50, 1.0, v50
	v_rcp_f32_e32 v50, v50
	s_nop 0
	v_mul_f32_e32 v47, v47, v50
	v_mul_f32_e32 v72, v46, v47
	v_pk_mul_f32 v[46:47], v[10:11], v[54:55]
	s_nop 0
	v_pk_fma_f32 v[46:47], v[6:7], v[82:83], v[46:47]
	s_nop 0
	v_pk_fma_f32 v[46:47], v[14:15], v[86:87], v[46:47]
	s_nop 0
	v_pk_add_f32 v[46:47], v[18:19], v[46:47]
	s_nop 0
	v_mul_f32_e32 v48, 0xbfb8aa3b, v47
	v_exp_f32_e32 v48, v48
	s_nop 0
	v_add_f32_e32 v48, 1.0, v48
	v_rcp_f32_e32 v48, v48
	s_nop 0
	v_mul_f32_e32 v47, v47, v48
	v_mul_f32_e32 v48, v46, v47
	v_pk_mul_f32 v[46:47], v[122:123], v[58:59]
	s_nop 0
	v_pk_fma_f32 v[46:47], v[118:119], v[88:89], v[46:47]
	v_and_b32_e32 v89, 0xffff0000, v49
	v_pk_fma_f32 v[46:47], v[126:127], v[120:121], v[46:47]
	v_and_b32_e32 v88, 0xffff0000, v53
	v_pk_add_f32 v[46:47], v[154:155], v[46:47]
	s_nop 0
	v_mul_f32_e32 v50, 0xbfb8aa3b, v47
	v_exp_f32_e32 v50, v50
	s_nop 0
	v_add_f32_e32 v50, 1.0, v50
	v_rcp_f32_e32 v50, v50
	s_nop 0
	v_mul_f32_e32 v47, v47, v50
	v_mul_f32_e32 v52, v46, v47
	v_pk_mul_f32 v[46:47], v[12:13], v[56:57]
	v_mad_i64_i32 v[50:51], s[28:29], v189, s97, v[2:3]
	v_pk_fma_f32 v[46:47], v[8:9], v[84:85], v[46:47]
	s_nop 0
	v_pk_fma_f32 v[46:47], v[16:17], v[88:89], v[46:47]
	s_nop 0
	v_pk_add_f32 v[46:47], v[20:21], v[46:47]
	s_nop 0
	v_mul_f32_e32 v49, 0xbfb8aa3b, v47
	v_exp_f32_e32 v49, v49
	s_nop 0
	v_add_f32_e32 v49, 1.0, v49
	v_rcp_f32_e32 v49, v49
	s_nop 0
	v_mul_f32_e32 v47, v47, v49
	v_mul_f32_e32 v49, v46, v47
	v_cvt_pk_bf16_f32 v46, v70, v71
	v_cvt_pk_bf16_f32 v47, v60, v61
	v_cvt_pk_bf16_f32 v48, v72, v48
	v_cvt_pk_bf16_f32 v49, v52, v49
	global_store_dwordx4 v[50:51], v[46:49], off
	s_nop 1
	v_pk_mul_f32 v[46:47], v[168:169], v[128:129]
	s_nop 0
	v_pk_fma_f32 v[46:47], v[166:167], v[78:79], v[46:47]
	s_nop 0
	v_pk_fma_f32 v[46:47], v[170:171], v[94:95], v[46:47]
	s_nop 0
	v_pk_add_f32 v[46:47], v[172:173], v[46:47]
	s_nop 0
	v_mul_f32_e32 v48, 0xbfb8aa3b, v47
	v_exp_f32_e32 v48, v48
	s_nop 0
	v_add_f32_e32 v48, 1.0, v48
	v_rcp_f32_e32 v48, v48
	s_nop 0
	v_mul_f32_e32 v47, v47, v48
	v_mul_f32_e32 v48, v46, v47
	v_pk_mul_f32 v[46:47], v[26:27], v[90:91]
	s_nop 0
	v_pk_fma_f32 v[46:47], v[22:23], v[64:65], v[46:47]
	s_nop 0
	v_pk_fma_f32 v[46:47], v[30:31], v[136:137], v[46:47]
	s_nop 0
	v_pk_add_f32 v[46:47], v[34:35], v[46:47]
	s_nop 0
	v_mul_f32_e32 v38, 0xbfb8aa3b, v47
	v_exp_f32_e32 v38, v38
	s_nop 0
	v_add_f32_e32 v38, 1.0, v38
	v_rcp_f32_e32 v38, v38
	s_nop 0
	v_mul_f32_e32 v38, v47, v38
	v_mul_f32_e32 v49, v46, v38
	v_pk_mul_f32 v[46:47], v[142:143], v[130:131]
	s_nop 0
	v_pk_fma_f32 v[46:47], v[138:139], v[68:69], v[46:47]
	s_nop 0
	v_pk_fma_f32 v[46:47], v[146:147], v[96:97], v[46:47]
	s_nop 0
	v_pk_add_f32 v[46:47], v[150:151], v[46:47]
	s_nop 0
	v_mul_f32_e32 v38, 0xbfb8aa3b, v47
	v_exp_f32_e32 v38, v38
	s_nop 0
	v_add_f32_e32 v38, 1.0, v38
	v_rcp_f32_e32 v38, v38
	s_nop 0
	v_mul_f32_e32 v38, v47, v38
	v_mul_f32_e32 v46, v46, v38
	v_pk_mul_f32 v[38:39], v[28:29], v[92:93]
	s_nop 0
	v_pk_fma_f32 v[38:39], v[24:25], v[66:67], v[38:39]
	s_nop 0
	v_pk_fma_f32 v[38:39], v[32:33], v[156:157], v[38:39]
	s_nop 0
	v_pk_add_f32 v[38:39], v[36:37], v[38:39]
	s_nop 0
	v_mul_f32_e32 v42, 0xbfb8aa3b, v39
	v_exp_f32_e32 v42, v42
	s_nop 0
	v_add_f32_e32 v42, 1.0, v42
	v_rcp_f32_e32 v42, v42
	s_nop 0
	v_mul_f32_e32 v39, v39, v42
	v_mul_f32_e32 v47, v38, v39
	v_pk_mul_f32 v[38:39], v[144:145], v[124:125]
	s_nop 0
	v_pk_fma_f32 v[38:39], v[140:141], v[62:63], v[38:39]
	s_nop 0
	v_pk_fma_f32 v[38:39], v[148:149], v[98:99], v[38:39]
	s_nop 0
	v_pk_add_f32 v[38:39], v[152:153], v[38:39]
	s_nop 0
	v_mul_f32_e32 v42, 0xbfb8aa3b, v39
	v_exp_f32_e32 v42, v42
	s_nop 0
	v_add_f32_e32 v42, 1.0, v42
	v_rcp_f32_e32 v42, v42
	s_nop 0
	v_mul_f32_e32 v39, v39, v42
	v_mul_f32_e32 v50, v38, v39
	v_pk_mul_f32 v[38:39], v[10:11], v[86:87]
	s_nop 0
	v_pk_fma_f32 v[38:39], v[6:7], v[54:55], v[38:39]
	s_nop 0
	v_pk_fma_f32 v[38:39], v[14:15], v[132:133], v[38:39]
	s_nop 0
	v_pk_add_f32 v[38:39], v[18:19], v[38:39]
	s_nop 0
	v_mul_f32_e32 v40, 0xbfb8aa3b, v39
	v_exp_f32_e32 v40, v40
	s_nop 0
	v_add_f32_e32 v40, 1.0, v40
	v_rcp_f32_e32 v40, v40
	s_nop 0
	v_mul_f32_e32 v39, v39, v40
	v_mul_f32_e32 v40, v38, v39
	v_pk_mul_f32 v[38:39], v[122:123], v[120:121]
	s_nop 0
	v_pk_fma_f32 v[38:39], v[118:119], v[58:59], v[38:39]
	s_nop 0
	v_pk_fma_f32 v[38:39], v[126:127], v[100:101], v[38:39]
	s_nop 0
	v_pk_add_f32 v[38:39], v[154:155], v[38:39]
	s_nop 0
	v_mul_f32_e32 v42, 0xbfb8aa3b, v39
	v_exp_f32_e32 v42, v42
	s_nop 0
	v_add_f32_e32 v42, 1.0, v42
	v_rcp_f32_e32 v42, v42
	s_nop 0
	v_mul_f32_e32 v39, v39, v42
	v_mul_f32_e32 v44, v38, v39
	v_pk_mul_f32 v[38:39], v[12:13], v[88:89]
	v_mad_i64_i32 v[42:43], s[28:29], v188, s97, v[2:3]
	v_pk_fma_f32 v[38:39], v[8:9], v[56:57], v[38:39]
	s_nop 0
	v_pk_fma_f32 v[38:39], v[16:17], v[134:135], v[38:39]
	s_nop 0
	v_pk_add_f32 v[38:39], v[20:21], v[38:39]
	s_nop 0
	v_mul_f32_e32 v41, 0xbfb8aa3b, v39
	v_exp_f32_e32 v41, v41
	s_nop 0
	v_add_f32_e32 v41, 1.0, v41
	v_rcp_f32_e32 v41, v41
	s_nop 0
	v_mul_f32_e32 v39, v39, v41
	v_mul_f32_e32 v41, v38, v39
	v_cvt_pk_bf16_f32 v38, v48, v49
	v_cvt_pk_bf16_f32 v39, v46, v47
	v_cvt_pk_bf16_f32 v40, v50, v40
	v_cvt_pk_bf16_f32 v41, v44, v41
	global_store_dwordx4 v[42:43], v[38:41], off
	s_nop 1
	v_mov_b64_e32 v[38:39], s[6:7]
	v_mad_i64_i32 v[40:41], s[28:29], v160, s91, v[38:39]
	v_lshl_add_u64 v[40:41], v[40:41], 0, v[174:175]
	global_load_dwordx4 v[110:113], v[40:41], off
	v_add_co_u32_e32 v40, vcc, s96, v40
	s_nop 1
	v_addc_co_u32_e32 v41, vcc, 0, v41, vcc
	global_load_dwordx4 v[114:117], v[40:41], off offset:1536
	v_mad_i64_i32 v[40:41], s[28:29], v180, s91, v[38:39]
	v_lshl_add_u64 v[40:41], v[40:41], 0, v[174:175]
	global_load_dwordx4 v[102:105], v[40:41], off
	v_add_co_u32_e32 v40, vcc, s96, v40
	s_nop 1
	v_addc_co_u32_e32 v41, vcc, 0, v41, vcc
	global_load_dwordx4 v[106:109], v[40:41], off offset:1536
	v_mad_i64_i32 v[40:41], s[28:29], v179, s91, v[38:39]
	v_lshl_add_u64 v[40:41], v[40:41], 0, v[174:175]
	global_load_dwordx4 v[78:81], v[40:41], off
	v_add_co_u32_e32 v40, vcc, s96, v40
	s_nop 1
	v_addc_co_u32_e32 v41, vcc, 0, v41, vcc
	global_load_dwordx4 v[82:85], v[40:41], off offset:1536
	v_mad_i64_i32 v[40:41], s[28:29], v178, s91, v[38:39]
	v_lshl_add_u64 v[40:41], v[40:41], 0, v[174:175]
	global_load_dwordx4 v[70:73], v[40:41], off
	v_add_co_u32_e32 v40, vcc, s96, v40
	s_nop 1
	v_addc_co_u32_e32 v41, vcc, 0, v41, vcc
	global_load_dwordx4 v[74:77], v[40:41], off offset:1536
	v_mad_i64_i32 v[40:41], s[28:29], v165, s91, v[38:39]
	v_lshl_add_u64 v[40:41], v[40:41], 0, v[174:175]
	global_load_dwordx4 v[62:65], v[40:41], off
	v_add_co_u32_e32 v40, vcc, s96, v40
	s_nop 1
	v_addc_co_u32_e32 v41, vcc, 0, v41, vcc
	global_load_dwordx4 v[66:69], v[40:41], off offset:1536
	v_mad_i64_i32 v[40:41], s[28:29], v164, s91, v[38:39]
	v_lshl_add_u64 v[40:41], v[40:41], 0, v[174:175]
	global_load_dwordx4 v[54:57], v[40:41], off
	v_add_co_u32_e32 v40, vcc, s96, v40
	s_nop 1
	v_addc_co_u32_e32 v41, vcc, 0, v41, vcc
	global_load_dwordx4 v[58:61], v[40:41], off offset:1536
	v_mad_i64_i32 v[40:41], s[28:29], v163, s91, v[38:39]
	v_lshl_add_u64 v[40:41], v[40:41], 0, v[174:175]
	global_load_dwordx4 v[46:49], v[40:41], off
	v_add_co_u32_e32 v40, vcc, s96, v40
	v_mad_i64_i32 v[38:39], s[28:29], v162, s91, v[38:39]
	s_nop 0
	v_addc_co_u32_e32 v41, vcc, 0, v41, vcc
	v_lshl_add_u64 v[42:43], v[38:39], 0, v[174:175]
	global_load_dwordx4 v[50:53], v[40:41], off offset:1536
	s_nop 0
	global_load_dwordx4 v[38:41], v[42:43], off
	v_add_co_u32_e32 v42, vcc, 0x1000, v42
	s_nop 1
	v_addc_co_u32_e32 v43, vcc, 0, v43, vcc
	global_load_dwordx4 v[42:45], v[42:43], off offset:1536
	s_and_saveexec_b64 s[28:29], s[2:3]
	s_cbranch_execz .LBB0_184
	v_or_b32_e32 v86, 2, v187
	v_mad_u64_u32 v[94:95], s[2:3], v86, s90, v[176:177]
	s_mov_b64 s[2:3], 0x2c00
	v_add_co_u32_e32 v120, vcc, 0x2000, v94
	v_lshl_add_u64 v[96:97], v[94:95], 0, s[2:3]
	s_nop 0
	v_addc_co_u32_e32 v121, vcc, 0, v95, vcc
	s_mov_b64 s[2:3], 0x5800
	global_load_dwordx4 v[86:89], v[94:95], off offset:16
	global_load_dwordx4 v[90:93], v[94:95], off
	global_load_dwordx4 v[132:135], v[96:97], off offset:16
	global_load_dwordx4 v[156:159], v[120:121], off offset:3072
	v_add_co_u32_e32 v96, vcc, 0x5000, v94
	v_lshl_add_u64 v[98:99], v[94:95], 0, s[2:3]
	s_mov_b64 s[2:3], 0x8400
	v_addc_co_u32_e32 v97, vcc, 0, v95, vcc
	v_lshl_add_u64 v[100:101], v[94:95], 0, s[2:3]
	v_add_co_u32_e32 v94, vcc, 0x8000, v94
	global_load_dwordx4 v[174:177], v[98:99], off offset:16
	s_nop 0
	v_addc_co_u32_e32 v95, vcc, 0, v95, vcc
	global_load_dwordx4 v[182:185], v[96:97], off offset:2048
	s_nop 0
	global_load_dwordx4 v[98:101], v[100:101], off offset:16
	s_waitcnt vmcnt(6)
	v_mov_b32_e32 v125, v86
	global_load_dwordx4 v[94:97], v[94:95], off offset:1024
	v_mov_b32_e32 v121, v88
	s_waitcnt vmcnt(6)
	v_mov_b32_e32 v129, v90
	v_mov_b32_e32 v131, v92
	s_waitcnt vmcnt(5)
	v_mov_b32_e32 v124, v132
	v_mov_b32_e32 v86, v133
	v_mov_b32_e32 v120, v134
	v_mov_b32_e32 v88, v135
	s_waitcnt vmcnt(4)
	v_mov_b32_e32 v128, v156
	v_mov_b32_e32 v90, v157
	v_mov_b32_e32 v130, v158
	s_waitcnt vmcnt(3)
	v_mov_b32_e32 v133, v175
	v_mov_b32_e32 v92, v159
	s_waitcnt vmcnt(2)
	v_mov_b32_e32 v137, v183
	s_waitcnt vmcnt(1)
	v_mov_b32_e32 v132, v99
	v_mov_b32_e32 v134, v101
	v_mov_b32_e32 v99, v174
	v_mov_b32_e32 v101, v176
	v_mov_b32_e32 v157, v185
	v_mov_b32_e32 v135, v177
	s_waitcnt vmcnt(0)
	v_mov_b32_e32 v136, v95
	v_mov_b32_e32 v156, v97
	v_mov_b32_e32 v95, v182
	v_mov_b32_e32 v97, v184
	s_branch .LBB0_184

.LBB0_253:
	s_andn2_b64 vcc, exec, s[2:3]
	s_cbranch_vccnz .LBB0_255
	s_mul_i32 s3, s25, 0x580000
	s_mul_hi_i32 s2, s25, 0x580000
	s_add_u32 s3, s82, s3
	s_addc_u32 s2, s83, s2
	s_add_u32 s6, s3, 0x5e00000
	s_addc_u32 s7, s2, 0
	s_movk_i32 s18, 0xb00
	s_mov_b64 s[2:3], 0x1400
	s_mov_b32 s33, 11
	s_add_u32 s4, s82, 0xd200000
	s_addc_u32 s5, s83, 0
	s_branch .LBB0_256
